# hazard fix + s_nop pruning in MLA/dilated/NSA loops (hazard-checked) + GEMM FFN-up handoff trim + final-norm loads in flight
# speedup vs baseline: 1.0042x; 1.0020x over previous
.LBB0_587:
	s_add_u32 s16, s52, s4
	s_addc_u32 s17, s53, s5
	s_add_u32 s16, s16, 0x100
	s_addc_u32 s17, s17, 0
	s_add_u32 s41, s21, s4
	s_addc_u32 s45, s74, s5
	s_add_i32 s51, 0, 0x10000
	s_cmpk_eq_i32 s4, 0xf00
	s_cselect_b32 s39, s61, s17
	s_cselect_b32 s38, s60, s16
	v_add_u32_e32 v156, s51, v157
	s_cselect_b32 s17, s31, s45
	s_cselect_b32 s16, s30, s41
	s_add_i32 s41, 0, 0x14000
	ds_read_b128 v[138:141], v156
	ds_read_b128 v[152:155], v156 offset:1024
	ds_read_b128 v[158:161], v156 offset:2048
	ds_read_b128 v[164:167], v156 offset:3072
	v_add_u32_e32 v156, s41, v157
	ds_read_b128 v[170:173], v156
	ds_read_b128 v[174:177], v156 offset:1024
	ds_read_b128 v[178:181], v156 offset:2048
	ds_read_b128 v[186:189], v156 offset:3072
	v_lshl_add_u64 v[200:201], v[136:137], 0, s[4:5]
	s_add_i32 m0, s58, 0xc000
	ds_read_b128 v[190:193], v184
	ds_read_b128 v[194:197], v184 offset:1024
	ds_read_b128 v[204:207], v184 offset:2048
	ds_read_b128 v[208:211], v184 offset:3072
	ds_read_b128 v[212:215], v184 offset:4096
	ds_read_b128 v[216:219], v184 offset:5120
	ds_read_b128 v[220:223], v184 offset:6144
	ds_read_b128 v[224:227], v184 offset:7168
	global_load_lds_dwordx4 v[200:201], off
	v_lshl_add_u64 v[200:201], v[134:135], 0, s[4:5]
	s_add_i32 m0, s58, 0xe000
	s_nop 0
	global_load_lds_dwordx4 v[200:201], off
	s_waitcnt vmcnt(8)
	s_waitcnt lgkmcnt(0)
	s_setprio 1
	s_barrier
	v_mfma_f32_16x16x32_bf16 v[6:9], v[138:141], v[190:193], v[6:9]
	v_mfma_f32_16x16x32_bf16 v[130:133], v[158:161], v[190:193], v[130:133]
	v_mfma_f32_16x16x32_bf16 v[126:129], v[138:141], v[204:207], v[126:129]
	v_mfma_f32_16x16x32_bf16 v[122:125], v[158:161], v[204:207], v[122:125]
	v_mfma_f32_16x16x32_bf16 v[118:121], v[138:141], v[212:215], v[118:121]
	v_mfma_f32_16x16x32_bf16 v[114:117], v[158:161], v[212:215], v[114:117]
	v_mfma_f32_16x16x32_bf16 v[110:113], v[138:141], v[220:223], v[110:113]
	v_mfma_f32_16x16x32_bf16 v[106:109], v[158:161], v[220:223], v[106:109]
	v_mfma_f32_16x16x32_bf16 v[6:9], v[152:155], v[194:197], v[6:9]
	v_mfma_f32_16x16x32_bf16 v[130:133], v[164:167], v[194:197], v[130:133]
	v_mfma_f32_16x16x32_bf16 v[126:129], v[152:155], v[208:211], v[126:129]
	v_mfma_f32_16x16x32_bf16 v[122:125], v[164:167], v[208:211], v[122:125]
	v_mfma_f32_16x16x32_bf16 v[118:121], v[152:155], v[216:219], v[118:121]
	v_mfma_f32_16x16x32_bf16 v[114:117], v[164:167], v[216:219], v[114:117]
	v_mfma_f32_16x16x32_bf16 v[110:113], v[152:155], v[224:227], v[110:113]
	v_mfma_f32_16x16x32_bf16 v[106:109], v[164:167], v[224:227], v[106:109]
	v_mfma_f32_16x16x32_bf16 v[102:105], v[170:173], v[190:193], v[102:105]
	v_mfma_f32_16x16x32_bf16 v[98:101], v[178:181], v[190:193], v[98:101]
	v_mfma_f32_16x16x32_bf16 v[94:97], v[170:173], v[204:207], v[94:97]
	v_mfma_f32_16x16x32_bf16 v[90:93], v[178:181], v[204:207], v[90:93]
	v_mfma_f32_16x16x32_bf16 v[86:89], v[170:173], v[212:215], v[86:89]
	v_mfma_f32_16x16x32_bf16 v[82:85], v[178:181], v[212:215], v[82:85]
	v_mfma_f32_16x16x32_bf16 v[78:81], v[170:173], v[220:223], v[78:81]
	v_mfma_f32_16x16x32_bf16 v[74:77], v[178:181], v[220:223], v[74:77]
	v_mfma_f32_16x16x32_bf16 v[102:105], v[174:177], v[194:197], v[102:105]
	v_mfma_f32_16x16x32_bf16 v[98:101], v[186:189], v[194:197], v[98:101]
	v_mfma_f32_16x16x32_bf16 v[94:97], v[174:177], v[208:211], v[94:97]
	v_mfma_f32_16x16x32_bf16 v[90:93], v[186:189], v[208:211], v[90:93]
	v_mfma_f32_16x16x32_bf16 v[86:89], v[174:177], v[216:219], v[86:89]
	v_mfma_f32_16x16x32_bf16 v[82:85], v[186:189], v[216:219], v[82:85]
	v_mfma_f32_16x16x32_bf16 v[78:81], v[174:177], v[224:227], v[78:81]
	v_mfma_f32_16x16x32_bf16 v[74:77], v[186:189], v[224:227], v[74:77]
	s_barrier
	s_setprio 0
	s_add_i32 s45, s51, s49
	v_lshl_add_u64 v[200:201], s[16:17], 0, v[0:1]
	s_mov_b32 m0, s45
	ds_read_b128 v[190:193], v184 offset:16384
	ds_read_b128 v[194:197], v184 offset:17408
	ds_read_b128 v[204:207], v184 offset:18432
	ds_read_b128 v[208:211], v184 offset:19456
	ds_read_b128 v[212:215], v184 offset:20480
	ds_read_b128 v[216:219], v184 offset:21504
	ds_read_b128 v[220:223], v184 offset:22528
	ds_read_b128 v[224:227], v184 offset:23552
	global_load_lds_dwordx4 v[200:201], off
	s_add_i32 m0, s45, 0x2000
	s_add_u32 s76, s16, 0x80000
	v_lshl_add_u64 v[202:203], s[16:17], 0, v[144:145]
	s_addc_u32 s77, s17, 0
	s_add_i32 s41, s41, s49
	global_load_lds_dwordx4 v[202:203], off
	v_lshl_add_u64 v[228:229], s[76:77], 0, v[0:1]
	s_mov_b32 m0, s41
	v_lshl_add_u64 v[230:231], s[38:39], 0, v[142:143]
	global_load_lds_dwordx4 v[228:229], off
	v_lshl_add_u64 v[228:229], s[76:77], 0, v[144:145]
	s_add_i32 m0, s41, 0x2000
	s_nop 0
	global_load_lds_dwordx4 v[228:229], off
	v_lshl_add_u64 v[228:229], s[38:39], 0, v[14:15]
	s_mov_b32 m0, s58
	s_nop 0
	global_load_lds_dwordx4 v[228:229], off
	s_mov_b32 m0, s59
	s_nop 0
	global_load_lds_dwordx4 v[230:231], off
	s_waitcnt vmcnt(8)
	s_waitcnt lgkmcnt(0)
	s_setprio 1
	s_barrier
	v_mfma_f32_16x16x32_bf16 v[70:73], v[138:141], v[190:193], v[70:73]
	v_mfma_f32_16x16x32_bf16 v[66:69], v[158:161], v[190:193], v[66:69]
	v_mfma_f32_16x16x32_bf16 v[62:65], v[138:141], v[204:207], v[62:65]
	v_mfma_f32_16x16x32_bf16 v[58:61], v[158:161], v[204:207], v[58:61]
	v_mfma_f32_16x16x32_bf16 v[54:57], v[138:141], v[212:215], v[54:57]
	v_mfma_f32_16x16x32_bf16 v[50:53], v[158:161], v[212:215], v[50:53]
	v_mfma_f32_16x16x32_bf16 v[46:49], v[138:141], v[220:223], v[46:49]
	v_mfma_f32_16x16x32_bf16 v[42:45], v[158:161], v[220:223], v[42:45]
	v_mfma_f32_16x16x32_bf16 v[70:73], v[152:155], v[194:197], v[70:73]
	v_mfma_f32_16x16x32_bf16 v[66:69], v[164:167], v[194:197], v[66:69]
	v_mfma_f32_16x16x32_bf16 v[62:65], v[152:155], v[208:211], v[62:65]
	v_mfma_f32_16x16x32_bf16 v[58:61], v[164:167], v[208:211], v[58:61]
	v_mfma_f32_16x16x32_bf16 v[54:57], v[152:155], v[216:219], v[54:57]
	v_mfma_f32_16x16x32_bf16 v[50:53], v[164:167], v[216:219], v[50:53]
	v_mfma_f32_16x16x32_bf16 v[46:49], v[152:155], v[224:227], v[46:49]
	v_mfma_f32_16x16x32_bf16 v[42:45], v[164:167], v[224:227], v[42:45]
	v_mfma_f32_16x16x32_bf16 v[38:41], v[170:173], v[190:193], v[38:41]
	v_mfma_f32_16x16x32_bf16 v[34:37], v[178:181], v[190:193], v[34:37]
	v_mfma_f32_16x16x32_bf16 v[30:33], v[170:173], v[204:207], v[30:33]
	v_mfma_f32_16x16x32_bf16 v[26:29], v[178:181], v[204:207], v[26:29]
	v_mfma_f32_16x16x32_bf16 v[22:25], v[170:173], v[212:215], v[22:25]
	v_mfma_f32_16x16x32_bf16 v[18:21], v[178:181], v[212:215], v[18:21]
	v_mfma_f32_16x16x32_bf16 v[10:13], v[170:173], v[220:223], v[10:13]
	v_mfma_f32_16x16x32_bf16 v[2:5], v[178:181], v[220:223], v[2:5]
	v_mfma_f32_16x16x32_bf16 v[38:41], v[174:177], v[194:197], v[38:41]
	v_mfma_f32_16x16x32_bf16 v[34:37], v[186:189], v[194:197], v[34:37]
	v_mfma_f32_16x16x32_bf16 v[30:33], v[174:177], v[208:211], v[30:33]
	v_mfma_f32_16x16x32_bf16 v[26:29], v[186:189], v[208:211], v[26:29]
	v_mfma_f32_16x16x32_bf16 v[22:25], v[174:177], v[216:219], v[22:25]
	v_mfma_f32_16x16x32_bf16 v[18:21], v[186:189], v[216:219], v[18:21]
	v_mfma_f32_16x16x32_bf16 v[10:13], v[174:177], v[224:227], v[10:13]
	v_mfma_f32_16x16x32_bf16 v[2:5], v[186:189], v[224:227], v[2:5]
	s_barrier
	s_setprio 0
	s_add_i32 s41, 0, 0x18000
	v_add_u32_e32 v156, s41, v157
	s_add_i32 s45, 0, 0x1c000
	ds_read_b128 v[138:141], v156
	ds_read_b128 v[152:155], v156 offset:1024
	ds_read_b128 v[158:161], v156 offset:2048
	ds_read_b128 v[164:167], v156 offset:3072
	v_add_u32_e32 v156, s45, v157
	ds_read_b128 v[170:173], v156
	ds_read_b128 v[174:177], v156 offset:1024
	ds_read_b128 v[178:181], v156 offset:2048
	ds_read_b128 v[186:189], v156 offset:3072
	s_add_u32 s38, s38, 0x80000
	s_addc_u32 s39, s39, 0
	s_mov_b32 m0, s62
	v_lshl_add_u64 v[232:233], s[38:39], 0, v[14:15]
	ds_read_b128 v[190:193], v184 offset:32768
	ds_read_b128 v[194:197], v184 offset:33792
	ds_read_b128 v[204:207], v184 offset:34816
	ds_read_b128 v[208:211], v184 offset:35840
	ds_read_b128 v[212:215], v184 offset:36864
	ds_read_b128 v[216:219], v184 offset:37888
	ds_read_b128 v[220:223], v184 offset:38912
	ds_read_b128 v[224:227], v184 offset:39936
	global_load_lds_dwordx4 v[232:233], off
	v_lshl_add_u64 v[232:233], s[38:39], 0, v[142:143]
	s_mov_b32 m0, s63
	s_nop 0
	global_load_lds_dwordx4 v[232:233], off
	s_waitcnt vmcnt(8)
	s_waitcnt lgkmcnt(0)
	s_setprio 1
	s_barrier
	v_mfma_f32_16x16x32_bf16 v[6:9], v[138:141], v[190:193], v[6:9]
	v_mfma_f32_16x16x32_bf16 v[130:133], v[158:161], v[190:193], v[130:133]
	v_mfma_f32_16x16x32_bf16 v[126:129], v[138:141], v[204:207], v[126:129]
	v_mfma_f32_16x16x32_bf16 v[122:125], v[158:161], v[204:207], v[122:125]
	v_mfma_f32_16x16x32_bf16 v[118:121], v[138:141], v[212:215], v[118:121]
	v_mfma_f32_16x16x32_bf16 v[114:117], v[158:161], v[212:215], v[114:117]
	v_mfma_f32_16x16x32_bf16 v[110:113], v[138:141], v[220:223], v[110:113]
	v_mfma_f32_16x16x32_bf16 v[106:109], v[158:161], v[220:223], v[106:109]
	v_mfma_f32_16x16x32_bf16 v[6:9], v[152:155], v[194:197], v[6:9]
	v_mfma_f32_16x16x32_bf16 v[130:133], v[164:167], v[194:197], v[130:133]
	v_mfma_f32_16x16x32_bf16 v[126:129], v[152:155], v[208:211], v[126:129]
	v_mfma_f32_16x16x32_bf16 v[122:125], v[164:167], v[208:211], v[122:125]
	v_mfma_f32_16x16x32_bf16 v[118:121], v[152:155], v[216:219], v[118:121]
	v_mfma_f32_16x16x32_bf16 v[114:117], v[164:167], v[216:219], v[114:117]
	v_mfma_f32_16x16x32_bf16 v[110:113], v[152:155], v[224:227], v[110:113]
	v_mfma_f32_16x16x32_bf16 v[106:109], v[164:167], v[224:227], v[106:109]
	v_mfma_f32_16x16x32_bf16 v[102:105], v[170:173], v[190:193], v[102:105]
	v_mfma_f32_16x16x32_bf16 v[98:101], v[178:181], v[190:193], v[98:101]
	v_mfma_f32_16x16x32_bf16 v[94:97], v[170:173], v[204:207], v[94:97]
	v_mfma_f32_16x16x32_bf16 v[90:93], v[178:181], v[204:207], v[90:93]
	v_mfma_f32_16x16x32_bf16 v[86:89], v[170:173], v[212:215], v[86:89]
	v_mfma_f32_16x16x32_bf16 v[82:85], v[178:181], v[212:215], v[82:85]
	v_mfma_f32_16x16x32_bf16 v[78:81], v[170:173], v[220:223], v[78:81]
	v_mfma_f32_16x16x32_bf16 v[74:77], v[178:181], v[220:223], v[74:77]
	v_mfma_f32_16x16x32_bf16 v[102:105], v[174:177], v[194:197], v[102:105]
	v_mfma_f32_16x16x32_bf16 v[98:101], v[186:189], v[194:197], v[98:101]
	v_mfma_f32_16x16x32_bf16 v[94:97], v[174:177], v[208:211], v[94:97]
	v_mfma_f32_16x16x32_bf16 v[90:93], v[186:189], v[208:211], v[90:93]
	v_mfma_f32_16x16x32_bf16 v[86:89], v[174:177], v[216:219], v[86:89]
	v_mfma_f32_16x16x32_bf16 v[82:85], v[186:189], v[216:219], v[82:85]
	v_mfma_f32_16x16x32_bf16 v[78:81], v[174:177], v[224:227], v[78:81]
	v_mfma_f32_16x16x32_bf16 v[74:77], v[186:189], v[224:227], v[74:77]
	s_barrier
	s_setprio 0
	s_add_i32 s38, s41, s49
	v_lshl_add_u64 v[200:201], v[200:201], 0, s[96:97]
	s_mov_b32 m0, s38
	ds_read_b128 v[190:193], v184 offset:49152
	ds_read_b128 v[194:197], v184 offset:50176
	ds_read_b128 v[204:207], v184 offset:51200
	ds_read_b128 v[208:211], v184 offset:52224
	ds_read_b128 v[212:215], v184 offset:53248
	ds_read_b128 v[216:219], v184 offset:54272
	ds_read_b128 v[220:223], v184 offset:55296
	ds_read_b128 v[224:227], v184 offset:56320
	global_load_lds_dwordx4 v[200:201], off
	s_add_i32 m0, s38, 0x2000
	s_add_u32 s16, s16, 0x80080
	v_lshl_add_u64 v[200:201], v[202:203], 0, s[96:97]
	s_addc_u32 s17, s17, 0
	s_add_i32 s38, s45, s49
	global_load_lds_dwordx4 v[200:201], off
	v_lshl_add_u64 v[200:201], s[16:17], 0, v[0:1]
	s_mov_b32 m0, s38
	s_nop 0
	global_load_lds_dwordx4 v[200:201], off
	v_lshl_add_u64 v[200:201], s[16:17], 0, v[144:145]
	s_add_i32 m0, s38, 0x2000
	s_nop 0
	global_load_lds_dwordx4 v[200:201], off
	v_lshl_add_u64 v[200:201], v[228:229], 0, s[96:97]
	s_mov_b32 m0, s68
	s_nop 0
	global_load_lds_dwordx4 v[200:201], off
	v_lshl_add_u64 v[200:201], v[230:231], 0, s[96:97]
	s_mov_b32 m0, s69
	s_nop 0
	global_load_lds_dwordx4 v[200:201], off
	s_waitcnt vmcnt(8)
	s_waitcnt lgkmcnt(0)
	s_setprio 1
	s_barrier
	v_mfma_f32_16x16x32_bf16 v[70:73], v[138:141], v[190:193], v[70:73]
	v_mfma_f32_16x16x32_bf16 v[66:69], v[158:161], v[190:193], v[66:69]
	v_mfma_f32_16x16x32_bf16 v[62:65], v[138:141], v[204:207], v[62:65]
	v_mfma_f32_16x16x32_bf16 v[58:61], v[158:161], v[204:207], v[58:61]
	v_mfma_f32_16x16x32_bf16 v[54:57], v[138:141], v[212:215], v[54:57]
	v_mfma_f32_16x16x32_bf16 v[50:53], v[158:161], v[212:215], v[50:53]
	v_mfma_f32_16x16x32_bf16 v[46:49], v[138:141], v[220:223], v[46:49]
	v_mfma_f32_16x16x32_bf16 v[42:45], v[158:161], v[220:223], v[42:45]
	v_mfma_f32_16x16x32_bf16 v[70:73], v[152:155], v[194:197], v[70:73]
	v_mfma_f32_16x16x32_bf16 v[66:69], v[164:167], v[194:197], v[66:69]
	v_mfma_f32_16x16x32_bf16 v[62:65], v[152:155], v[208:211], v[62:65]
	v_mfma_f32_16x16x32_bf16 v[58:61], v[164:167], v[208:211], v[58:61]
	v_mfma_f32_16x16x32_bf16 v[54:57], v[152:155], v[216:219], v[54:57]
	v_mfma_f32_16x16x32_bf16 v[50:53], v[164:167], v[216:219], v[50:53]
	v_mfma_f32_16x16x32_bf16 v[46:49], v[152:155], v[224:227], v[46:49]
	v_mfma_f32_16x16x32_bf16 v[42:45], v[164:167], v[224:227], v[42:45]
	v_mfma_f32_16x16x32_bf16 v[38:41], v[170:173], v[190:193], v[38:41]
	v_mfma_f32_16x16x32_bf16 v[34:37], v[178:181], v[190:193], v[34:37]
	v_mfma_f32_16x16x32_bf16 v[30:33], v[170:173], v[204:207], v[30:33]
	v_mfma_f32_16x16x32_bf16 v[26:29], v[178:181], v[204:207], v[26:29]
	v_mfma_f32_16x16x32_bf16 v[22:25], v[170:173], v[212:215], v[22:25]
	v_mfma_f32_16x16x32_bf16 v[18:21], v[178:181], v[212:215], v[18:21]
	v_mfma_f32_16x16x32_bf16 v[10:13], v[170:173], v[220:223], v[10:13]
	v_mfma_f32_16x16x32_bf16 v[2:5], v[178:181], v[220:223], v[2:5]
	v_mfma_f32_16x16x32_bf16 v[38:41], v[174:177], v[194:197], v[38:41]
	v_mfma_f32_16x16x32_bf16 v[34:37], v[186:189], v[194:197], v[34:37]
	v_mfma_f32_16x16x32_bf16 v[30:33], v[174:177], v[208:211], v[30:33]
	v_mfma_f32_16x16x32_bf16 v[26:29], v[186:189], v[208:211], v[26:29]
	v_mfma_f32_16x16x32_bf16 v[22:25], v[174:177], v[216:219], v[22:25]
	v_mfma_f32_16x16x32_bf16 v[18:21], v[186:189], v[216:219], v[18:21]
	v_mfma_f32_16x16x32_bf16 v[10:13], v[174:177], v[224:227], v[10:13]
	v_mfma_f32_16x16x32_bf16 v[2:5], v[186:189], v[224:227], v[2:5]
	s_barrier
	s_setprio 0
	s_add_i32 s40, s40, 2
	s_add_u32 s4, s4, 0x100
	s_addc_u32 s5, s5, 0
	s_cmp_gt_u32 s40, 29
	s_cbranch_scc0 .LBB0_587
	s_and_b64 vcc, exec, s[26:27]
	s_cbranch_vccz .LBB0_590
	s_barrier

.LBB0_1446:
	s_andn2_b64 vcc, exec, s[24:25]
	s_cbranch_vccnz .LBB0_1448
	v_mov_b32_e32 v2, v196
	s_add_i32 s24, 0, 0x10000
	v_lshl_add_u32 v3, v2, 8, s24
	v_lshlrev_b32_e32 v2, 4, v2
	v_and_b32_e32 v2, 0x70, v2
	v_xad_u32 v200, v2, v206, v3
	v_xad_u32 v201, v2, v227, v3
	v_xad_u32 v202, v2, v228, v3
	v_xad_u32 v17, v2, v229, v3
	ds_read_b128 v[2:5], v200 offset:0
	ds_read_b128 v[6:9], v200 offset:0x2000
	ds_read_b128 v[10:13], v201 offset:0
	ds_read_b128 v[26:29], v201 offset:0x2000
	v_add_f32_e32 v25, 0, v112
	s_waitcnt lgkmcnt(3)
	s_mov_b32 m0, s55
	v_mfma_f32_32x32x16_bf16 v[128:143], v[2:5], v[188:191], 0
	ds_read_b128 v[2:5], v202 offset:0
	s_lshl_b32 s24, s62, 14
	s_waitcnt lgkmcnt(3)
	s_add_i32 s24, s54, s24
	v_exp_f32_e32 v113, v113
	v_exp_f32_e32 v114, v114
	v_mfma_f32_32x32x16_bf16 v[144:159], v[6:9], v[188:191], 0
	v_add_f32_e32 v24, v24, v97
	v_add_f32_e32 v25, v25, v113
	ds_read_b128 v[6:9], v202 offset:0x2000
	v_add_f32_e32 v24, v98, v24
	v_add_f32_e32 v25, v114, v25
	global_load_lds_dwordx4 v[20:21], off
	v_exp_f32_e32 v115, v115
	s_waitcnt lgkmcnt(3)
	v_add_f32_e32 v20, v24, v99
	v_mfma_f32_32x32x16_bf16 v[128:143], v[10:13], v[184:187], v[128:143]
	ds_read_b128 v[10:13], v17 offset:0
	v_add_f32_e32 v21, v25, v115
	s_waitcnt lgkmcnt(3)
	s_mov_b32 m0, s56
	v_exp_f32_e32 v116, v116
	v_exp_f32_e32 v117, v117
	v_mfma_f32_32x32x16_bf16 v[144:159], v[26:29], v[184:187], v[144:159]
	v_add_f32_e32 v20, v20, v100
	v_add_f32_e32 v21, v21, v116
	ds_read_b128 v[24:27], v17 offset:0x2000
	v_add_f32_e32 v20, v101, v20
	v_add_f32_e32 v21, v117, v21
	s_waitcnt lgkmcnt(3)
	v_exp_f32_e32 v118, v118
	v_mfma_f32_32x32x16_bf16 v[128:143], v[2:5], v[180:183], v[128:143]
	ds_read_b128 v[2:5], v200 offset:0x80
	v_add_f32_e32 v20, v20, v102
	v_add_f32_e32 v21, v21, v118
	s_waitcnt lgkmcnt(3)
	v_exp_f32_e32 v119, v119
	v_exp_f32_e32 v120, v120
	v_mfma_f32_32x32x16_bf16 v[144:159], v[6:9], v[180:183], v[144:159]
	v_add_f32_e32 v6, v20, v103
	v_add_f32_e32 v7, v21, v119
	ds_read_b128 v[192:195], v200 offset:0x2080
	v_add_f32_e32 v20, v104, v6
	v_add_f32_e32 v21, v120, v7
	global_load_lds_dwordx4 v[18:19], off
	v_exp_f32_e32 v121, v121
	s_waitcnt lgkmcnt(3)
	v_add_f32_e32 v18, v20, v105
	v_mfma_f32_32x32x16_bf16 v[128:143], v[10:13], v[176:179], v[128:143]
	ds_read_b128 v[6:9], v201 offset:0x80
	v_add_f32_e32 v19, v21, v121
	s_waitcnt lgkmcnt(3)
	s_mov_b32 m0, s24
	v_exp_f32_e32 v122, v122
	v_exp_f32_e32 v123, v123
	v_mfma_f32_32x32x16_bf16 v[144:159], v[24:27], v[176:179], v[144:159]
	v_add_f32_e32 v18, v18, v106
	v_add_f32_e32 v19, v19, v122
	ds_read_b128 v[10:13], v201 offset:0x2080
	v_add_f32_e32 v18, v107, v18
	v_add_f32_e32 v19, v123, v19
	s_waitcnt lgkmcnt(3)
	v_exp_f32_e32 v124, v124
	v_mfma_f32_32x32x16_bf16 v[128:143], v[2:5], v[172:175], v[128:143]
	ds_read_b128 v[2:5], v202 offset:0x80
	v_add_f32_e32 v24, v18, v108
	v_add_f32_e32 v25, v19, v124
	s_waitcnt lgkmcnt(3)
	v_exp_f32_e32 v125, v125
	v_exp_f32_e32 v126, v126
	v_mfma_f32_32x32x16_bf16 v[144:159], v[192:195], v[172:175], v[144:159]
	v_add_f32_e32 v24, v24, v109
	v_add_f32_e32 v25, v25, v125
	ds_read_b128 v[18:21], v202 offset:0x2080
	v_add_f32_e32 v24, v110, v24
	v_add_f32_e32 v25, v126, v25
	global_load_lds_dwordx4 v[22:23], off
	v_exp_f32_e32 v127, v127
	s_waitcnt lgkmcnt(3)
	v_add_f32_e32 v200, v24, v111
	v_mfma_f32_32x32x16_bf16 v[128:143], v[6:9], v[168:171], v[128:143]
	ds_read_b128 v[26:29], v17 offset:0x80
	v_add_f32_e32 v201, v25, v127
	s_waitcnt lgkmcnt(3)
	s_add_i32 m0, s24, 0x2000
	v_mfma_f32_32x32x16_bf16 v[144:159], v[10:13], v[168:171], v[144:159]
	ds_read_b128 v[22:25], v17 offset:0x2080
	v_cvt_pk_bf16_f32 v6, v96, v97
	v_cvt_pk_bf16_f32 v8, v100, v101
	s_nop 0
	v_permlane32_swap_b32_e32 v6, v8
	v_cvt_pk_bf16_f32 v7, v98, v99
	v_cvt_pk_bf16_f32 v9, v102, v103
	s_nop 0
	v_permlane32_swap_b32_e32 v7, v9
	s_waitcnt lgkmcnt(3)
	v_cvt_pk_bf16_f32 v10, v104, v105
	v_cvt_pk_bf16_f32 v12, v108, v109
	v_mfma_f32_32x32x16_bf16 v[128:143], v[2:5], v[164:167], v[128:143]
	v_permlane32_swap_b32_e32 v10, v12
	s_waitcnt lgkmcnt(2)
	v_cvt_pk_bf16_f32 v11, v106, v107
	v_cvt_pk_bf16_f32 v13, v110, v111
	v_mfma_f32_32x32x16_bf16 v[144:159], v[18:21], v[164:167], v[144:159]
	v_permlane32_swap_b32_e32 v11, v13
	v_cvt_pk_bf16_f32 v2, v112, v113
	v_cvt_pk_bf16_f32 v4, v116, v117
	s_nop 0
	v_permlane32_swap_b32_e32 v2, v4
	global_load_lds_dwordx4 v[30:31], off
	s_waitcnt lgkmcnt(1)
	v_cvt_pk_bf16_f32 v3, v114, v115
	v_cvt_pk_bf16_f32 v5, v118, v119
	s_nop 0
	v_mfma_f32_32x32x16_bf16 v[128:143], v[26:29], v[160:163], v[128:143]
	v_permlane32_swap_b32_e32 v3, v5
	s_waitcnt lgkmcnt(0)
	v_cvt_pk_bf16_f32 v192, v120, v121
	v_cvt_pk_bf16_f32 v194, v124, v125
	v_mfma_f32_32x32x16_bf16 v[144:159], v[22:25], v[160:163], v[144:159]
	v_permlane32_swap_b32_e32 v192, v194
	v_cvt_pk_bf16_f32 v193, v122, v123
	v_cvt_pk_bf16_f32 v195, v126, v127
	s_nop 0
	v_permlane32_swap_b32_e32 v193, v195
	v_add_f32_e32 v17, v200, v201
	v_mov_b32_e32 v18, v17
	s_nop 1
	v_permlane32_swap_b32_e32 v17, v18
	v_add_f32_e32 v239, v17, v18
	v_fmac_f32_e32 v239, v236, v205
	s_andn2_b64 vcc, exec, s[22:23]
	s_cbranch_vccz .LBB0_1449
	s_branch .LBB0_1451

.LBB0_1455:
	v_lshl_add_u32 v19, s26, 14, v207
	ds_read_b64_tr_b16 v[20:21], v19 offset:0
	ds_read_b64_tr_b16 v[22:23], v19 offset:0x800
	ds_read_b64_tr_b16 v[24:25], v19 offset:0x1000
	ds_read_b64_tr_b16 v[26:27], v19 offset:0x1800
	ds_read_b64_tr_b16 v[28:29], v19 offset:0x2000
	ds_read_b64_tr_b16 v[30:31], v19 offset:0x2800
	ds_read_b64_tr_b16 v[96:97], v19 offset:0x3000
	v_max3_f32 v17, v128, s72, v129
	ds_read_b64_tr_b16 v[98:99], v19 offset:0x3800
	v_max3_f32 v17, v17, v130, v131
	s_waitcnt lgkmcnt(6)
	v_max3_f32 v17, v17, v132, v133
	v_mfma_f32_32x32x16_bf16 v[64:79], v[6:9], v[20:23], v[64:79]
	v_max3_f32 v17, v17, v134, v135
	ds_read_b64_tr_b16 v[20:21], v19 offset:0x200
	ds_read_b64_tr_b16 v[22:23], v19 offset:0xa00
	s_waitcnt lgkmcnt(6)
	v_max3_f32 v17, v17, v136, v137
	v_max3_f32 v17, v17, v138, v139
	v_max3_f32 v17, v17, v140, v141
	v_mfma_f32_32x32x16_bf16 v[64:79], v[10:13], v[24:27], v[64:79]
	v_max3_f32 v17, v17, v142, v143
	ds_read_b64_tr_b16 v[24:25], v19 offset:0x1200
	ds_read_b64_tr_b16 v[26:27], v19 offset:0x1a00
	s_waitcnt lgkmcnt(6)
	v_max3_f32 v17, v17, v144, v145
	v_max3_f32 v17, v17, v146, v147
	v_max3_f32 v17, v17, v148, v149
	v_mfma_f32_32x32x16_bf16 v[64:79], v[2:5], v[28:31], v[64:79]
	v_max3_f32 v17, v17, v150, v151
	ds_read_b64_tr_b16 v[28:29], v19 offset:0x2200
	ds_read_b64_tr_b16 v[30:31], v19 offset:0x2a00
	s_waitcnt lgkmcnt(6)
	v_max3_f32 v17, v17, v152, v153
	v_max3_f32 v17, v17, v154, v155
	v_max3_f32 v17, v17, v156, v157
	v_mfma_f32_32x32x16_bf16 v[64:79], v[192:195], v[96:99], v[64:79]
	v_max3_f32 v17, v17, v158, v159
	ds_read_b64_tr_b16 v[96:97], v19 offset:0x3200
	ds_read_b64_tr_b16 v[98:99], v19 offset:0x3a00
	s_waitcnt lgkmcnt(6)
	v_mov_b32_e32 v100, v17
	s_nop 1
	v_permlane32_swap_b32_e32 v17, v100
	v_max_f32_e32 v100, v100, v100
	v_max_f32_e32 v17, v17, v17
	v_max_f32_e32 v102, v17, v100
	v_sub_f32_e32 v17, v102, v237
	v_cmp_ge_f32_e32 vcc, s83, v17
	s_cmp_eq_u64 vcc, exec
	v_max_f32_e32 v18, v18, v102
	s_cselect_b64 vcc, -1, 0
	v_cndmask_b32_e32 v238, v18, v237, vcc
	v_mfma_f32_32x32x16_bf16 v[80:95], v[6:9], v[20:23], v[80:95]
	v_sub_f32_e32 v17, v237, v238
	v_mov_b32_e32 v18, v238
	v_exp_f32_e32 v17, v17
	ds_read_b64_tr_b16 v[20:21], v19 offset:0x400
	ds_read_b64_tr_b16 v[22:23], v19 offset:0xc00
	s_waitcnt lgkmcnt(6)
	v_sub_f32_e32 v100, v128, v18
	v_mfma_f32_32x32x16_bf16 v[80:95], v[10:13], v[24:27], v[80:95]
	v_sub_f32_e32 v144, v144, v18
	v_exp_f32_e32 v128, v100
	ds_read_b64_tr_b16 v[24:25], v19 offset:0x1400
	ds_read_b64_tr_b16 v[26:27], v19 offset:0x1c00
	s_waitcnt lgkmcnt(6)
	v_sub_f32_e32 v100, v129, v18
	v_mfma_f32_32x32x16_bf16 v[80:95], v[2:5], v[28:31], v[80:95]
	v_sub_f32_e32 v145, v145, v18
	v_exp_f32_e32 v129, v100
	ds_read_b64_tr_b16 v[28:29], v19 offset:0x2400
	ds_read_b64_tr_b16 v[30:31], v19 offset:0x2c00
	s_waitcnt lgkmcnt(6)
	v_sub_f32_e32 v100, v130, v18
	v_sub_f32_e32 v101, v131, v18
	v_mfma_f32_32x32x16_bf16 v[80:95], v[192:195], v[96:99], v[80:95]
	v_add_f32_e64 v146, v146, -v18
	v_add_f32_e64 v147, v147, -v18
	v_exp_f32_e32 v130, v100
	v_exp_f32_e32 v131, v101
	ds_read_b64_tr_b16 v[96:97], v19 offset:0x3400
	ds_read_b64_tr_b16 v[98:99], v19 offset:0x3c00
	s_waitcnt lgkmcnt(6)
	v_sub_f32_e32 v100, v132, v18
	v_mfma_f32_32x32x16_bf16 v[48:63], v[6:9], v[20:23], v[48:63]
	v_sub_f32_e32 v148, v148, v18
	v_exp_f32_e32 v132, v100
	ds_read_b64_tr_b16 v[20:21], v19 offset:0x600
	ds_read_b64_tr_b16 v[22:23], v19 offset:0xe00
	s_waitcnt lgkmcnt(6)
	v_mov_b32_e32 v100, v149
	v_mov_b32_e32 v101, v150
	v_sub_f32_e32 v103, v133, v18
	v_sub_f32_e32 v104, v134, v18
	v_pk_add_f32 v[100:101], v[100:101], v[18:19] op_sel_hi:[1,0] neg_lo:[0,1] neg_hi:[0,1]
	v_mfma_f32_32x32x16_bf16 v[48:63], v[10:13], v[24:27], v[48:63]
	v_exp_f32_e32 v133, v103
	v_exp_f32_e32 v134, v104
	v_mov_b32_e32 v149, v100
	v_mov_b32_e32 v150, v101
	ds_read_b64_tr_b16 v[24:25], v19 offset:0x1600
	ds_read_b64_tr_b16 v[26:27], v19 offset:0x1e00
	s_waitcnt lgkmcnt(6)
	v_sub_f32_e32 v100, v135, v18
	v_mfma_f32_32x32x16_bf16 v[48:63], v[2:5], v[28:31], v[48:63]
	v_sub_f32_e32 v151, v151, v18
	v_exp_f32_e32 v135, v100
	ds_read_b64_tr_b16 v[28:29], v19 offset:0x2600
	ds_read_b64_tr_b16 v[30:31], v19 offset:0x2e00
	s_waitcnt lgkmcnt(6)
	v_sub_f32_e32 v100, v136, v18
	v_sub_f32_e32 v101, v137, v18
	v_mfma_f32_32x32x16_bf16 v[48:63], v[192:195], v[96:99], v[48:63]
	v_add_f32_e64 v152, v152, -v18
	v_add_f32_e64 v153, v153, -v18
	v_exp_f32_e32 v136, v100
	v_exp_f32_e32 v137, v101
	ds_read_b64_tr_b16 v[96:97], v19 offset:0x3600
	ds_read_b64_tr_b16 v[98:99], v19 offset:0x3e00
	s_waitcnt lgkmcnt(6)
	v_sub_f32_e32 v19, v138, v18
	v_sub_f32_e32 v154, v154, v18
	v_exp_f32_e32 v138, v19
	v_mfma_f32_32x32x16_bf16 v[32:47], v[6:9], v[20:23], v[32:47]
	s_waitcnt lgkmcnt(4)
	v_mov_b32_e32 v6, v155
	v_mov_b32_e32 v7, v156
	v_sub_f32_e32 v8, v139, v18
	v_sub_f32_e32 v9, v140, v18
	v_pk_add_f32 v[6:7], v[6:7], v[18:19] op_sel_hi:[1,0] neg_lo:[0,1] neg_hi:[0,1]
	v_exp_f32_e32 v139, v8
	v_exp_f32_e32 v140, v9
	v_mfma_f32_32x32x16_bf16 v[32:47], v[10:13], v[24:27], v[32:47]
	v_mov_b32_e32 v155, v6
	v_mov_b32_e32 v156, v7
	s_waitcnt lgkmcnt(2)
	v_sub_f32_e32 v6, v141, v18
	v_exp_f32_e32 v141, v6
	v_mfma_f32_32x32x16_bf16 v[32:47], v[2:5], v[28:31], v[32:47]
	v_sub_f32_e32 v157, v157, v18
	s_waitcnt lgkmcnt(0)
	v_sub_f32_e32 v2, v142, v18
	v_sub_f32_e32 v3, v143, v18
	v_exp_f32_e32 v142, v2
	v_exp_f32_e32 v143, v3
	v_mfma_f32_32x32x16_bf16 v[32:47], v[192:195], v[96:99], v[32:47]
	v_add_f32_e64 v158, v158, -v18
	v_add_f32_e64 v159, v159, -v18
	v_mov_b64_e32 v[112:113], v[128:129]
	v_mov_b64_e32 v[96:97], v[144:145]
	v_mov_b64_e32 v[114:115], v[130:131]
	v_mov_b64_e32 v[116:117], v[132:133]
	v_mov_b64_e32 v[118:119], v[134:135]
	v_mov_b64_e32 v[120:121], v[136:137]
	v_mov_b64_e32 v[122:123], v[138:139]
	v_mov_b64_e32 v[124:125], v[140:141]
	v_mov_b64_e32 v[126:127], v[142:143]
	v_mov_b64_e32 v[98:99], v[146:147]
	v_mov_b64_e32 v[100:101], v[148:149]
	v_mov_b64_e32 v[102:103], v[150:151]
	v_mov_b64_e32 v[104:105], v[152:153]
	v_mov_b64_e32 v[106:107], v[154:155]
	v_mov_b64_e32 v[108:109], v[156:157]
	v_mov_b64_e32 v[110:111], v[158:159]
	v_cmp_gt_f32_e32 vcc, 1.0, v17
	s_cbranch_vccz .LBB0_1459

.LBB0_1461:
	s_andn2_b64 vcc, exec, s[26:27]
	s_cbranch_vccnz .LBB0_1463
	v_mov_b32_e32 v2, v196
	s_add_i32 s26, 0, 0xc000
	v_lshl_add_u32 v3, v2, 8, s26
	v_lshlrev_b32_e32 v2, 4, v2
	v_and_b32_e32 v2, 0x70, v2
	v_xad_u32 v193, v2, v206, v3
	v_xad_u32 v194, v2, v227, v3
	v_xad_u32 v195, v2, v228, v3
	v_xad_u32 v192, v2, v229, v3
	ds_read_b128 v[2:5], v193 offset:0
	ds_read_b128 v[6:9], v193 offset:0x2000
	ds_read_b128 v[10:13], v194 offset:0
	ds_read_b128 v[26:29], v194 offset:0x2000
	v_add_f32_e32 v25, 0, v96
	s_waitcnt lgkmcnt(3)
	s_add_i32 m0, s54, 0x10000
	v_mfma_f32_32x32x16_bf16 v[128:143], v[2:5], v[188:191], 0
	ds_read_b128 v[2:5], v195 offset:0
	s_lshl_b32 s26, s63, 14
	s_waitcnt lgkmcnt(3)
	s_add_i32 s26, s54, s26
	v_exp_f32_e32 v97, v97
	v_exp_f32_e32 v98, v98
	v_mfma_f32_32x32x16_bf16 v[144:159], v[6:9], v[188:191], 0
	v_add_f32_e32 v24, v24, v113
	v_add_f32_e32 v25, v25, v97
	ds_read_b128 v[6:9], v195 offset:0x2000
	v_add_f32_e32 v24, v114, v24
	v_add_f32_e32 v25, v98, v25
	global_load_lds_dwordx4 v[20:21], off
	v_exp_f32_e32 v99, v99
	s_waitcnt lgkmcnt(3)
	v_add_f32_e32 v20, v24, v115
	v_mfma_f32_32x32x16_bf16 v[128:143], v[10:13], v[184:187], v[128:143]
	ds_read_b128 v[10:13], v192 offset:0
	v_add_f32_e32 v21, v25, v99
	s_waitcnt lgkmcnt(3)
	s_add_i32 m0, s54, 0x12000
	v_exp_f32_e32 v100, v100
	v_exp_f32_e32 v101, v101
	v_mfma_f32_32x32x16_bf16 v[144:159], v[26:29], v[184:187], v[144:159]
	v_add_f32_e32 v20, v20, v116
	v_add_f32_e32 v21, v21, v100
	ds_read_b128 v[24:27], v192 offset:0x2000
	v_add_f32_e32 v20, v117, v20
	v_add_f32_e32 v21, v101, v21
	s_waitcnt lgkmcnt(3)
	v_exp_f32_e32 v102, v102
	v_mfma_f32_32x32x16_bf16 v[128:143], v[2:5], v[180:183], v[128:143]
	ds_read_b128 v[2:5], v193 offset:0x80
	v_add_f32_e32 v20, v20, v118
	v_add_f32_e32 v21, v21, v102
	s_waitcnt lgkmcnt(3)
	v_exp_f32_e32 v103, v103
	v_exp_f32_e32 v104, v104
	v_mfma_f32_32x32x16_bf16 v[144:159], v[6:9], v[180:183], v[144:159]
	v_add_f32_e32 v6, v20, v119
	v_add_f32_e32 v7, v21, v103
	ds_read_b128 v[240:243], v193 offset:0x2080
	v_add_f32_e32 v20, v120, v6
	v_add_f32_e32 v21, v104, v7
	global_load_lds_dwordx4 v[18:19], off
	v_exp_f32_e32 v105, v105
	s_waitcnt lgkmcnt(3)
	v_add_f32_e32 v18, v20, v121
	v_mfma_f32_32x32x16_bf16 v[128:143], v[10:13], v[176:179], v[128:143]
	ds_read_b128 v[6:9], v194 offset:0x80
	v_add_f32_e32 v19, v21, v105
	s_waitcnt lgkmcnt(3)
	s_mov_b32 m0, s26
	v_exp_f32_e32 v106, v106
	v_exp_f32_e32 v107, v107
	v_mfma_f32_32x32x16_bf16 v[144:159], v[24:27], v[176:179], v[144:159]
	v_add_f32_e32 v18, v18, v122
	v_add_f32_e32 v19, v19, v106
	ds_read_b128 v[10:13], v194 offset:0x2080
	v_add_f32_e32 v18, v123, v18
	v_add_f32_e32 v19, v107, v19
	s_waitcnt lgkmcnt(3)
	v_exp_f32_e32 v108, v108
	v_mfma_f32_32x32x16_bf16 v[128:143], v[2:5], v[172:175], v[128:143]
	ds_read_b128 v[2:5], v195 offset:0x80
	v_add_f32_e32 v24, v18, v124
	v_add_f32_e32 v25, v19, v108
	s_waitcnt lgkmcnt(3)
	v_exp_f32_e32 v109, v109
	v_exp_f32_e32 v110, v110
	v_mfma_f32_32x32x16_bf16 v[144:159], v[240:243], v[172:175], v[144:159]
	v_add_f32_e32 v24, v24, v125
	v_add_f32_e32 v25, v25, v109
	ds_read_b128 v[18:21], v195 offset:0x2080
	v_add_f32_e32 v24, v126, v24
	v_add_f32_e32 v25, v110, v25
	global_load_lds_dwordx4 v[22:23], off
	v_exp_f32_e32 v111, v111
	s_waitcnt lgkmcnt(3)
	v_add_f32_e32 v200, v24, v127
	v_mfma_f32_32x32x16_bf16 v[128:143], v[6:9], v[168:171], v[128:143]
	ds_read_b128 v[26:29], v192 offset:0x80
	v_add_f32_e32 v201, v25, v111
	s_waitcnt lgkmcnt(3)
	s_add_i32 m0, s26, 0x2000
	v_mfma_f32_32x32x16_bf16 v[144:159], v[10:13], v[168:171], v[144:159]
	ds_read_b128 v[22:25], v192 offset:0x2080
	v_cvt_pk_bf16_f32 v10, v112, v113
	v_cvt_pk_bf16_f32 v12, v116, v117
	s_nop 0
	v_permlane32_swap_b32_e32 v10, v12
	v_cvt_pk_bf16_f32 v11, v114, v115
	v_cvt_pk_bf16_f32 v13, v118, v119
	s_nop 0
	v_permlane32_swap_b32_e32 v11, v13
	s_waitcnt lgkmcnt(3)
	v_cvt_pk_bf16_f32 v6, v120, v121
	v_cvt_pk_bf16_f32 v8, v124, v125
	v_mfma_f32_32x32x16_bf16 v[128:143], v[2:5], v[164:167], v[128:143]
	v_permlane32_swap_b32_e32 v6, v8
	s_waitcnt lgkmcnt(2)
	v_cvt_pk_bf16_f32 v7, v122, v123
	v_cvt_pk_bf16_f32 v9, v126, v127
	v_mfma_f32_32x32x16_bf16 v[144:159], v[18:21], v[164:167], v[144:159]
	v_permlane32_swap_b32_e32 v7, v9
	v_cvt_pk_bf16_f32 v2, v96, v97
	v_cvt_pk_bf16_f32 v4, v100, v101
	s_nop 0
	v_permlane32_swap_b32_e32 v2, v4
	global_load_lds_dwordx4 v[30:31], off
	s_waitcnt lgkmcnt(1)
	v_cvt_pk_bf16_f32 v3, v98, v99
	v_cvt_pk_bf16_f32 v5, v102, v103
	s_nop 0
	v_mfma_f32_32x32x16_bf16 v[128:143], v[26:29], v[160:163], v[128:143]
	v_permlane32_swap_b32_e32 v3, v5
	s_waitcnt lgkmcnt(0)
	v_cvt_pk_bf16_f32 v192, v104, v105
	v_cvt_pk_bf16_f32 v194, v108, v109
	v_mfma_f32_32x32x16_bf16 v[144:159], v[22:25], v[160:163], v[144:159]
	v_permlane32_swap_b32_e32 v192, v194
	v_cvt_pk_bf16_f32 v193, v106, v107
	v_cvt_pk_bf16_f32 v195, v110, v111
	s_nop 0
	v_permlane32_swap_b32_e32 v193, v195
	v_add_f32_e32 v18, v200, v201
	v_mov_b32_e32 v19, v18
	s_nop 1
	v_permlane32_swap_b32_e32 v18, v19
	v_add_f32_e32 v236, v18, v19
	v_fmac_f32_e32 v236, v239, v17
	s_andn2_b64 vcc, exec, s[24:25]
	s_cbranch_vccz .LBB0_1464
	s_branch .LBB0_1466

.LBB0_1470:
	v_lshl_add_u32 v104, s61, 14, v207
	ds_read_b64_tr_b16 v[18:19], v104 offset:0
	ds_read_b64_tr_b16 v[20:21], v104 offset:0x800
	ds_read_b64_tr_b16 v[22:23], v104 offset:0x1000
	ds_read_b64_tr_b16 v[24:25], v104 offset:0x1800
	ds_read_b64_tr_b16 v[26:27], v104 offset:0x2000
	ds_read_b64_tr_b16 v[28:29], v104 offset:0x2800
	ds_read_b64_tr_b16 v[96:97], v104 offset:0x3000
	v_max3_f32 v30, v128, s72, v129
	ds_read_b64_tr_b16 v[98:99], v104 offset:0x3800
	v_max3_f32 v30, v30, v130, v131
	s_waitcnt lgkmcnt(6)
	v_max3_f32 v30, v30, v132, v133
	v_mfma_f32_32x32x16_bf16 v[64:79], v[10:13], v[18:21], v[64:79]
	v_max3_f32 v30, v30, v134, v135
	ds_read_b64_tr_b16 v[18:19], v104 offset:0x200
	ds_read_b64_tr_b16 v[20:21], v104 offset:0xa00
	s_waitcnt lgkmcnt(6)
	v_max3_f32 v30, v30, v136, v137
	v_max3_f32 v30, v30, v138, v139
	v_max3_f32 v30, v30, v140, v141
	v_mfma_f32_32x32x16_bf16 v[64:79], v[6:9], v[22:25], v[64:79]
	v_max3_f32 v30, v30, v142, v143
	ds_read_b64_tr_b16 v[22:23], v104 offset:0x1200
	ds_read_b64_tr_b16 v[24:25], v104 offset:0x1a00
	s_waitcnt lgkmcnt(6)
	v_max3_f32 v30, v30, v144, v145
	v_max3_f32 v30, v30, v146, v147
	v_max3_f32 v30, v30, v148, v149
	v_mfma_f32_32x32x16_bf16 v[64:79], v[2:5], v[26:29], v[64:79]
	v_max3_f32 v30, v30, v150, v151
	ds_read_b64_tr_b16 v[26:27], v104 offset:0x2200
	ds_read_b64_tr_b16 v[28:29], v104 offset:0x2a00
	s_waitcnt lgkmcnt(6)
	v_max3_f32 v30, v30, v152, v153
	v_max3_f32 v30, v30, v154, v155
	v_max3_f32 v30, v30, v156, v157
	v_mfma_f32_32x32x16_bf16 v[64:79], v[192:195], v[96:99], v[64:79]
	v_max3_f32 v30, v30, v158, v159
	ds_read_b64_tr_b16 v[96:97], v104 offset:0x3200
	ds_read_b64_tr_b16 v[98:99], v104 offset:0x3a00
	s_waitcnt lgkmcnt(6)
	v_mov_b32_e32 v31, v30
	s_nop 1
	v_permlane32_swap_b32_e32 v30, v31
	v_max_f32_e32 v31, v31, v31
	v_max_f32_e32 v30, v30, v30
	v_mfma_f32_32x32x16_bf16 v[80:95], v[10:13], v[18:21], v[80:95]
	v_max_f32_e32 v19, v30, v31
	v_sub_f32_e32 v18, v19, v238
	v_cmp_ge_f32_e32 vcc, s83, v18
	s_cmp_eq_u64 vcc, exec
	v_max_f32_e32 v17, v17, v19
	s_cselect_b64 vcc, -1, 0
	v_cndmask_b32_e32 v237, v17, v238, vcc
	v_sub_f32_e32 v17, v238, v237
	v_mov_b32_e32 v18, v237
	v_exp_f32_e32 v205, v17
	ds_read_b64_tr_b16 v[100:101], v104 offset:0x400
	ds_read_b64_tr_b16 v[102:103], v104 offset:0xc00
	s_waitcnt lgkmcnt(6)
	v_sub_f32_e32 v17, v128, v18
	v_mfma_f32_32x32x16_bf16 v[80:95], v[6:9], v[22:25], v[80:95]
	v_sub_f32_e32 v144, v144, v18
	v_exp_f32_e32 v128, v17
	ds_read_b64_tr_b16 v[20:21], v104 offset:0x1400
	ds_read_b64_tr_b16 v[22:23], v104 offset:0x1c00
	s_waitcnt lgkmcnt(6)
	v_sub_f32_e32 v17, v129, v18
	v_mfma_f32_32x32x16_bf16 v[80:95], v[2:5], v[26:29], v[80:95]
	v_sub_f32_e32 v145, v145, v18
	v_exp_f32_e32 v129, v17
	ds_read_b64_tr_b16 v[24:25], v104 offset:0x2400
	ds_read_b64_tr_b16 v[26:27], v104 offset:0x2c00
	s_waitcnt lgkmcnt(6)
	v_sub_f32_e32 v17, v130, v18
	v_sub_f32_e32 v28, v131, v18
	v_mfma_f32_32x32x16_bf16 v[80:95], v[192:195], v[96:99], v[80:95]
	v_add_f32_e64 v146, v146, -v18
	v_add_f32_e64 v147, v147, -v18
	v_exp_f32_e32 v130, v17
	v_exp_f32_e32 v131, v28
	ds_read_b64_tr_b16 v[28:29], v104 offset:0x3400
	ds_read_b64_tr_b16 v[30:31], v104 offset:0x3c00
	s_waitcnt lgkmcnt(6)
	v_sub_f32_e32 v17, v132, v18
	v_mfma_f32_32x32x16_bf16 v[48:63], v[10:13], v[100:103], v[48:63]
	v_sub_f32_e32 v148, v148, v18
	v_exp_f32_e32 v132, v17
	ds_read_b64_tr_b16 v[96:97], v104 offset:0x600
	ds_read_b64_tr_b16 v[98:99], v104 offset:0xe00
	s_waitcnt lgkmcnt(6)
	v_mov_b32_e32 v100, v149
	v_mov_b32_e32 v101, v150
	v_sub_f32_e32 v17, v133, v18
	v_sub_f32_e32 v102, v134, v18
	v_pk_add_f32 v[100:101], v[100:101], v[18:19] op_sel_hi:[1,0] neg_lo:[0,1] neg_hi:[0,1]
	v_mfma_f32_32x32x16_bf16 v[48:63], v[6:9], v[20:23], v[48:63]
	v_exp_f32_e32 v133, v17
	v_exp_f32_e32 v134, v102
	v_mov_b32_e32 v149, v100
	v_mov_b32_e32 v150, v101
	ds_read_b64_tr_b16 v[20:21], v104 offset:0x1600
	ds_read_b64_tr_b16 v[22:23], v104 offset:0x1e00
	s_waitcnt lgkmcnt(6)
	v_sub_f32_e32 v17, v135, v18
	v_mfma_f32_32x32x16_bf16 v[48:63], v[2:5], v[24:27], v[48:63]
	v_sub_f32_e32 v151, v151, v18
	v_exp_f32_e32 v135, v17
	ds_read_b64_tr_b16 v[24:25], v104 offset:0x2600
	ds_read_b64_tr_b16 v[26:27], v104 offset:0x2e00
	s_waitcnt lgkmcnt(6)
	v_sub_f32_e32 v17, v136, v18
	v_sub_f32_e32 v100, v137, v18
	v_mfma_f32_32x32x16_bf16 v[48:63], v[192:195], v[28:31], v[48:63]
	v_add_f32_e64 v152, v152, -v18
	v_add_f32_e64 v153, v153, -v18
	v_exp_f32_e32 v136, v17
	v_exp_f32_e32 v137, v100
	ds_read_b64_tr_b16 v[28:29], v104 offset:0x3600
	ds_read_b64_tr_b16 v[30:31], v104 offset:0x3e00
	s_waitcnt lgkmcnt(6)
	v_sub_f32_e32 v17, v138, v18
	v_sub_f32_e32 v154, v154, v18
	v_exp_f32_e32 v138, v17
	v_mfma_f32_32x32x16_bf16 v[32:47], v[10:13], v[96:99], v[32:47]
	s_waitcnt lgkmcnt(4)
	v_mov_b32_e32 v10, v155
	v_mov_b32_e32 v11, v156
	v_sub_f32_e32 v12, v139, v18
	v_sub_f32_e32 v13, v140, v18
	v_pk_add_f32 v[10:11], v[10:11], v[18:19] op_sel_hi:[1,0] neg_lo:[0,1] neg_hi:[0,1]
	v_exp_f32_e32 v139, v12
	v_exp_f32_e32 v140, v13
	v_mfma_f32_32x32x16_bf16 v[32:47], v[6:9], v[20:23], v[32:47]
	v_mov_b32_e32 v155, v10
	v_mov_b32_e32 v156, v11
	s_waitcnt lgkmcnt(2)
	v_sub_f32_e32 v6, v141, v18
	v_sub_f32_e32 v157, v157, v18
	v_exp_f32_e32 v141, v6
	v_mfma_f32_32x32x16_bf16 v[32:47], v[2:5], v[24:27], v[32:47]
	s_waitcnt lgkmcnt(0)
	v_sub_f32_e32 v2, v142, v18
	v_sub_f32_e32 v3, v143, v18
	v_pk_add_f32 v[158:159], v[158:159], v[18:19] op_sel_hi:[1,0] neg_lo:[0,1] neg_hi:[0,1]
	v_exp_f32_e32 v142, v2
	v_exp_f32_e32 v143, v3
	v_mfma_f32_32x32x16_bf16 v[32:47], v[192:195], v[28:31], v[32:47]
	v_mov_b64_e32 v[112:113], v[144:145]
	v_mov_b64_e32 v[114:115], v[146:147]
	v_mov_b64_e32 v[116:117], v[148:149]
	v_mov_b64_e32 v[118:119], v[150:151]
	v_mov_b64_e32 v[120:121], v[152:153]
	v_mov_b64_e32 v[122:123], v[154:155]
	v_mov_b64_e32 v[124:125], v[156:157]
	v_mov_b64_e32 v[126:127], v[158:159]
	v_mov_b32_e32 v96, v128
	v_mov_b32_e32 v97, v129
	v_mov_b32_e32 v98, v130
	v_mov_b32_e32 v99, v131
	v_mov_b32_e32 v100, v132
	v_mov_b32_e32 v101, v133
	v_mov_b32_e32 v102, v134
	v_mov_b32_e32 v103, v135
	v_mov_b32_e32 v104, v136
	v_mov_b32_e32 v105, v137
	v_mov_b32_e32 v106, v138
	v_mov_b32_e32 v107, v139
	v_mov_b32_e32 v108, v140
	v_mov_b32_e32 v109, v141
	v_mov_b32_e32 v110, v142
	v_mov_b32_e32 v111, v143
	v_cmp_gt_f32_e32 vcc, 1.0, v205
	s_cbranch_vccz .LBB0_1443

.LBB0_1696:
	ds_read_b128 v[2:5], v121 offset:49152
	ds_read_b128 v[6:9], v121 offset:49280
	v_exp_f32_e32 v14, v64
	v_exp_f32_e32 v15, v63
	v_exp_f32_e32 v64, v62
	s_waitcnt lgkmcnt(1)
	v_mfma_f32_32x32x16_bf16 v[18:33], v[2:5], v[102:105], 0
	ds_read_b128 v[2:5], v120 offset:49152
	v_exp_f32_e32 v65, v61
	v_exp_f32_e32 v80, v60
	ds_read_b128 v[10:13], v119 offset:49152
	ds_read_b128 v[34:37], v121 offset:57344
	ds_read_b128 v[60:63], v121 offset:57472
	ds_read_b128 v[38:41], v120 offset:49280
	v_exp_f32_e32 v81, v59
	v_exp_f32_e32 v112, v58
	v_exp_f32_e32 v113, v57
	v_exp_f32_e32 v124, v56
	s_waitcnt lgkmcnt(4)
	v_mfma_f32_32x32x16_bf16 v[18:33], v[2:5], v[98:101], v[18:33]
	ds_read_b128 v[2:5], v120 offset:57344
	ds_read_b128 v[76:79], v120 offset:57472
	ds_read_b128 v[42:45], v119 offset:49280
	ds_read_b128 v[132:135], v119 offset:57344
	ds_read_b128 v[136:139], v119 offset:57472
	ds_read_b128 v[46:49], v118 offset:49152
	ds_read_b128 v[140:143], v118 offset:49280
	v_exp_f32_e32 v55, v55
	v_exp_f32_e32 v54, v54
	v_exp_f32_e32 v53, v53
	v_exp_f32_e32 v17, v17
	s_waitcnt lgkmcnt(10)
	v_mfma_f32_32x32x16_bf16 v[18:33], v[10:13], v[94:97], v[18:33]
	ds_read_b128 v[10:13], v118 offset:57344
	ds_read_b128 v[144:147], v118 offset:57472
	ds_read_b128 v[56:59], v115
	ds_read_b128 v[148:151], v115 offset:1024
	s_waitcnt lgkmcnt(5)
	v_mfma_f32_32x32x16_bf16 v[18:33], v[46:49], v[90:93], v[18:33]
	v_add_f32_e32 v49, 0, v128
	v_add_f32_e32 v49, v129, v49
	v_add_f32_e32 v49, v130, v49
	v_exp_f32_e32 v46, v52
	v_exp_f32_e32 v47, v51
	v_exp_f32_e32 v48, v50
	v_mfma_f32_32x32x16_bf16 v[18:33], v[6:9], v[86:89], v[18:33]
	v_add_f32_e32 v6, v69, v49
	v_add_f32_e32 v6, v70, v6
	v_add_f32_e32 v6, v71, v6
	v_add_f32_e32 v6, v72, v6
	v_add_f32_e32 v6, v73, v6
	v_add_f32_e32 v6, v74, v6
	v_add_f32_e32 v6, v75, v6
	v_mfma_f32_32x32x16_bf16 v[18:33], v[38:41], v[82:85], v[18:33]
	v_add_f32_e32 v6, v66, v6
	v_add_f32_e32 v6, v67, v6
	v_add_f32_e32 v6, v68, v6
	v_add_f32_e32 v6, v126, v6
	v_add_f32_e32 v6, v127, v6
	v_add_f32_e32 v6, v107, v6
	v_add_f32_e32 v6, v14, v6
	v_add_f32_e32 v6, v15, v6
	s_waitcnt lgkmcnt(1)
	v_mfma_f32_32x32x16_bf16 v[18:33], v[42:45], v[56:59], v[18:33]
	v_add_f32_e32 v6, v64, v6
	v_add_f32_e32 v6, v65, v6
	v_add_f32_e32 v6, v80, v6
	v_add_f32_e32 v6, v81, v6
	v_add_f32_e32 v6, v112, v6
	v_add_f32_e32 v6, v113, v6
	v_add_f32_e32 v6, v124, v6
	v_add_f32_e32 v6, v55, v6
	s_waitcnt lgkmcnt(0)
	v_mfma_f32_32x32x16_bf16 v[18:33], v[140:143], v[148:151], v[18:33]
	v_add_f32_e32 v6, v54, v6
	v_add_f32_e32 v6, v53, v6
	v_add_f32_e32 v6, v46, v6
	v_add_f32_e32 v6, v47, v6
	v_add_f32_e32 v6, v48, v6
	v_add_f32_e32 v124, v17, v6
	v_mov_b32_e32 v125, v124
	s_nop 1
	v_permlane32_swap_b32_e32 v124, v125
	v_mfma_f32_32x32x16_bf16 v[34:49], v[34:37], v[102:105], 0
	v_mov_b32_e32 v6, v116
	v_mfma_f32_32x32x16_bf16 v[34:49], v[2:5], v[98:101], v[34:49]
	v_ashrrev_i32_e32 v2, 31, v6
	v_lshrrev_b32_e32 v2, 28, v2
	v_add_lshl_u32 v2, v6, v2, 3
	v_and_b32_e32 v2, 0xffffff80, v2
	v_lshlrev_b32_e32 v4, 3, v6
	v_sub_u32_e32 v4, v4, v2
	v_ashrrev_i32_e32 v5, 31, v4
	v_ashrrev_i32_e32 v3, 31, v2
	v_lshlrev_b64 v[4:5], 1, v[4:5]
	v_add_u32_e32 v6, 0x200, v6
	v_lshl_add_u64 v[2:3], v[2:3], 1, v[4:5]
	v_ashrrev_i32_e32 v4, 31, v6
	v_lshrrev_b32_e32 v4, 28, v4
	v_add_lshl_u32 v4, v6, v4, 3
	v_and_b32_e32 v4, 0xffffff80, v4
	v_lshlrev_b32_e32 v6, 3, v6
	v_sub_u32_e32 v6, v6, v4
	v_ashrrev_i32_e32 v7, 31, v6
	v_ashrrev_i32_e32 v5, 31, v4
	v_lshlrev_b64 v[6:7], 1, v[6:7]
	v_lshl_add_u64 v[4:5], v[4:5], 1, v[6:7]
	v_lshl_add_u64 v[2:3], s[6:7], 0, v[2:3]
	v_lshl_add_u64 v[4:5], s[6:7], 0, v[4:5]
	flat_load_dwordx4 v[6:9], v[2:3]
	flat_load_dwordx4 v[2:5], v[4:5]
	v_mfma_f32_32x32x16_bf16 v[34:49], v[132:135], v[94:97], v[34:49]
	v_mfma_f32_32x32x16_bf16 v[34:49], v[10:13], v[90:93], v[34:49]
	v_mfma_f32_32x32x16_bf16 v[34:49], v[60:63], v[86:89], v[34:49]
	v_mfma_f32_32x32x16_bf16 v[34:49], v[76:79], v[82:85], v[34:49]
	v_mfma_f32_32x32x16_bf16 v[34:49], v[136:139], v[56:59], v[34:49]
	v_mfma_f32_32x32x16_bf16 v[34:49], v[144:147], v[148:151], v[34:49]
	v_add_u32_e32 v17, 0x7b, v0
	v_cvt_f32_i32_e32 v10, v17
	s_mov_b32 s0, 2.0
	s_mov_b32 s1, 0x40400000
	v_mov_b32_e32 v107, v106
	v_mul_f32_e64 v50, -v106, v10
	v_pk_fma_f32 v[52:53], v[110:111], s[0:1], v[50:51] op_sel_hi:[1,1,0]
	s_mov_b32 s0, 0x41000000
	s_mov_b32 s1, 0x41100000
	v_pk_fma_f32 v[54:55], v[110:111], s[0:1], v[50:51] op_sel_hi:[1,1,0]
	s_mov_b32 s0, 0x41200000
	s_mov_b32 s1, 0x41300000
	v_pk_fma_f32 v[56:57], v[110:111], s[0:1], v[50:51] op_sel_hi:[1,1,0]
	s_mov_b32 s0, 0x41800000
	s_mov_b32 s1, 0x41880000
	v_pk_fma_f32 v[58:59], v[110:111], s[0:1], v[50:51] op_sel_hi:[1,1,0]
	s_mov_b32 s0, 0x41900000
	s_mov_b32 s1, 0x41980000
	v_pk_fma_f32 v[14:15], v[110:111], s[0:1], v[50:51] op_sel_hi:[1,1,0]
	s_mov_b32 s0, 0x41c00000
	s_mov_b32 s1, 0x41c80000
	v_pk_fma_f32 v[12:13], v[110:111], s[0:1], v[50:51] op_sel_hi:[1,1,0]
	s_mov_b32 s0, 0x41d00000
	s_mov_b32 s1, 0x41d80000
	v_pk_fma_f32 v[60:61], v[110:111], s[0:1], v[50:51] op_sel_hi:[1,1,0]
	s_mov_b32 s0, 0x42080000
	s_mov_b32 s1, 0x420c0000
	v_pk_add_f32 v[14:15], v[14:15], v[28:29]
	v_pk_fma_f32 v[28:29], v[106:107], s[0:1], v[50:51] op_sel_hi:[1,1,0]
	s_mov_b32 s0, 0x42200000
	s_mov_b32 s1, 0x42240000
	v_fma_f32 v11, -v106, v10, v106
	v_mov_b32_e32 v10, v50
	v_pk_add_f32 v[12:13], v[12:13], v[30:31]
	v_pk_fma_f32 v[30:31], v[106:107], s[0:1], v[50:51] op_sel_hi:[1,1,0]
	s_mov_b32 s0, 0x42280000
	v_fmac_f32_e32 v10, 0, v106
	s_mov_b32 s1, 0x422c0000
	v_pk_add_f32 v[18:19], v[10:11], v[18:19]
	v_pk_add_f32 v[10:11], v[60:61], v[32:33]
	v_pk_fma_f32 v[32:33], v[106:107], s[0:1], v[50:51] op_sel_hi:[1,1,0]
	s_mov_b32 s0, 0x42400000
	s_mov_b32 s1, 0x42440000
	v_pk_add_f32 v[20:21], v[52:53], v[20:21]
	v_pk_fma_f32 v[52:53], v[106:107], s[0:1], v[50:51] op_sel_hi:[1,1,0]
	s_mov_b32 s0, 0x42480000
	s_mov_b32 s1, 0x424c0000
	v_pk_add_f32 v[22:23], v[54:55], v[22:23]
	v_pk_fma_f32 v[54:55], v[106:107], s[0:1], v[50:51] op_sel_hi:[1,1,0]
	s_mov_b32 s0, 0x42600000
	s_mov_b32 s1, 0x42640000
	v_pk_add_f32 v[24:25], v[56:57], v[24:25]
	v_pk_fma_f32 v[56:57], v[106:107], s[0:1], v[50:51] op_sel_hi:[1,1,0]
	s_mov_b32 s0, 0x42000000
	s_mov_b32 s1, 0x42040000
	v_pk_add_f32 v[26:27], v[58:59], v[26:27]
	v_pk_fma_f32 v[58:59], v[106:107], s[94:95], v[50:51] op_sel_hi:[1,1,0]
	v_pk_fma_f32 v[50:51], v[108:109], s[0:1], v[50:51] op_sel_hi:[1,1,0]
	s_sub_i32 s0, s21, 64
	v_pk_add_f32 v[48:49], v[58:59], v[48:49]
	v_pk_add_f32 v[46:47], v[56:57], v[46:47]
	v_pk_add_f32 v[44:45], v[54:55], v[44:45]
	v_pk_add_f32 v[42:43], v[52:53], v[42:43]
	v_pk_add_f32 v[40:41], v[32:33], v[40:41]
	v_pk_add_f32 v[38:39], v[30:31], v[38:39]
	v_pk_add_f32 v[36:37], v[28:29], v[36:37]
	s_cmp_le_i32 s0, s18
	v_pk_add_f32 v[34:35], v[50:51], v[34:35]
	s_cbranch_scc1 .LBB0_1698
	v_cmp_gt_u32_e32 vcc, 2.0, v17
	v_add_u32_e32 v17, 0x5b, v0
	s_nop 0
	v_cndmask_b32_e32 v18, v16, v18, vcc
	v_cmp_gt_u32_e32 vcc, 2.0, v17
	v_add_u32_e32 v17, 0x7a, v0
	s_nop 0
	v_cndmask_b32_e32 v34, v16, v34, vcc
	v_cmp_gt_u32_e32 vcc, 2.0, v17
	v_add_u32_e32 v17, 0x5a, v0
	s_nop 0
	v_cndmask_b32_e32 v19, v16, v19, vcc
	v_cmp_gt_u32_e32 vcc, 2.0, v17
	v_add_u32_e32 v17, 0x79, v0
	s_nop 0
	v_cndmask_b32_e32 v35, v16, v35, vcc
	v_cmp_gt_u32_e32 vcc, 2.0, v17
	v_add_u32_e32 v17, 0x59, v0
	s_nop 0
	v_cndmask_b32_e32 v20, v16, v20, vcc
	v_cmp_gt_u32_e32 vcc, 2.0, v17
	v_add_u32_e32 v17, 0x78, v0
	s_nop 0
	v_cndmask_b32_e32 v36, v16, v36, vcc
	v_cmp_gt_u32_e32 vcc, 2.0, v17
	v_add_u32_e32 v17, 0x58, v0
	s_nop 0
	v_cndmask_b32_e32 v21, v16, v21, vcc
	v_cmp_gt_u32_e32 vcc, 2.0, v17
	v_add_u32_e32 v17, 0x73, v0
	s_nop 0
	v_cndmask_b32_e32 v37, v16, v37, vcc
	v_cmp_gt_u32_e32 vcc, 2.0, v17
	v_add_u32_e32 v17, 0x53, v0
	s_nop 0
	v_cndmask_b32_e32 v22, v16, v22, vcc
	v_cmp_gt_u32_e32 vcc, 2.0, v17
	v_add_u32_e32 v17, 0x72, v0
	s_nop 0
	v_cndmask_b32_e32 v38, v16, v38, vcc
	v_cmp_gt_u32_e32 vcc, 2.0, v17
	v_add_u32_e32 v17, 0x52, v0
	s_nop 0
	v_cndmask_b32_e32 v23, v16, v23, vcc
	v_cmp_gt_u32_e32 vcc, 2.0, v17
	v_add_u32_e32 v17, 0x71, v0
	s_nop 0
	v_cndmask_b32_e32 v39, v16, v39, vcc
	v_cmp_gt_u32_e32 vcc, 2.0, v17
	v_add_u32_e32 v17, 0x51, v0
	s_nop 0
	v_cndmask_b32_e32 v24, v16, v24, vcc
	v_cmp_gt_u32_e32 vcc, 2.0, v17
	v_add_u32_e32 v17, 0x70, v0
	s_nop 0
	v_cndmask_b32_e32 v40, v16, v40, vcc
	v_cmp_gt_u32_e32 vcc, 2.0, v17
	v_add_u32_e32 v17, 0x50, v0
	s_nop 0
	v_cndmask_b32_e32 v25, v16, v25, vcc
	v_cmp_gt_u32_e32 vcc, 2.0, v17
	v_add_u32_e32 v17, 0x6b, v0
	s_nop 0
	v_cndmask_b32_e32 v41, v16, v41, vcc
	v_cmp_gt_u32_e32 vcc, 2.0, v17
	v_add_u32_e32 v17, 0x4b, v0
	s_nop 0
	v_cndmask_b32_e32 v26, v16, v26, vcc
	v_cmp_gt_u32_e32 vcc, 2.0, v17
	v_add_u32_e32 v17, 0x6a, v0
	s_nop 0
	v_cndmask_b32_e32 v42, v16, v42, vcc
	v_cmp_gt_u32_e32 vcc, 2.0, v17
	v_add_u32_e32 v17, 0x4a, v0
	s_nop 0
	v_cndmask_b32_e32 v27, v16, v27, vcc
	v_cmp_gt_u32_e32 vcc, 2.0, v17
	v_add_u32_e32 v17, 0x69, v0
	s_nop 0
	v_cndmask_b32_e32 v43, v16, v43, vcc
	v_cmp_gt_u32_e32 vcc, 2.0, v17
	v_add_u32_e32 v17, 0x49, v0
	s_nop 0
	v_cndmask_b32_e32 v14, v16, v14, vcc
	v_cmp_gt_u32_e32 vcc, 2.0, v17
	v_add_u32_e32 v17, 0x68, v0
	s_nop 0
	v_cndmask_b32_e32 v44, v16, v44, vcc
	v_cmp_gt_u32_e32 vcc, 2.0, v17
	v_add_u32_e32 v17, 0x48, v0
	s_nop 0
	v_cndmask_b32_e32 v15, v16, v15, vcc
	v_cmp_gt_u32_e32 vcc, 2.0, v17
	v_add_u32_e32 v17, 0x63, v0
	s_nop 0
	v_cndmask_b32_e32 v45, v16, v45, vcc
	v_cmp_gt_u32_e32 vcc, 2.0, v17
	v_add_u32_e32 v17, 0x43, v0
	s_nop 0
	v_cndmask_b32_e32 v12, v16, v12, vcc
	v_cmp_gt_u32_e32 vcc, 2.0, v17
	v_add_u32_e32 v17, 0x62, v0
	s_nop 0
	v_cndmask_b32_e32 v46, v16, v46, vcc
	v_cmp_gt_u32_e32 vcc, 2.0, v17
	v_add_u32_e32 v17, 0x42, v0
	s_nop 0
	v_cndmask_b32_e32 v13, v16, v13, vcc
	v_cmp_gt_u32_e32 vcc, 2.0, v17
	v_add_u32_e32 v17, 0x61, v0
	s_nop 0
	v_cndmask_b32_e32 v47, v16, v47, vcc
	v_cmp_gt_u32_e32 vcc, 2.0, v17
	v_add_u32_e32 v17, 0x41, v0
	s_nop 0
	v_cndmask_b32_e32 v10, v16, v10, vcc
	v_cmp_gt_u32_e32 vcc, 2.0, v17
	v_add_u32_e32 v17, 0x60, v0
	s_nop 0
	v_cndmask_b32_e32 v48, v16, v48, vcc
	v_cmp_gt_u32_e32 vcc, 2.0, v17
	v_add_u32_e32 v17, 64, v0
	s_nop 0
	v_cndmask_b32_e32 v11, v16, v11, vcc
	v_cmp_gt_u32_e32 vcc, 2.0, v17
	s_nop 1
	v_cndmask_b32_e32 v49, v16, v49, vcc
.LBB0_1698:
	v_max_f32_e32 v17, v19, v19
	v_max_f32_e32 v28, v18, v18
	v_max_f32_e32 v17, v28, v17
	v_max3_f32 v17, v17, v20, v21
	v_max3_f32 v17, v17, v22, v23
	v_max3_f32 v17, v17, v24, v25
	v_max3_f32 v17, v17, v26, v27
	v_max3_f32 v17, v17, v14, v15
	v_max3_f32 v17, v17, v12, v13
	v_max3_f32 v17, v17, v10, v11
	v_max3_f32 v17, v17, v34, v35
	v_max3_f32 v17, v17, v36, v37
	v_max3_f32 v17, v17, v38, v39
	v_max3_f32 v17, v17, v40, v41
	v_max3_f32 v17, v17, v42, v43
	v_max3_f32 v17, v17, v44, v45
	v_max3_f32 v17, v17, v46, v47
	v_max3_f32 v17, v17, v48, v49
	v_mov_b32_e32 v28, v17
	s_nop 1
	v_permlane32_swap_b32_e32 v17, v28
	v_max_f32_e32 v28, v28, v28
	v_max_f32_e32 v17, v17, v17
	v_max_f32_e32 v17, v17, v28
	v_sub_f32_e32 v28, v17, v114
	v_cmp_ge_f32_e32 vcc, s83, v28
	s_cmp_eq_u64 vcc, exec
	v_max_f32_e32 v28, v114, v114
	v_max_f32_e32 v126, v28, v17
	s_cselect_b64 s[0:1], -1, 0
	v_cndmask_b32_e64 v17, v126, v114, s[0:1]
	v_sub_f32_e32 v10, v10, v17
	v_sub_f32_e32 v12, v12, v17
	v_exp_f32_e32 v32, v10
	v_mov_b32_e32 v10, v116
	v_exp_f32_e32 v30, v12
	s_waitcnt lgkmcnt(0)
	s_barrier
	s_waitcnt vmcnt(0)
	v_sub_f32_e32 v14, v14, v17
	v_ashrrev_i32_e32 v12, 31, v10
	v_lshrrev_b32_e32 v12, 28, v12
	v_add_u32_e32 v12, v10, v12
	v_exp_f32_e32 v28, v14
	v_lshlrev_b32_e32 v14, 4, v12
	v_and_b32_e32 v14, 0xffffff00, v14
	v_lshlrev_b32_e32 v29, 4, v10
	v_sub_u32_e32 v29, v29, v14
	v_bitop3_b32 v12, v29, v12, s73 bitop3:0x78
	v_add3_u32 v12, 0, v14, v12
	v_add_u32_e32 v10, 0x200, v10
	s_waitcnt vmcnt(0)
	ds_write_b128 v12, v[6:9] offset:32768
	v_ashrrev_i32_e32 v12, 31, v10
	v_lshrrev_b32_e32 v12, 28, v12
	v_add_u32_e32 v12, v10, v12
	v_lshlrev_b32_e32 v14, 4, v12
	v_and_b32_e32 v14, 0xffffff00, v14
	v_lshlrev_b32_e32 v10, 4, v10
	v_sub_u32_e32 v10, v10, v14
	v_bitop3_b32 v10, v10, v12, s73 bitop3:0x78
	v_add3_u32 v10, 0, v14, v10
	v_sub_f32_e32 v18, v18, v17
	v_sub_f32_e32 v20, v20, v17
	v_sub_f32_e32 v22, v22, v17
	v_sub_f32_e32 v24, v24, v17
	v_sub_f32_e32 v26, v26, v17
	ds_write_b128 v10, v[2:5] offset:32768
	v_sub_f32_e32 v10, v19, v17
	v_sub_f32_e32 v12, v21, v17
	v_sub_f32_e32 v23, v23, v17
	v_sub_f32_e32 v25, v25, v17
	v_sub_f32_e32 v27, v27, v17
	v_sub_f32_e32 v15, v15, v17
	v_sub_f32_e32 v13, v13, v17
	v_sub_f32_e32 v11, v11, v17
	v_exp_f32_e32 v18, v18
	v_exp_f32_e32 v20, v20
	v_exp_f32_e32 v22, v22
	v_exp_f32_e32 v24, v24
	v_exp_f32_e32 v26, v26
	v_exp_f32_e32 v19, v10
	v_exp_f32_e32 v21, v12
	v_exp_f32_e32 v23, v23
	v_exp_f32_e32 v25, v25
	v_exp_f32_e32 v27, v27
	v_exp_f32_e32 v29, v15
	v_exp_f32_e32 v31, v13
	v_exp_f32_e32 v33, v11
	v_sub_f32_e32 v42, v42, v17
	v_sub_f32_e32 v43, v43, v17
	v_sub_f32_e32 v44, v44, v17
	v_sub_f32_e32 v45, v45, v17
	v_sub_f32_e32 v46, v46, v17
	v_sub_f32_e32 v47, v47, v17
	v_sub_f32_e32 v48, v48, v17
	v_sub_f32_e32 v49, v49, v17
	v_sub_f32_e32 v14, v34, v17
	v_sub_f32_e32 v107, v35, v17
	v_sub_f32_e32 v112, v36, v17
	v_sub_f32_e32 v113, v37, v17
	v_sub_f32_e32 v127, v38, v17
	v_sub_f32_e32 v128, v39, v17
	v_sub_f32_e32 v129, v40, v17
	v_sub_f32_e32 v130, v41, v17
	s_waitcnt lgkmcnt(0)
	s_barrier
	ds_read_b128 v[10:13], v121 offset:32768
	ds_read_b128 v[34:37], v121 offset:40960
	v_exp_f32_e32 v42, v42
	v_exp_f32_e32 v43, v43
	v_exp_f32_e32 v44, v44
	s_waitcnt lgkmcnt(1)
	v_mfma_f32_32x32x16_bf16 v[66:81], v[10:13], v[102:105], 0
	v_exp_f32_e32 v45, v45
	v_exp_f32_e32 v46, v46
	v_exp_f32_e32 v47, v47
	v_exp_f32_e32 v48, v48
	v_exp_f32_e32 v49, v49
	s_waitcnt lgkmcnt(0)
	v_mfma_f32_32x32x16_bf16 v[50:65], v[34:37], v[102:105], 0
	ds_read_b128 v[10:13], v120 offset:32768
	ds_read_b128 v[34:37], v120 offset:40960
	s_waitcnt lgkmcnt(1)
	v_mfma_f32_32x32x16_bf16 v[66:81], v[10:13], v[98:101], v[66:81]
	s_waitcnt lgkmcnt(0)
	v_mfma_f32_32x32x16_bf16 v[50:65], v[34:37], v[98:101], v[50:65]
	ds_read_b128 v[10:13], v119 offset:32768
	ds_read_b128 v[34:37], v119 offset:40960
	s_waitcnt lgkmcnt(1)
	v_mfma_f32_32x32x16_bf16 v[66:81], v[10:13], v[94:97], v[66:81]
	s_waitcnt lgkmcnt(0)
	v_mfma_f32_32x32x16_bf16 v[50:65], v[34:37], v[94:97], v[50:65]
	ds_read_b128 v[10:13], v118 offset:32768
	ds_read_b128 v[34:37], v118 offset:40960
	s_waitcnt lgkmcnt(1)
	v_mfma_f32_32x32x16_bf16 v[66:81], v[10:13], v[90:93], v[66:81]
	s_waitcnt lgkmcnt(0)
	v_mfma_f32_32x32x16_bf16 v[50:65], v[34:37], v[90:93], v[50:65]
	ds_read_b128 v[10:13], v121 offset:32896
	ds_read_b128 v[34:37], v121 offset:41088
	s_waitcnt lgkmcnt(1)
	v_mfma_f32_32x32x16_bf16 v[66:81], v[10:13], v[86:89], v[66:81]
	s_waitcnt lgkmcnt(0)
	v_mfma_f32_32x32x16_bf16 v[50:65], v[34:37], v[86:89], v[50:65]
	ds_read_b128 v[10:13], v120 offset:32896
	ds_read_b128 v[34:37], v120 offset:41088
	s_waitcnt lgkmcnt(1)
	v_mfma_f32_32x32x16_bf16 v[66:81], v[10:13], v[82:85], v[66:81]
	s_waitcnt lgkmcnt(0)
	v_mfma_f32_32x32x16_bf16 v[50:65], v[34:37], v[82:85], v[50:65]
	ds_read_b128 v[10:13], v119 offset:32896
	ds_read_b128 v[34:37], v119 offset:41088
	ds_read_b128 v[38:41], v115
	s_waitcnt lgkmcnt(0)
	v_mfma_f32_32x32x16_bf16 v[66:81], v[10:13], v[38:41], v[66:81]
	v_mfma_f32_32x32x16_bf16 v[50:65], v[34:37], v[38:41], v[50:65]
	ds_read_b128 v[10:13], v118 offset:32896
	ds_read_b128 v[34:37], v118 offset:41088
	ds_read_b128 v[38:41], v115 offset:1024
	s_waitcnt lgkmcnt(0)
	v_mfma_f32_32x32x16_bf16 v[66:81], v[10:13], v[38:41], v[66:81]
	v_add_f32_e32 v10, 0, v18
	v_add_f32_e32 v10, v19, v10
	v_add_f32_e32 v10, v20, v10
	v_add_f32_e32 v10, v21, v10
	v_add_f32_e32 v10, v22, v10
	v_add_f32_e32 v10, v23, v10
	v_add_f32_e32 v10, v24, v10
	v_add_f32_e32 v10, v25, v10
	v_add_f32_e32 v10, v26, v10
	v_add_f32_e32 v10, v27, v10
	v_add_f32_e32 v10, v28, v10
	v_add_f32_e32 v10, v29, v10
	v_mfma_f32_32x32x16_bf16 v[50:65], v[34:37], v[38:41], v[50:65]
	v_exp_f32_e32 v34, v14
	v_add_f32_e32 v10, v30, v10
	v_exp_f32_e32 v35, v107
	v_add_f32_e32 v10, v31, v10
	v_exp_f32_e32 v36, v112
	v_add_f32_e32 v10, v32, v10
	v_exp_f32_e32 v37, v113
	v_add_f32_e32 v10, v33, v10
	v_exp_f32_e32 v38, v127
	v_add_f32_e32 v10, v34, v10
	v_exp_f32_e32 v39, v128
	v_add_f32_e32 v10, v35, v10
	v_exp_f32_e32 v40, v129
	v_add_f32_e32 v10, v36, v10
	v_exp_f32_e32 v41, v130
	v_add_f32_e32 v10, v37, v10
	v_add_f32_e32 v10, v38, v10
	v_add_f32_e32 v10, v39, v10
	v_add_f32_e32 v10, v40, v10
	v_add_f32_e32 v10, v41, v10
	v_add_f32_e32 v10, v42, v10
	v_add_f32_e32 v10, v43, v10
	v_add_f32_e32 v10, v44, v10
	v_add_f32_e32 v10, v45, v10
	v_add_f32_e32 v10, v46, v10
	v_add_f32_e32 v10, v47, v10
	v_add_f32_e32 v10, v48, v10
	v_add_f32_e32 v131, v49, v10
	v_mov_b32_e32 v132, v131
	s_nop 1
	v_permlane32_swap_b32_e32 v131, v132
	s_add_i32 s4, s22, 1
	s_cmp_le_u32 s4, s16
	s_cselect_b64 s[14:15], -1, 0
	s_cmp_gt_u32 s4, s16
	s_cbranch_scc1 .LBB0_1700
	v_mov_b32_e32 v6, v116
	v_ashrrev_i32_e32 v2, 31, v6
	v_lshrrev_b32_e32 v2, 28, v2
	v_add_lshl_u32 v2, v6, v2, 3
	v_and_b32_e32 v2, 0xffffff80, v2
	v_lshlrev_b32_e32 v4, 3, v6
	v_sub_u32_e32 v4, v4, v2
	v_ashrrev_i32_e32 v5, 31, v4
	v_ashrrev_i32_e32 v3, 31, v2
	v_lshlrev_b64 v[4:5], 1, v[4:5]
	v_add_u32_e32 v6, 0x200, v6
	v_lshl_add_u64 v[2:3], v[2:3], 1, v[4:5]
	v_ashrrev_i32_e32 v4, 31, v6
	v_lshrrev_b32_e32 v4, 28, v4
	v_add_lshl_u32 v4, v6, v4, 3
	v_and_b32_e32 v4, 0xffffff80, v4
	v_lshlrev_b32_e32 v6, 3, v6
	v_sub_u32_e32 v6, v6, v4
	v_ashrrev_i32_e32 v7, 31, v6
	v_lshl_add_u64 v[2:3], s[6:7], 0, v[2:3]
	v_ashrrev_i32_e32 v5, 31, v4
	v_lshlrev_b64 v[6:7], 1, v[6:7]
	v_add_co_u32_e32 v2, vcc, 0x4000, v2
	v_lshl_add_u64 v[4:5], v[4:5], 1, v[6:7]
	s_nop 0
	v_addc_co_u32_e32 v3, vcc, 0, v3, vcc
	v_lshl_add_u64 v[4:5], s[6:7], 0, v[4:5]
	v_add_co_u32_e32 v4, vcc, 0x4000, v4
	s_nop 1
	v_addc_co_u32_e32 v5, vcc, 0, v5, vcc
	flat_load_dwordx4 v[6:9], v[2:3]
	flat_load_dwordx4 v[2:5], v[4:5]

.LBB0_1702:
	v_max_f32_e32 v50, v67, v67
	v_max_f32_e32 v51, v66, v66
	v_max_f32_e32 v50, v51, v50
	v_max3_f32 v50, v50, v68, v69
	v_max3_f32 v50, v50, v70, v71
	v_max3_f32 v50, v50, v72, v73
	v_max3_f32 v50, v50, v74, v75
	v_max3_f32 v50, v50, v14, v15
	v_max3_f32 v50, v50, v12, v13
	v_max3_f32 v50, v50, v10, v11
	v_max3_f32 v50, v50, v64, v65
	v_max3_f32 v50, v50, v112, v113
	v_max3_f32 v50, v50, v80, v81
	v_max3_f32 v50, v50, v78, v79
	v_max3_f32 v50, v50, v58, v59
	v_max3_f32 v50, v50, v60, v61
	v_max3_f32 v50, v50, v62, v63
	v_max3_f32 v50, v50, v76, v77
	v_mov_b32_e32 v51, v50
	s_nop 1
	v_permlane32_swap_b32_e32 v50, v51
	v_max_f32_e32 v51, v51, v51
	v_max_f32_e32 v50, v50, v50
	v_max_f32_e32 v50, v50, v51
	v_sub_f32_e32 v51, v50, v17
	v_cmp_ge_f32_e32 vcc, s83, v51
	s_cmp_eq_u64 vcc, exec
	s_cselect_b64 s[4:5], -1, 0
	s_andn2_b64 vcc, exec, s[14:15]
	s_waitcnt lgkmcnt(0)
	s_barrier
	s_cbranch_vccnz .LBB0_1695
	v_mov_b32_e32 v51, v116
	s_waitcnt vmcnt(0)
	v_ashrrev_i32_e32 v52, 31, v51
	v_lshrrev_b32_e32 v52, 28, v52
	v_add_u32_e32 v52, v51, v52
	v_lshlrev_b32_e32 v53, 4, v52
	v_and_b32_e32 v53, 0xffffff00, v53
	v_lshlrev_b32_e32 v54, 4, v51
	v_sub_u32_e32 v54, v54, v53
	v_bitop3_b32 v52, v54, v52, s73 bitop3:0x78
	v_add3_u32 v52, 0, v53, v52
	s_waitcnt vmcnt(0)
	ds_write_b128 v52, v[6:9] offset:49152
	v_add_u32_e32 v6, 0x200, v51
	v_ashrrev_i32_e32 v7, 31, v6
	v_lshrrev_b32_e32 v7, 28, v7
	v_add_u32_e32 v7, v6, v7
	v_lshlrev_b32_e32 v8, 4, v7
	v_and_b32_e32 v8, 0xffffff00, v8
	v_lshlrev_b32_e32 v6, 4, v6
	v_sub_u32_e32 v6, v6, v8
	v_bitop3_b32 v6, v6, v7, s73 bitop3:0x78
	v_add3_u32 v6, 0, v8, v6
	ds_write_b128 v6, v[2:5] offset:49152
	s_branch .LBB0_1695

.LBB0_1735:
	s_or_b64 exec, exec, s[10:11]
	v_cvt_pk_bf16_f32 v114, v143, v145
	v_cvt_pk_bf16_f32 v115, v141, v144
	v_cvt_pk_bf16_f32 v116, v139, v142
	v_cvt_pk_bf16_f32 v117, v138, v140
	v_cvt_pk_bf16_f32 v118, v135, v137
	v_cvt_pk_bf16_f32 v119, v133, v136
	v_cvt_pk_bf16_f32 v120, v131, v134
	v_cvt_pk_bf16_f32 v121, v130, v132
	v_cvt_pk_bf16_f32 v122, v2, v5
	v_cvt_pk_bf16_f32 v123, v3, v4
	v_cvt_pk_bf16_f32 v124, v7, v9
	v_cvt_pk_bf16_f32 v125, v6, v8
	v_cvt_pk_bf16_f32 v126, v11, v13
	v_cvt_pk_bf16_f32 v127, v10, v12
	v_cvt_pk_bf16_f32 v128, v15, v128
	v_cvt_pk_bf16_f32 v129, v14, v17
	v_permlane32_swap_b32_e32 v114, v116
	v_permlane32_swap_b32_e32 v115, v117
	v_permlane32_swap_b32_e32 v118, v120
	v_permlane32_swap_b32_e32 v119, v121
	v_permlane32_swap_b32_e32 v122, v124
	v_permlane32_swap_b32_e32 v123, v125
	v_permlane32_swap_b32_e32 v126, v128
	v_permlane32_swap_b32_e32 v127, v129
	v_mov_b32_e32 v12, v212
	s_mov_b32 s10, 0x80000
	v_ashrrev_i32_e32 v2, 31, v12
	v_lshrrev_b32_e32 v2, 28, v2
	v_add_lshl_u32 v2, v12, v2, 3
	v_and_b32_e32 v2, 0xffffff80, v2
	v_lshlrev_b32_e32 v10, 3, v12
	v_sub_u32_e32 v4, v10, v2
	v_ashrrev_i32_e32 v5, 31, v4
	v_ashrrev_i32_e32 v3, 31, v2
	v_lshlrev_b64 v[4:5], 1, v[4:5]
	v_add_u32_e32 v6, 0x200, v12
	v_lshl_add_u64 v[2:3], v[2:3], 1, v[4:5]
	v_ashrrev_i32_e32 v4, 31, v6
	v_and_b32_e32 v10, 0xffffff80, v10
	v_lshrrev_b32_e32 v4, 28, v4
	v_ashrrev_i32_e32 v11, 31, v10
	v_lshlrev_b32_e32 v12, 4, v12
	v_add_lshl_u32 v4, v6, v4, 3
	v_and_b32_e32 v14, 0xf0, v12
	v_lshlrev_b64 v[12:13], 1, v[10:11]
	v_add_u32_e32 v10, 0x1000, v10
	v_and_b32_e32 v4, 0xffffff80, v4
	v_lshlrev_b32_e32 v6, 3, v6
	v_or_b32_e32 v12, v12, v14
	v_ashrrev_i32_e32 v11, 31, v10
	v_sub_u32_e32 v6, v6, v4
	v_lshl_add_u64 v[12:13], s[8:9], 0, v[12:13]
	v_lshlrev_b64 v[10:11], 1, v[10:11]
	v_ashrrev_i32_e32 v7, 31, v6
	v_add_co_u32_e32 v12, vcc, s10, v12
	v_or_b32_e32 v10, v10, v14
	v_ashrrev_i32_e32 v5, 31, v4
	v_lshlrev_b64 v[6:7], 1, v[6:7]
	v_addc_co_u32_e32 v13, vcc, 0, v13, vcc
	v_lshl_add_u64 v[10:11], s[8:9], 0, v[10:11]
	v_lshl_add_u64 v[4:5], v[4:5], 1, v[6:7]
	v_add_co_u32_e32 v10, vcc, s10, v10
	v_lshl_add_u64 v[2:3], s[8:9], 0, v[2:3]
	v_lshl_add_u64 v[4:5], s[8:9], 0, v[4:5]
	v_addc_co_u32_e32 v11, vcc, 0, v11, vcc
	flat_load_dwordx4 v[6:9], v[2:3]
	flat_load_dwordx4 v[2:5], v[4:5]
	flat_load_dwordx4 v[170:173], v[12:13]
	flat_load_dwordx4 v[10:13], v[10:11]
	ds_read_b64_tr_b16 v[130:131], v209 offset:0
	ds_read_b64_tr_b16 v[132:133], v209 offset:0x800
	ds_read_b64_tr_b16 v[134:135], v209 offset:0x1000
	ds_read_b64_tr_b16 v[136:137], v209 offset:0x1800
	ds_read_b64_tr_b16 v[138:139], v209 offset:0x2000
	ds_read_b64_tr_b16 v[140:141], v209 offset:0x2800
	ds_read_b64_tr_b16 v[142:143], v209 offset:0x3000
	ds_read_b64_tr_b16 v[144:145], v209 offset:0x3800
	s_waitcnt lgkmcnt(0)
	v_mfma_f32_32x32x16_bf16 v[18:33], v[114:117], v[130:133], v[18:33]
	ds_read_b64_tr_b16 v[130:131], v209 offset:0x200
	ds_read_b64_tr_b16 v[132:133], v209 offset:0xa00
	v_mfma_f32_32x32x16_bf16 v[18:33], v[118:121], v[134:137], v[18:33]
	ds_read_b64_tr_b16 v[134:135], v209 offset:0x1200
	ds_read_b64_tr_b16 v[136:137], v209 offset:0x1a00
	v_mfma_f32_32x32x16_bf16 v[18:33], v[122:125], v[138:141], v[18:33]
	ds_read_b64_tr_b16 v[138:139], v209 offset:0x2200
	ds_read_b64_tr_b16 v[140:141], v209 offset:0x2a00
	v_mfma_f32_32x32x16_bf16 v[18:33], v[126:129], v[142:145], v[18:33]
	ds_read_b64_tr_b16 v[142:143], v209 offset:0x3200
	ds_read_b64_tr_b16 v[144:145], v209 offset:0x3a00
	s_waitcnt lgkmcnt(0)
	v_mfma_f32_32x32x16_bf16 v[34:49], v[114:117], v[130:133], v[34:49]
	ds_read_b64_tr_b16 v[130:131], v209 offset:0x400
	ds_read_b64_tr_b16 v[132:133], v209 offset:0xc00
	v_mfma_f32_32x32x16_bf16 v[34:49], v[118:121], v[134:137], v[34:49]
	ds_read_b64_tr_b16 v[134:135], v209 offset:0x1400
	ds_read_b64_tr_b16 v[136:137], v209 offset:0x1c00
	v_mfma_f32_32x32x16_bf16 v[34:49], v[122:125], v[138:141], v[34:49]
	ds_read_b64_tr_b16 v[138:139], v209 offset:0x2400
	ds_read_b64_tr_b16 v[140:141], v209 offset:0x2c00
	v_mfma_f32_32x32x16_bf16 v[34:49], v[126:129], v[142:145], v[34:49]
	ds_read_b64_tr_b16 v[142:143], v209 offset:0x3400
	ds_read_b64_tr_b16 v[144:145], v209 offset:0x3c00
	s_waitcnt lgkmcnt(0)
	v_mfma_f32_32x32x16_bf16 v[50:65], v[114:117], v[130:133], v[50:65]
	ds_read_b64_tr_b16 v[130:131], v209 offset:0x600
	ds_read_b64_tr_b16 v[132:133], v209 offset:0xe00
	v_mfma_f32_32x32x16_bf16 v[50:65], v[118:121], v[134:137], v[50:65]
	ds_read_b64_tr_b16 v[134:135], v209 offset:0x1600
	ds_read_b64_tr_b16 v[136:137], v209 offset:0x1e00
	v_mfma_f32_32x32x16_bf16 v[50:65], v[122:125], v[138:141], v[50:65]
	ds_read_b64_tr_b16 v[138:139], v209 offset:0x2600
	ds_read_b64_tr_b16 v[140:141], v209 offset:0x2e00
	v_mfma_f32_32x32x16_bf16 v[50:65], v[126:129], v[142:145], v[50:65]
	ds_read_b64_tr_b16 v[142:143], v209 offset:0x3600
	ds_read_b64_tr_b16 v[144:145], v209 offset:0x3e00
	s_waitcnt lgkmcnt(0)
	v_mfma_f32_32x32x16_bf16 v[66:81], v[114:117], v[130:133], v[66:81]
	v_add_u32_e32 v17, 0x7b, v0
	v_cvt_f32_i32_e32 v14, v17
	s_mov_b32 s10, 2.0
	s_mov_b32 s11, 0x40400000
	v_mov_b32_e32 v195, v194
	v_mul_f32_e64 v114, -v194, v14
	v_fma_f32 v117, -v194, v14, v194
	v_mfma_f32_32x32x16_bf16 v[66:81], v[118:121], v[134:137], v[66:81]
	v_fma_f32 v118, v204, s10, v114
	v_fma_f32 v119, v205, s11, v114
	s_mov_b32 s10, 0x41000000
	s_mov_b32 s11, 0x41100000
	v_fma_f32 v120, v204, s10, v114
	v_fma_f32 v121, v205, s11, v114
	s_mov_b32 s10, 0x41200000
	s_mov_b32 s11, 0x41300000
	v_mov_b32_e32 v116, v114
	v_mfma_f32_32x32x16_bf16 v[66:81], v[122:125], v[138:141], v[66:81]
	v_fma_f32 v122, v204, s10, v114
	v_fma_f32 v123, v205, s11, v114
	s_mov_b32 s10, 0x41800000
	s_mov_b32 s11, 0x41880000
	v_fma_f32 v124, v204, s10, v114
	v_fma_f32 v125, v205, s11, v114
	s_mov_b32 s10, 0x41900000
	s_mov_b32 s11, 0x41980000
	v_fmac_f32_e32 v116, 0, v194
	v_mfma_f32_32x32x16_bf16 v[66:81], v[126:129], v[142:145], v[66:81]
	v_fma_f32 v126, v204, s10, v114
	v_fma_f32 v127, v205, s11, v114
	s_mov_b32 s10, 0x41c00000
	s_mov_b32 s11, 0x41c80000
	v_fma_f32 v128, v204, s10, v114
	v_fma_f32 v129, v205, s11, v114
	s_mov_b32 s10, 0x41d00000
	s_mov_b32 s11, 0x41d80000
	v_pk_fma_f32 v[14:15], v[204:205], s[10:11], v[114:115] op_sel_hi:[1,1,0]
	s_mov_b32 s10, 0x42080000
	s_mov_b32 s11, 0x420c0000
	v_pk_add_f32 v[98:99], v[116:117], v[98:99]
	v_pk_fma_f32 v[116:117], v[194:195], s[10:11], v[114:115] op_sel_hi:[1,1,0]
	s_mov_b32 s10, 0x42200000
	s_mov_b32 s11, 0x42240000
	v_pk_add_f32 v[100:101], v[118:119], v[100:101]
	v_pk_fma_f32 v[118:119], v[194:195], s[10:11], v[114:115] op_sel_hi:[1,1,0]
	s_mov_b32 s10, 0x42280000
	s_mov_b32 s11, 0x422c0000
	v_pk_add_f32 v[102:103], v[120:121], v[102:103]
	v_pk_fma_f32 v[120:121], v[194:195], s[10:11], v[114:115] op_sel_hi:[1,1,0]
	s_mov_b32 s10, 0x42400000
	s_mov_b32 s11, 0x42440000
	v_pk_add_f32 v[104:105], v[122:123], v[104:105]
	v_pk_fma_f32 v[122:123], v[194:195], s[10:11], v[114:115] op_sel_hi:[1,1,0]
	s_mov_b32 s10, 0x42480000
	s_mov_b32 s11, 0x424c0000
	v_pk_add_f32 v[106:107], v[124:125], v[106:107]
	v_pk_fma_f32 v[124:125], v[194:195], s[10:11], v[114:115] op_sel_hi:[1,1,0]
	s_mov_b32 s10, 0x42600000
	s_mov_b32 s11, 0x42640000
	v_pk_add_f32 v[108:109], v[126:127], v[108:109]
	v_pk_fma_f32 v[126:127], v[194:195], s[10:11], v[114:115] op_sel_hi:[1,1,0]
	s_mov_b32 s10, 0x42000000
	s_mov_b32 s11, 0x42040000
	v_pk_add_f32 v[14:15], v[14:15], v[112:113]
	v_pk_fma_f32 v[112:113], v[194:195], s[94:95], v[114:115] op_sel_hi:[1,1,0]
	v_pk_fma_f32 v[114:115], v[196:197], s[10:11], v[114:115] op_sel_hi:[1,1,0]
	s_sub_i32 s10, s12, 64
	v_pk_add_f32 v[110:111], v[128:129], v[110:111]
	v_pk_add_f32 v[112:113], v[112:113], v[96:97]
	v_pk_add_f32 v[174:175], v[126:127], v[94:95]
	v_pk_add_f32 v[94:95], v[124:125], v[92:93]
	v_pk_add_f32 v[96:97], v[122:123], v[90:91]
	v_pk_add_f32 v[90:91], v[120:121], v[88:89]
	v_pk_add_f32 v[92:93], v[118:119], v[86:87]
	v_pk_add_f32 v[86:87], v[116:117], v[84:85]
	v_pk_add_f32 v[88:89], v[114:115], v[82:83]
	s_cmp_le_i32 s10, s15
	s_cbranch_scc1 .LBB0_1737
	v_cmp_gt_u32_e32 vcc, 2.0, v17
	v_add_u32_e32 v17, 0x5b, v0
	s_nop 0
	v_cndmask_b32_e32 v98, v16, v98, vcc
	v_cmp_gt_u32_e32 vcc, 2.0, v17
	v_add_u32_e32 v17, 0x7a, v0
	s_nop 0
	v_cndmask_b32_e32 v88, v16, v88, vcc
	v_cmp_gt_u32_e32 vcc, 2.0, v17
	v_add_u32_e32 v17, 0x5a, v0
	s_nop 0
	v_cndmask_b32_e32 v99, v16, v99, vcc
	v_cmp_gt_u32_e32 vcc, 2.0, v17
	v_add_u32_e32 v17, 0x79, v0
	s_nop 0
	v_cndmask_b32_e32 v89, v16, v89, vcc
	v_cmp_gt_u32_e32 vcc, 2.0, v17
	v_add_u32_e32 v17, 0x59, v0
	s_nop 0
	v_cndmask_b32_e32 v100, v16, v100, vcc
	v_cmp_gt_u32_e32 vcc, 2.0, v17
	v_add_u32_e32 v17, 0x78, v0
	s_nop 0
	v_cndmask_b32_e32 v86, v16, v86, vcc
	v_cmp_gt_u32_e32 vcc, 2.0, v17
	v_add_u32_e32 v17, 0x58, v0
	s_nop 0
	v_cndmask_b32_e32 v101, v16, v101, vcc
	v_cmp_gt_u32_e32 vcc, 2.0, v17
	v_add_u32_e32 v17, 0x73, v0
	s_nop 0
	v_cndmask_b32_e32 v87, v16, v87, vcc
	v_cmp_gt_u32_e32 vcc, 2.0, v17
	v_add_u32_e32 v17, 0x53, v0
	s_nop 0
	v_cndmask_b32_e32 v102, v16, v102, vcc
	v_cmp_gt_u32_e32 vcc, 2.0, v17
	v_add_u32_e32 v17, 0x72, v0
	s_nop 0
	v_cndmask_b32_e32 v92, v16, v92, vcc
	v_cmp_gt_u32_e32 vcc, 2.0, v17
	v_add_u32_e32 v17, 0x52, v0
	s_nop 0
	v_cndmask_b32_e32 v103, v16, v103, vcc
	v_cmp_gt_u32_e32 vcc, 2.0, v17
	v_add_u32_e32 v17, 0x71, v0
	s_nop 0
	v_cndmask_b32_e32 v93, v16, v93, vcc
	v_cmp_gt_u32_e32 vcc, 2.0, v17
	v_add_u32_e32 v17, 0x51, v0
	s_nop 0
	v_cndmask_b32_e32 v104, v16, v104, vcc
	v_cmp_gt_u32_e32 vcc, 2.0, v17
	v_add_u32_e32 v17, 0x70, v0
	s_nop 0
	v_cndmask_b32_e32 v90, v16, v90, vcc
	v_cmp_gt_u32_e32 vcc, 2.0, v17
	v_add_u32_e32 v17, 0x50, v0
	s_nop 0
	v_cndmask_b32_e32 v105, v16, v105, vcc
	v_cmp_gt_u32_e32 vcc, 2.0, v17
	v_add_u32_e32 v17, 0x6b, v0
	s_nop 0
	v_cndmask_b32_e32 v91, v16, v91, vcc
	v_cmp_gt_u32_e32 vcc, 2.0, v17
	v_add_u32_e32 v17, 0x4b, v0
	s_nop 0
	v_cndmask_b32_e32 v106, v16, v106, vcc
	v_cmp_gt_u32_e32 vcc, 2.0, v17
	v_add_u32_e32 v17, 0x6a, v0
	s_nop 0
	v_cndmask_b32_e32 v96, v16, v96, vcc
	v_cmp_gt_u32_e32 vcc, 2.0, v17
	v_add_u32_e32 v17, 0x4a, v0
	s_nop 0
	v_cndmask_b32_e32 v107, v16, v107, vcc
	v_cmp_gt_u32_e32 vcc, 2.0, v17
	v_add_u32_e32 v17, 0x69, v0
	s_nop 0
	v_cndmask_b32_e32 v97, v16, v97, vcc
	v_cmp_gt_u32_e32 vcc, 2.0, v17
	v_add_u32_e32 v17, 0x49, v0
	s_nop 0
	v_cndmask_b32_e32 v108, v16, v108, vcc
	v_cmp_gt_u32_e32 vcc, 2.0, v17
	v_add_u32_e32 v17, 0x68, v0
	s_nop 0
	v_cndmask_b32_e32 v94, v16, v94, vcc
	v_cmp_gt_u32_e32 vcc, 2.0, v17
	v_add_u32_e32 v17, 0x48, v0
	s_nop 0
	v_cndmask_b32_e32 v109, v16, v109, vcc
	v_cmp_gt_u32_e32 vcc, 2.0, v17
	v_add_u32_e32 v17, 0x63, v0
	s_nop 0
	v_cndmask_b32_e32 v95, v16, v95, vcc
	v_cmp_gt_u32_e32 vcc, 2.0, v17
	v_add_u32_e32 v17, 0x43, v0
	s_nop 0
	v_cndmask_b32_e32 v110, v16, v110, vcc
	v_cmp_gt_u32_e32 vcc, 2.0, v17
	v_add_u32_e32 v17, 0x62, v0
	s_nop 0
	v_cndmask_b32_e32 v174, v16, v174, vcc
	v_cmp_gt_u32_e32 vcc, 2.0, v17
	v_add_u32_e32 v17, 0x42, v0
	s_nop 0
	v_cndmask_b32_e32 v111, v16, v111, vcc
	v_cmp_gt_u32_e32 vcc, 2.0, v17
	v_add_u32_e32 v17, 0x61, v0
	s_nop 0
	v_cndmask_b32_e32 v175, v16, v175, vcc
	v_cmp_gt_u32_e32 vcc, 2.0, v17
	v_add_u32_e32 v17, 0x41, v0
	s_nop 0
	v_cndmask_b32_e32 v14, v16, v14, vcc
	v_cmp_gt_u32_e32 vcc, 2.0, v17
	v_add_u32_e32 v17, 0x60, v0
	s_nop 0
	v_cndmask_b32_e32 v112, v16, v112, vcc
	v_cmp_gt_u32_e32 vcc, 2.0, v17
	v_add_u32_e32 v17, 64, v0
	s_nop 0
	v_cndmask_b32_e32 v15, v16, v15, vcc
	v_cmp_gt_u32_e32 vcc, 2.0, v17
	s_nop 1
	v_cndmask_b32_e32 v113, v16, v113, vcc

.LBB0_1753:
	s_or_b64 exec, exec, s[10:11]
	v_cvt_pk_bf16_f32 v174, v82, v83
	v_cvt_pk_bf16_f32 v175, v84, v85
	v_cvt_pk_bf16_f32 v176, v86, v87
	v_cvt_pk_bf16_f32 v177, v88, v89
	v_cvt_pk_bf16_f32 v178, v90, v91
	v_cvt_pk_bf16_f32 v179, v92, v93
	v_cvt_pk_bf16_f32 v180, v94, v95
	v_cvt_pk_bf16_f32 v181, v96, v97
	v_cvt_pk_bf16_f32 v182, v98, v99
	v_cvt_pk_bf16_f32 v183, v100, v101
	v_cvt_pk_bf16_f32 v184, v102, v103
	v_cvt_pk_bf16_f32 v185, v104, v105
	v_cvt_pk_bf16_f32 v186, v106, v107
	v_cvt_pk_bf16_f32 v187, v108, v109
	v_cvt_pk_bf16_f32 v188, v110, v111
	v_cvt_pk_bf16_f32 v189, v112, v113
	v_permlane32_swap_b32_e32 v174, v176
	v_permlane32_swap_b32_e32 v175, v177
	v_permlane32_swap_b32_e32 v178, v180
	v_permlane32_swap_b32_e32 v179, v181
	v_permlane32_swap_b32_e32 v182, v184
	v_permlane32_swap_b32_e32 v183, v185
	v_permlane32_swap_b32_e32 v186, v188
	v_permlane32_swap_b32_e32 v187, v189
	s_cmp_le_u32 s13, s16
	s_cselect_b64 s[10:11], -1, 0
	s_cmp_gt_u32 s13, s16
	s_cbranch_scc1 .LBB0_1755
	v_mov_b32_e32 v12, v212
	s_movk_i32 s19, 0x4000
	v_ashrrev_i32_e32 v2, 31, v12
	v_lshrrev_b32_e32 v2, 28, v2
	v_add_lshl_u32 v2, v12, v2, 3
	v_and_b32_e32 v2, 0xffffff80, v2
	v_lshlrev_b32_e32 v10, 3, v12
	v_sub_u32_e32 v4, v10, v2
	v_ashrrev_i32_e32 v5, 31, v4
	v_ashrrev_i32_e32 v3, 31, v2
	v_lshlrev_b64 v[4:5], 1, v[4:5]
	v_add_u32_e32 v6, 0x200, v12
	v_lshl_add_u64 v[2:3], v[2:3], 1, v[4:5]
	v_ashrrev_i32_e32 v4, 31, v6
	v_lshrrev_b32_e32 v4, 28, v4
	v_add_lshl_u32 v4, v6, v4, 3
	v_and_b32_e32 v4, 0xffffff80, v4
	v_lshlrev_b32_e32 v6, 3, v6
	v_sub_u32_e32 v6, v6, v4
	v_ashrrev_i32_e32 v7, 31, v6
	v_lshl_add_u64 v[2:3], s[8:9], 0, v[2:3]
	v_ashrrev_i32_e32 v5, 31, v4
	v_lshlrev_b64 v[6:7], 1, v[6:7]
	v_and_b32_e32 v10, 0xffffff80, v10
	v_add_co_u32_e32 v2, vcc, 0x4000, v2
	v_lshl_add_u64 v[4:5], v[4:5], 1, v[6:7]
	v_ashrrev_i32_e32 v11, 31, v10
	v_lshlrev_b32_e32 v12, 4, v12
	v_addc_co_u32_e32 v3, vcc, 0, v3, vcc
	v_lshl_add_u64 v[4:5], s[8:9], 0, v[4:5]
	v_and_b32_e32 v14, 0xf0, v12
	v_lshlrev_b64 v[12:13], 1, v[10:11]
	v_add_u32_e32 v10, 0x1000, v10
	v_add_co_u32_e32 v4, vcc, s19, v4
	v_or_b32_e32 v12, v12, v14
	v_ashrrev_i32_e32 v11, 31, v10
	v_addc_co_u32_e32 v5, vcc, 0, v5, vcc
	v_lshl_add_u64 v[12:13], s[8:9], 0, v[12:13]
	s_mov_b32 s19, 0x84000
	v_lshlrev_b64 v[10:11], 1, v[10:11]
	v_add_co_u32_e32 v12, vcc, s19, v12
	v_or_b32_e32 v10, v10, v14
	s_nop 0
	v_addc_co_u32_e32 v13, vcc, 0, v13, vcc
	v_lshl_add_u64 v[10:11], s[8:9], 0, v[10:11]
	v_add_co_u32_e32 v10, vcc, 0x84000, v10
	flat_load_dwordx4 v[6:9], v[2:3]
	flat_load_dwordx4 v[2:5], v[4:5]
	v_addc_co_u32_e32 v11, vcc, 0, v11, vcc
	flat_load_dwordx4 v[170:173], v[12:13]
	flat_load_dwordx4 v[10:13], v[10:11]
.LBB0_1755:
	ds_read_b64_tr_b16 v[220:221], v209 offset:0x4000
	ds_read_b64_tr_b16 v[222:223], v209 offset:0x4800
	ds_read_b64_tr_b16 v[224:225], v209 offset:0x5000
	ds_read_b64_tr_b16 v[226:227], v209 offset:0x5800
	ds_read_b64_tr_b16 v[234:235], v209 offset:0x6000
	ds_read_b64_tr_b16 v[236:237], v209 offset:0x6800
	ds_read_b64_tr_b16 v[238:239], v209 offset:0x7000
	ds_read_b64_tr_b16 v[240:241], v209 offset:0x7800
	s_waitcnt lgkmcnt(0)
	v_mfma_f32_32x32x16_bf16 v[18:33], v[174:177], v[220:223], v[18:33]
	ds_read_b64_tr_b16 v[220:221], v209 offset:0x4200
	ds_read_b64_tr_b16 v[222:223], v209 offset:0x4a00
	v_mfma_f32_32x32x16_bf16 v[18:33], v[178:181], v[224:227], v[18:33]
	ds_read_b64_tr_b16 v[224:225], v209 offset:0x5200
	ds_read_b64_tr_b16 v[226:227], v209 offset:0x5a00
	v_mfma_f32_32x32x16_bf16 v[18:33], v[182:185], v[234:237], v[18:33]
	ds_read_b64_tr_b16 v[234:235], v209 offset:0x6200
	ds_read_b64_tr_b16 v[236:237], v209 offset:0x6a00
	v_mfma_f32_32x32x16_bf16 v[18:33], v[186:189], v[238:241], v[18:33]
	ds_read_b64_tr_b16 v[238:239], v209 offset:0x7200
	ds_read_b64_tr_b16 v[240:241], v209 offset:0x7a00
	s_waitcnt lgkmcnt(0)
	v_mfma_f32_32x32x16_bf16 v[34:49], v[174:177], v[220:223], v[34:49]
	ds_read_b64_tr_b16 v[220:221], v209 offset:0x4400
	ds_read_b64_tr_b16 v[222:223], v209 offset:0x4c00
	v_mfma_f32_32x32x16_bf16 v[34:49], v[178:181], v[224:227], v[34:49]
	ds_read_b64_tr_b16 v[224:225], v209 offset:0x5400
	ds_read_b64_tr_b16 v[226:227], v209 offset:0x5c00
	v_mfma_f32_32x32x16_bf16 v[34:49], v[182:185], v[234:237], v[34:49]
	ds_read_b64_tr_b16 v[234:235], v209 offset:0x6400
	ds_read_b64_tr_b16 v[236:237], v209 offset:0x6c00
	v_mfma_f32_32x32x16_bf16 v[34:49], v[186:189], v[238:241], v[34:49]
	ds_read_b64_tr_b16 v[238:239], v209 offset:0x7400
	ds_read_b64_tr_b16 v[240:241], v209 offset:0x7c00
	s_waitcnt lgkmcnt(0)
	v_mfma_f32_32x32x16_bf16 v[50:65], v[174:177], v[220:223], v[50:65]
	ds_read_b64_tr_b16 v[220:221], v209 offset:0x4600
	ds_read_b64_tr_b16 v[222:223], v209 offset:0x4e00
	v_mfma_f32_32x32x16_bf16 v[50:65], v[178:181], v[224:227], v[50:65]
	ds_read_b64_tr_b16 v[224:225], v209 offset:0x5600
	ds_read_b64_tr_b16 v[226:227], v209 offset:0x5e00
	v_mfma_f32_32x32x16_bf16 v[50:65], v[182:185], v[234:237], v[50:65]
	ds_read_b64_tr_b16 v[234:235], v209 offset:0x6600
	ds_read_b64_tr_b16 v[236:237], v209 offset:0x6e00
	v_mfma_f32_32x32x16_bf16 v[50:65], v[186:189], v[238:241], v[50:65]
	ds_read_b64_tr_b16 v[238:239], v209 offset:0x7600
	ds_read_b64_tr_b16 v[240:241], v209 offset:0x7e00
	s_waitcnt lgkmcnt(0)
	v_mfma_f32_32x32x16_bf16 v[66:81], v[174:177], v[220:223], v[66:81]
	v_add_u32_e32 v17, 59, v0
	v_cvt_f32_i32_e32 v15, v17
	s_mov_b32 s20, 2.0
	s_mov_b32 s21, 0x40400000
	v_mov_b32_e32 v195, v194
	v_mul_f32_e64 v14, -v194, v15
	v_pk_fma_f32 v[176:177], v[204:205], s[20:21], v[14:15] op_sel_hi:[1,1,0]
	v_mfma_f32_32x32x16_bf16 v[66:81], v[178:181], v[224:227], v[66:81]
	s_mov_b32 s20, 0x41000000
	s_mov_b32 s21, 0x41100000
	v_fma_f32 v178, v204, s20, v14
	v_fma_f32 v179, v205, s21, v14
	s_mov_b32 s20, 0x41200000
	s_mov_b32 s21, 0x41300000
	v_pk_fma_f32 v[180:181], v[204:205], s[20:21], v[14:15] op_sel_hi:[1,1,0]
	s_mov_b32 s20, 0x41800000
	v_mfma_f32_32x32x16_bf16 v[66:81], v[182:185], v[234:237], v[66:81]
	s_mov_b32 s21, 0x41880000
	v_fma_f32 v182, v204, s20, v14
	v_fma_f32 v183, v205, s21, v14
	s_mov_b32 s20, 0x41900000
	s_mov_b32 s21, 0x41980000
	v_pk_fma_f32 v[184:185], v[204:205], s[20:21], v[14:15] op_sel_hi:[1,1,0]
	s_mov_b32 s20, 0x41c00000
	s_mov_b32 s21, 0x41c80000
	v_mfma_f32_32x32x16_bf16 v[66:81], v[186:189], v[238:241], v[66:81]
	v_fma_f32 v186, v204, s20, v14
	v_fma_f32 v187, v205, s21, v14
	s_mov_b32 s20, 0x41d00000
	s_mov_b32 s21, 0x41d80000
	v_fma_f32 v188, v204, s20, v14
	v_fma_f32 v189, v205, s21, v14
	s_mov_b32 s20, 0x42080000
	s_mov_b32 s21, 0x420c0000
	v_pk_add_f32 v[134:135], v[178:179], v[134:135]
	v_pk_fma_f32 v[178:179], v[194:195], s[20:21], v[14:15] op_sel_hi:[1,1,0]
	s_mov_b32 s20, 0x42200000
	s_mov_b32 s21, 0x42240000
	v_mov_b32_e32 v174, v14
	v_pk_add_f32 v[132:133], v[176:177], v[132:133]
	v_pk_fma_f32 v[176:177], v[194:195], s[20:21], v[14:15] op_sel_hi:[1,1,0]
	s_mov_b32 s20, 0x42280000
	v_fma_f32 v175, -v194, v15, v194
	v_fmac_f32_e32 v174, 0, v194
	s_mov_b32 s21, 0x422c0000
	v_pk_add_f32 v[130:131], v[174:175], v[130:131]
	v_pk_fma_f32 v[174:175], v[194:195], s[20:21], v[14:15] op_sel_hi:[1,1,0]
	s_mov_b32 s20, 0x42400000
	s_mov_b32 s21, 0x42440000
	v_pk_add_f32 v[136:137], v[180:181], v[136:137]
	v_pk_fma_f32 v[180:181], v[194:195], s[20:21], v[14:15] op_sel_hi:[1,1,0]
	s_mov_b32 s20, 0x42480000
	s_mov_b32 s21, 0x424c0000
	v_pk_add_f32 v[138:139], v[182:183], v[138:139]
	v_pk_fma_f32 v[182:183], v[194:195], s[20:21], v[14:15] op_sel_hi:[1,1,0]
	s_mov_b32 s20, 0x42600000
	s_mov_b32 s21, 0x42640000
	v_pk_add_f32 v[140:141], v[184:185], v[140:141]
	v_pk_fma_f32 v[184:185], v[194:195], s[20:21], v[14:15] op_sel_hi:[1,1,0]
	s_mov_b32 s20, 0x42000000
	s_mov_b32 s21, 0x42040000
	v_pk_add_f32 v[142:143], v[186:187], v[142:143]
	v_pk_fma_f32 v[186:187], v[194:195], s[94:95], v[14:15] op_sel_hi:[1,1,0]
	v_pk_fma_f32 v[14:15], v[196:197], s[20:21], v[14:15] op_sel_hi:[1,1,0]
	v_pk_add_f32 v[144:145], v[188:189], v[144:145]
	v_pk_add_f32 v[128:129], v[186:187], v[128:129]
	v_pk_add_f32 v[126:127], v[184:185], v[126:127]
	v_pk_add_f32 v[124:125], v[182:183], v[124:125]
	v_pk_add_f32 v[122:123], v[180:181], v[122:123]
	v_pk_add_f32 v[174:175], v[174:175], v[120:121]
	v_pk_add_f32 v[176:177], v[176:177], v[118:119]
	v_pk_add_f32 v[178:179], v[178:179], v[116:117]
	v_pk_add_f32 v[14:15], v[14:15], v[114:115]
	s_cmp_le_i32 s12, s15
	s_cbranch_scc1 .LBB0_1757
	v_cmp_gt_u32_e32 vcc, 2.0, v17
	v_add_u32_e32 v17, 27, v0
	s_nop 0
	v_cndmask_b32_e32 v130, v16, v130, vcc
	v_cmp_gt_u32_e32 vcc, 2.0, v17
	v_add_u32_e32 v17, 58, v0
	s_nop 0
	v_cndmask_b32_e32 v14, v16, v14, vcc
	v_cmp_gt_u32_e32 vcc, 2.0, v17
	v_add_u32_e32 v17, 26, v0
	s_nop 0
	v_cndmask_b32_e32 v131, v16, v131, vcc
	v_cmp_gt_u32_e32 vcc, 2.0, v17
	v_add_u32_e32 v17, 57, v0
	s_nop 0
	v_cndmask_b32_e32 v15, v16, v15, vcc
	v_cmp_gt_u32_e32 vcc, 2.0, v17
	v_add_u32_e32 v17, 25, v0
	s_nop 0
	v_cndmask_b32_e32 v132, v16, v132, vcc
	v_cmp_gt_u32_e32 vcc, 2.0, v17
	v_add_u32_e32 v17, 56, v0
	s_nop 0
	v_cndmask_b32_e32 v178, v16, v178, vcc
	v_cmp_gt_u32_e32 vcc, 2.0, v17
	v_add_u32_e32 v17, 24, v0
	s_nop 0
	v_cndmask_b32_e32 v133, v16, v133, vcc
	v_cmp_gt_u32_e32 vcc, 2.0, v17
	v_add_u32_e32 v17, 51, v0
	s_nop 0
	v_cndmask_b32_e32 v179, v16, v179, vcc
	v_cmp_gt_u32_e32 vcc, 2.0, v17
	v_add_u32_e32 v17, 19, v0
	s_nop 0
	v_cndmask_b32_e32 v134, v16, v134, vcc
	v_cmp_gt_u32_e32 vcc, 2.0, v17
	v_add_u32_e32 v17, 50, v0
	s_nop 0
	v_cndmask_b32_e32 v176, v16, v176, vcc
	v_cmp_gt_u32_e32 vcc, 2.0, v17
	v_add_u32_e32 v17, 18, v0
	s_nop 0
	v_cndmask_b32_e32 v135, v16, v135, vcc
	v_cmp_gt_u32_e32 vcc, 2.0, v17
	v_add_u32_e32 v17, 49, v0
	s_nop 0
	v_cndmask_b32_e32 v177, v16, v177, vcc
	v_cmp_gt_u32_e32 vcc, 2.0, v17
	v_add_u32_e32 v17, 17, v0
	s_nop 0
	v_cndmask_b32_e32 v136, v16, v136, vcc
	v_cmp_gt_u32_e32 vcc, 2.0, v17
	v_add_u32_e32 v17, 48, v0
	s_nop 0
	v_cndmask_b32_e32 v174, v16, v174, vcc
	v_cmp_gt_u32_e32 vcc, 2.0, v17
	v_add_u32_e32 v17, 16, v0
	s_nop 0
	v_cndmask_b32_e32 v137, v16, v137, vcc
	v_cmp_gt_u32_e32 vcc, 2.0, v17
	v_add_u32_e32 v17, 43, v0
	s_nop 0
	v_cndmask_b32_e32 v175, v16, v175, vcc
	v_cmp_gt_u32_e32 vcc, 2.0, v17
	v_add_u32_e32 v17, 11, v0
	s_nop 0
	v_cndmask_b32_e32 v138, v16, v138, vcc
	v_cmp_gt_u32_e32 vcc, 2.0, v17
	v_add_u32_e32 v17, 42, v0
	s_nop 0
	v_cndmask_b32_e32 v122, v16, v122, vcc
	v_cmp_gt_u32_e32 vcc, 2.0, v17
	v_add_u32_e32 v17, 10, v0
	s_nop 0
	v_cndmask_b32_e32 v139, v16, v139, vcc
	v_cmp_gt_u32_e32 vcc, 2.0, v17
	v_add_u32_e32 v17, 41, v0
	s_nop 0
	v_cndmask_b32_e32 v123, v16, v123, vcc
	v_cmp_gt_u32_e32 vcc, 2.0, v17
	v_add_u32_e32 v17, 9, v0
	s_nop 0
	v_cndmask_b32_e32 v140, v16, v140, vcc
	v_cmp_gt_u32_e32 vcc, 2.0, v17
	v_add_u32_e32 v17, 40, v0
	s_nop 0
	v_cndmask_b32_e32 v124, v16, v124, vcc
	v_cmp_gt_u32_e32 vcc, 2.0, v17
	v_add_u32_e32 v17, 8, v0
	s_nop 0
	v_cndmask_b32_e32 v141, v16, v141, vcc
	v_cmp_gt_u32_e32 vcc, 2.0, v17
	v_add_u32_e32 v17, 35, v0
	s_nop 0
	v_cndmask_b32_e32 v125, v16, v125, vcc
	v_cmp_gt_u32_e32 vcc, 2.0, v17
	v_add_u32_e32 v17, 3, v0
	s_nop 0
	v_cndmask_b32_e32 v142, v16, v142, vcc
	v_cmp_gt_u32_e32 vcc, 2.0, v17
	v_add_u32_e32 v17, 34, v0
	s_nop 0
	v_cndmask_b32_e32 v126, v16, v126, vcc
	v_cmp_gt_u32_e32 vcc, 2.0, v17
	v_add_u32_e32 v17, 2, v0
	s_nop 0
	v_cndmask_b32_e32 v143, v16, v143, vcc
	v_cmp_gt_u32_e32 vcc, 2.0, v17
	v_add_u32_e32 v17, 33, v0
	s_nop 0
	v_cndmask_b32_e32 v127, v16, v127, vcc
	v_cmp_gt_u32_e32 vcc, 2.0, v17
	v_add_u32_e32 v17, 1, v0
	s_nop 0
	v_cndmask_b32_e32 v144, v16, v144, vcc
	v_cmp_gt_u32_e32 vcc, 2.0, v17
	v_add_u32_e32 v17, 32, v0
	s_nop 0
	v_cndmask_b32_e32 v128, v16, v128, vcc
	v_cmp_gt_u32_e32 vcc, 2.0, v17
	s_nop 1
	v_cndmask_b32_e32 v145, v16, v145, vcc
	v_cmp_gt_u32_e32 vcc, 2.0, v0
	s_nop 1
	v_cndmask_b32_e32 v129, v16, v129, vcc
.LBB0_1757:
	s_andn2_b64 vcc, exec, s[10:11]
	s_waitcnt lgkmcnt(0)
	s_barrier
	s_cbranch_vccnz .LBB0_1759
	v_mov_b32_e32 v17, v212
	s_waitcnt vmcnt(0)
	v_ashrrev_i32_e32 v114, 31, v17
	v_lshrrev_b32_e32 v114, 28, v114
	v_add_u32_e32 v114, v17, v114
	v_lshlrev_b32_e32 v115, 4, v114
	v_and_b32_e32 v115, 0xffffff00, v115
	v_lshlrev_b32_e32 v116, 4, v17
	v_sub_u32_e32 v117, v116, v115
	v_bitop3_b32 v114, v117, v114, s73 bitop3:0x78
	v_add3_u32 v114, 0, v115, v114
	s_waitcnt vmcnt(0)
	ds_write_b128 v114, v[6:9] offset:49152
	v_add_u32_e32 v6, 0x200, v17
	v_ashrrev_i32_e32 v7, 31, v6
	v_lshrrev_b32_e32 v7, 28, v7
	v_add_u32_e32 v7, v6, v7
	v_lshlrev_b32_e32 v8, 4, v7
	v_and_b32_e32 v8, 0xffffff00, v8
	v_lshlrev_b32_e32 v6, 4, v6
	v_sub_u32_e32 v6, v6, v8
	v_bitop3_b32 v6, v6, v7, s73 bitop3:0x78
	v_add3_u32 v6, 0, v8, v6
	ds_write_b128 v6, v[2:5] offset:49152
	v_ashrrev_i32_e32 v2, 4, v17
	v_and_b32_e32 v3, 0xfffff0, v2
	v_lshlrev_b32_e32 v4, 1, v2
	v_and_or_b32 v3, v4, 8, v3
	v_lshrrev_b32_e32 v4, 1, v2
	v_lshrrev_b32_e32 v3, 1, v3
	v_bfe_u32 v5, v17, 2, 2
	v_and_b32_e32 v6, 3, v2
	v_or_b32_e32 v3, v3, v5
	v_and_or_b32 v4, v4, 4, v6
	v_lshlrev_b32_e32 v3, 9, v3
	v_and_b32_e32 v6, 48, v116
	v_lshl_add_u32 v4, v4, 6, 0
	v_add3_u32 v3, v4, v3, v6
	v_add_u32_e32 v2, 32, v2
	ds_write_b128 v3, v[170:173] offset:16384
	v_and_b32_e32 v3, 0xfffff0, v2
	v_lshlrev_b32_e32 v2, 1, v2
	v_and_or_b32 v2, v2, 8, v3
	v_lshrrev_b32_e32 v2, 1, v2
	v_or_b32_e32 v2, v2, v5
	v_lshlrev_b32_e32 v2, 9, v2
	v_add3_u32 v2, v4, v2, v6
	ds_write_b128 v2, v[10:13] offset:16384

.LBB0_1921:
	v_add_f32_e32 v20, 0, v157
	v_add_f32_e32 v20, v159, v20
	v_add_f32_e32 v20, v155, v20
	v_add_f32_e32 v20, v158, v20
	v_add_f32_e32 v20, v153, v20
	v_add_f32_e32 v20, v156, v20
	v_add_f32_e32 v20, v152, v20
	v_add_f32_e32 v20, v154, v20
	v_add_f32_e32 v20, v147, v20
	v_add_f32_e32 v20, v150, v20
	v_add_f32_e32 v20, v145, v20
	v_add_f32_e32 v20, v148, v20
	v_exp_f32_e32 v18, v128
	v_add_f32_e32 v20, v144, v20
	v_exp_f32_e32 v19, v129
	v_add_f32_e32 v20, v151, v20
	v_exp_f32_e32 v2, v2
	v_add_f32_e32 v20, v146, v20
	v_exp_f32_e32 v3, v3
	v_add_f32_e32 v20, v149, v20
	v_exp_f32_e32 v4, v4
	v_add_f32_e32 v20, v18, v20
	v_exp_f32_e32 v5, v5
	v_add_f32_e32 v20, v19, v20
	v_exp_f32_e32 v6, v6
	v_add_f32_e32 v20, v2, v20
	v_exp_f32_e32 v7, v7
	v_add_f32_e32 v20, v3, v20
	v_exp_f32_e32 v8, v8
	v_add_f32_e32 v20, v4, v20
	v_exp_f32_e32 v9, v9
	v_add_f32_e32 v20, v5, v20
	v_exp_f32_e32 v10, v10
	v_add_f32_e32 v20, v6, v20
	v_exp_f32_e32 v11, v11
	v_add_f32_e32 v20, v7, v20
	v_exp_f32_e32 v12, v12
	v_add_f32_e32 v20, v8, v20
	v_exp_f32_e32 v13, v13
	v_add_f32_e32 v20, v9, v20
	v_exp_f32_e32 v14, v14
	v_add_f32_e32 v20, v10, v20
	v_exp_f32_e32 v15, v15
	v_add_f32_e32 v20, v11, v20
	v_add_f32_e32 v20, v12, v20
	v_add_f32_e32 v20, v13, v20
	v_add_f32_e32 v20, v14, v20
	v_add_f32_e32 v238, v15, v20
	v_mov_b32_e32 v239, v238
	v_cvt_pk_bf16_f32 v22, v157, v159
	v_cvt_pk_bf16_f32 v23, v155, v158
	v_cvt_pk_bf16_f32 v24, v153, v156
	v_cvt_pk_bf16_f32 v25, v152, v154
	v_cvt_pk_bf16_f32 v26, v147, v150
	v_cvt_pk_bf16_f32 v27, v145, v148
	v_cvt_pk_bf16_f32 v28, v144, v151
	v_cvt_pk_bf16_f32 v29, v146, v149
	v_cvt_pk_bf16_f32 v128, v18, v19
	v_cvt_pk_bf16_f32 v129, v2, v3
	v_cvt_pk_bf16_f32 v130, v4, v5
	v_cvt_pk_bf16_f32 v131, v6, v7
	v_cvt_pk_bf16_f32 v132, v8, v9
	v_cvt_pk_bf16_f32 v133, v10, v11
	v_cvt_pk_bf16_f32 v134, v12, v13
	v_cvt_pk_bf16_f32 v135, v14, v15
	v_permlane32_swap_b32_e32 v238, v239
	v_permlane32_swap_b32_e32 v22, v24
	v_permlane32_swap_b32_e32 v23, v25
	v_permlane32_swap_b32_e32 v26, v28
	v_permlane32_swap_b32_e32 v27, v29
	v_permlane32_swap_b32_e32 v128, v130
	v_permlane32_swap_b32_e32 v129, v131
	v_permlane32_swap_b32_e32 v132, v134
	v_permlane32_swap_b32_e32 v133, v135
	s_add_i32 s22, s20, -4
	v_mov_b32_e32 v2, v221
	v_mov_b32_e32 v3, s22
	ds_read_b32 v3, v3
	v_lshlrev_b32_e32 v2, 4, v2
	v_add_u32_e32 v4, 0x2000, v2
	s_waitcnt lgkmcnt(0)
	v_readfirstlane_b32 s2, v3
	s_lshl_b32 s2, s2, 6
	s_ashr_i32 s3, s2, 31
	s_lshl_b64 s[2:3], s[2:3], 8
	s_add_u32 s40, s11, s2
	s_addc_u32 s4, s12, s3
	s_and_b32 s41, s4, 0xffff
	buffer_load_dwordx4 v[18:21], v2, s[40:43], 0 offen sc1
	buffer_load_dwordx4 v[6:9], v4, s[40:43], 0 offen sc1
	s_add_u32 s40, s13, s2
	s_addc_u32 s2, s14, s3
	s_and_b32 s41, s2, 0xffff
	buffer_load_dwordx4 v[10:13], v2, s[40:43], 0 offen sc1
	buffer_load_dwordx4 v[2:5], v4, s[40:43], 0 offen sc1
	s_add_i32 s2, s20, -12
	v_mov_b32_e32 v14, s2
	ds_read_b32 v14, v14
	s_waitcnt lgkmcnt(0)
	v_readfirstlane_b32 s2, v14
	s_lshl_b32 s2, s2, 6
	s_cmp_gt_i32 s2, s8
	s_cbranch_scc1 .LBB0_1925
	v_readfirstlane_b32 s2, v14
	s_lshl_b32 s2, s2, 6
	s_or_b32 s2, s2, 63
	s_cmp_le_i32 s2, s16
	s_cbranch_scc1 .LBB0_1925
	v_readfirstlane_b32 s2, v14
	s_ashr_i32 s3, s2, 5
	s_lshl_b32 s3, s3, 2
	s_add_i32 s3, s19, s3
	v_mov_b32_e32 v14, s3
	ds_read_b32 v14, v14
	s_waitcnt lgkmcnt(0)
	v_readfirstlane_b32 s3, v14
	s_lshr_b32 s2, s3, s2
	s_bitcmp0_b32 s2, 0
	s_cbranch_scc1 .LBB0_1925
	ds_read_b64_tr_b16 v[136:137], v223 offset:0
	ds_read_b64_tr_b16 v[138:139], v223 offset:0x800
	ds_read_b64_tr_b16 v[140:141], v223 offset:0x1000
	ds_read_b64_tr_b16 v[142:143], v223 offset:0x1800
	ds_read_b64_tr_b16 v[144:145], v223 offset:0x2000
	ds_read_b64_tr_b16 v[146:147], v223 offset:0x2800
	ds_read_b64_tr_b16 v[148:149], v223 offset:0x3000
	ds_read_b64_tr_b16 v[150:151], v223 offset:0x3800
	s_waitcnt lgkmcnt(0)
	v_mfma_f32_32x32x16_bf16 v[80:95], v[22:25], v[136:139], v[80:95]
	ds_read_b64_tr_b16 v[136:137], v223 offset:0x200
	ds_read_b64_tr_b16 v[138:139], v223 offset:0xa00
	v_mfma_f32_32x32x16_bf16 v[80:95], v[26:29], v[140:143], v[80:95]
	ds_read_b64_tr_b16 v[140:141], v223 offset:0x1200
	ds_read_b64_tr_b16 v[142:143], v223 offset:0x1a00
	v_mfma_f32_32x32x16_bf16 v[80:95], v[128:131], v[144:147], v[80:95]
	ds_read_b64_tr_b16 v[144:145], v223 offset:0x2200
	ds_read_b64_tr_b16 v[146:147], v223 offset:0x2a00
	v_mfma_f32_32x32x16_bf16 v[80:95], v[132:135], v[148:151], v[80:95]
	ds_read_b64_tr_b16 v[148:149], v223 offset:0x3200
	ds_read_b64_tr_b16 v[150:151], v223 offset:0x3a00
	s_waitcnt lgkmcnt(0)
	v_mfma_f32_32x32x16_bf16 v[64:79], v[22:25], v[136:139], v[64:79]
	ds_read_b64_tr_b16 v[136:137], v223 offset:0x400
	ds_read_b64_tr_b16 v[138:139], v223 offset:0xc00
	v_mfma_f32_32x32x16_bf16 v[64:79], v[26:29], v[140:143], v[64:79]
	ds_read_b64_tr_b16 v[140:141], v223 offset:0x1400
	ds_read_b64_tr_b16 v[142:143], v223 offset:0x1c00
	v_mfma_f32_32x32x16_bf16 v[64:79], v[128:131], v[144:147], v[64:79]
	ds_read_b64_tr_b16 v[144:145], v223 offset:0x2400
	ds_read_b64_tr_b16 v[146:147], v223 offset:0x2c00
	v_mfma_f32_32x32x16_bf16 v[64:79], v[132:135], v[148:151], v[64:79]
	ds_read_b64_tr_b16 v[148:149], v223 offset:0x3400
	ds_read_b64_tr_b16 v[150:151], v223 offset:0x3c00
	s_waitcnt lgkmcnt(0)
	v_mfma_f32_32x32x16_bf16 v[48:63], v[22:25], v[136:139], v[48:63]
	ds_read_b64_tr_b16 v[136:137], v223 offset:0x600
	ds_read_b64_tr_b16 v[138:139], v223 offset:0xe00
	v_mfma_f32_32x32x16_bf16 v[48:63], v[26:29], v[140:143], v[48:63]
	ds_read_b64_tr_b16 v[140:141], v223 offset:0x1600
	ds_read_b64_tr_b16 v[142:143], v223 offset:0x1e00
	v_mfma_f32_32x32x16_bf16 v[48:63], v[128:131], v[144:147], v[48:63]
	ds_read_b64_tr_b16 v[144:145], v223 offset:0x2600
	ds_read_b64_tr_b16 v[146:147], v223 offset:0x2e00
	v_mfma_f32_32x32x16_bf16 v[48:63], v[132:135], v[148:151], v[48:63]
	ds_read_b64_tr_b16 v[148:149], v223 offset:0x3600
	ds_read_b64_tr_b16 v[150:151], v223 offset:0x3e00
	s_waitcnt lgkmcnt(0)
	v_mfma_f32_32x32x16_bf16 v[32:47], v[22:25], v[136:139], v[32:47]
	v_mfma_f32_32x32x16_bf16 v[32:47], v[26:29], v[140:143], v[32:47]
	v_mfma_f32_32x32x16_bf16 v[32:47], v[128:131], v[144:147], v[32:47]
	v_mfma_f32_32x32x16_bf16 v[32:47], v[132:135], v[148:151], v[32:47]

.LBB0_1942:
	v_sub_f32_e32 v22, v97, v14
	v_exp_f32_e32 v97, v22
	v_sub_f32_e32 v25, v99, v14
	v_sub_f32_e32 v15, v112, v14
	v_exp_f32_e32 v99, v25
	v_sub_f32_e32 v28, v101, v14
	v_exp_f32_e32 v112, v15
	v_add_f32_e32 v15, 0, v96
	v_exp_f32_e32 v101, v28
	v_add_f32_e32 v15, v97, v15
	v_sub_f32_e32 v103, v103, v14
	v_add_f32_e32 v15, v98, v15
	v_exp_f32_e32 v103, v103
	v_add_f32_e32 v15, v99, v15
	v_sub_f32_e32 v105, v105, v14
	v_add_f32_e32 v15, v100, v15
	v_exp_f32_e32 v105, v105
	v_add_f32_e32 v15, v101, v15
	v_sub_f32_e32 v107, v107, v14
	v_add_f32_e32 v15, v102, v15
	v_exp_f32_e32 v107, v107
	v_add_f32_e32 v15, v103, v15
	v_sub_f32_e32 v109, v109, v14
	v_add_f32_e32 v15, v104, v15
	v_exp_f32_e32 v109, v109
	v_add_f32_e32 v15, v105, v15
	v_sub_f32_e32 v111, v111, v14
	v_add_f32_e32 v15, v106, v15
	v_exp_f32_e32 v111, v111
	v_add_f32_e32 v15, v107, v15
	v_sub_f32_e32 v23, v113, v14
	v_add_f32_e32 v15, v108, v15
	v_sub_f32_e32 v24, v114, v14
	v_exp_f32_e32 v113, v23
	v_add_f32_e32 v15, v109, v15
	v_sub_f32_e32 v26, v115, v14
	v_exp_f32_e32 v114, v24
	v_add_f32_e32 v15, v110, v15
	v_sub_f32_e32 v27, v116, v14
	v_exp_f32_e32 v115, v26
	v_add_f32_e32 v15, v111, v15
	v_sub_f32_e32 v29, v117, v14
	v_exp_f32_e32 v116, v27
	v_add_f32_e32 v15, v112, v15
	v_sub_f32_e32 v118, v118, v14
	v_exp_f32_e32 v117, v29
	v_add_f32_e32 v15, v113, v15
	v_sub_f32_e32 v119, v119, v14
	v_exp_f32_e32 v118, v118
	v_add_f32_e32 v15, v114, v15
	v_sub_f32_e32 v120, v120, v14
	v_exp_f32_e32 v119, v119
	v_add_f32_e32 v15, v115, v15
	v_sub_f32_e32 v121, v121, v14
	v_exp_f32_e32 v120, v120
	v_add_f32_e32 v15, v116, v15
	v_sub_f32_e32 v122, v122, v14
	v_exp_f32_e32 v121, v121
	v_add_f32_e32 v15, v117, v15
	v_sub_f32_e32 v123, v123, v14
	v_exp_f32_e32 v122, v122
	v_add_f32_e32 v15, v118, v15
	v_sub_f32_e32 v124, v124, v14
	v_exp_f32_e32 v123, v123
	v_add_f32_e32 v15, v119, v15
	v_sub_f32_e32 v125, v125, v14
	v_exp_f32_e32 v124, v124
	v_add_f32_e32 v15, v120, v15
	v_sub_f32_e32 v126, v126, v14
	v_exp_f32_e32 v125, v125
	v_add_f32_e32 v15, v121, v15
	v_sub_f32_e32 v127, v127, v14
	v_exp_f32_e32 v126, v126
	v_add_f32_e32 v15, v122, v15
	v_exp_f32_e32 v127, v127
	v_add_f32_e32 v15, v123, v15
	v_add_f32_e32 v15, v124, v15
	v_add_f32_e32 v15, v125, v15
	v_add_f32_e32 v15, v126, v15
	v_add_f32_e32 v241, v127, v15
	v_mov_b32_e32 v242, v241
	v_cvt_pk_bf16_f32 v22, v96, v97
	v_cvt_pk_bf16_f32 v23, v98, v99
	v_cvt_pk_bf16_f32 v24, v100, v101
	v_cvt_pk_bf16_f32 v25, v102, v103
	v_cvt_pk_bf16_f32 v26, v104, v105
	v_cvt_pk_bf16_f32 v27, v106, v107
	v_cvt_pk_bf16_f32 v28, v108, v109
	v_cvt_pk_bf16_f32 v29, v110, v111
	v_cvt_pk_bf16_f32 v184, v112, v113
	v_cvt_pk_bf16_f32 v185, v114, v115
	v_cvt_pk_bf16_f32 v186, v116, v117
	v_cvt_pk_bf16_f32 v187, v118, v119
	v_cvt_pk_bf16_f32 v188, v120, v121
	v_cvt_pk_bf16_f32 v189, v122, v123
	v_cvt_pk_bf16_f32 v190, v124, v125
	v_cvt_pk_bf16_f32 v191, v126, v127
	v_permlane32_swap_b32_e32 v241, v242
	v_permlane32_swap_b32_e32 v22, v24
	v_permlane32_swap_b32_e32 v23, v25
	v_permlane32_swap_b32_e32 v26, v28
	v_permlane32_swap_b32_e32 v27, v29
	v_permlane32_swap_b32_e32 v184, v186
	v_permlane32_swap_b32_e32 v185, v187
	v_permlane32_swap_b32_e32 v188, v190
	v_permlane32_swap_b32_e32 v189, v191
	s_add_i32 s2, s18, 1
	s_cmp_lt_i32 s2, s9
	s_cselect_b64 s[4:5], -1, 0
	s_cmp_ge_i32 s2, s9
	s_cbranch_scc1 .LBB0_1944
	v_mov_b32_e32 v2, v221
	v_mov_b32_e32 v3, s20
	ds_read_b32 v3, v3
	v_lshlrev_b32_e32 v2, 4, v2
	v_add_u32_e32 v4, 0x2000, v2
	s_waitcnt lgkmcnt(0)
	v_readfirstlane_b32 s2, v3
	s_lshl_b32 s2, s2, 6
	s_ashr_i32 s3, s2, 31
	s_lshl_b64 s[2:3], s[2:3], 8
	s_add_u32 s40, s11, s2
	s_addc_u32 s23, s12, s3
	s_and_b32 s41, s23, 0xffff
	buffer_load_dwordx4 v[18:21], v2, s[40:43], 0 offen sc1
	buffer_load_dwordx4 v[6:9], v4, s[40:43], 0 offen sc1
	s_add_u32 s40, s13, s2
	s_addc_u32 s2, s14, s3
	s_and_b32 s41, s2, 0xffff
	buffer_load_dwordx4 v[10:13], v2, s[40:43], 0 offen sc1
	buffer_load_dwordx4 v[2:5], v4, s[40:43], 0 offen sc1

.LBB0_1956:
	v_max_f32_e32 v15, v145, v145
	v_max_f32_e32 v22, v144, v144
	v_max_f32_e32 v15, v22, v15
	v_max3_f32 v15, v15, v146, v147
	v_max3_f32 v15, v15, v148, v149
	v_max3_f32 v15, v15, v150, v151
	v_max3_f32 v15, v15, v152, v153
	v_max3_f32 v15, v15, v154, v155
	v_max3_f32 v15, v15, v156, v157
	v_max3_f32 v15, v15, v158, v159
	v_max3_f32 v15, v15, v128, v129
	v_max3_f32 v15, v15, v130, v131
	v_max3_f32 v15, v15, v132, v133
	v_max3_f32 v15, v15, v134, v135
	v_max3_f32 v15, v15, v136, v137
	v_max3_f32 v15, v15, v138, v139
	v_max3_f32 v15, v15, v140, v141
	v_max3_f32 v15, v15, v142, v143
	v_mov_b32_e32 v22, v15
	s_nop 1
	v_permlane32_swap_b32_e32 v15, v22
	v_max_f32_e32 v22, v22, v22
	v_max_f32_e32 v15, v15, v15
	v_max_f32_e32 v15, v15, v22
	v_sub_f32_e32 v22, v15, v14
	v_cmp_ge_f32_e32 vcc, s83, v22
	s_cmp_eq_u64 vcc, exec
	s_cselect_b64 s[2:3], -1, 0
	s_andn2_b64 vcc, exec, s[4:5]
	s_barrier
	s_cbranch_vccnz .LBB0_1958
	v_mov_b32_e32 v22, v221
	s_waitcnt vmcnt(0)
	v_ashrrev_i32_e32 v23, 31, v22
	v_lshrrev_b32_e32 v23, 28, v23
	v_add_u32_e32 v23, v22, v23
	v_lshlrev_b32_e32 v24, 4, v23
	v_and_b32_e32 v24, 0xffffff00, v24
	v_lshlrev_b32_e32 v25, 4, v22
	v_sub_u32_e32 v26, v25, v24
	v_bitop3_b32 v23, v26, v23, s73 bitop3:0x78
	v_add3_u32 v23, 0, v24, v23
	s_waitcnt vmcnt(3)
	ds_write_b128 v23, v[18:21] offset:49152
	v_add_u32_e32 v18, 0x200, v22
	v_ashrrev_i32_e32 v19, 31, v18
	v_lshrrev_b32_e32 v19, 28, v19
	v_add_u32_e32 v19, v18, v19
	v_lshlrev_b32_e32 v20, 4, v19
	v_and_b32_e32 v20, 0xffffff00, v20
	v_lshlrev_b32_e32 v18, 4, v18
	v_sub_u32_e32 v18, v18, v20
	v_bitop3_b32 v18, v18, v19, s73 bitop3:0x78
	v_add3_u32 v18, 0, v20, v18
	s_waitcnt vmcnt(2)
	ds_write_b128 v18, v[6:9] offset:49152
	v_ashrrev_i32_e32 v6, 4, v22
	v_and_b32_e32 v7, 0xfffff0, v6
	v_lshlrev_b32_e32 v8, 1, v6
	v_and_or_b32 v7, v8, 8, v7
	v_lshrrev_b32_e32 v8, 1, v6
	v_lshrrev_b32_e32 v7, 1, v7
	v_bfe_u32 v9, v22, 2, 2
	v_and_b32_e32 v18, 3, v6
	v_or_b32_e32 v7, v7, v9
	v_and_or_b32 v8, v8, 4, v18
	v_lshlrev_b32_e32 v7, 9, v7
	v_and_b32_e32 v18, 48, v25
	v_lshl_add_u32 v8, v8, 6, 0
	v_add3_u32 v7, v8, v7, v18
	v_add_u32_e32 v6, 32, v6
	s_waitcnt vmcnt(1)
	ds_write_b128 v7, v[10:13] offset:16384
	v_and_b32_e32 v7, 0xfffff0, v6
	v_lshlrev_b32_e32 v6, 1, v6
	v_and_or_b32 v6, v6, 8, v7
	v_lshrrev_b32_e32 v6, 1, v6
	v_or_b32_e32 v6, v6, v9
	v_lshlrev_b32_e32 v6, 9, v6
	v_add3_u32 v6, v8, v6, v18
	s_waitcnt vmcnt(0)
	ds_write_b128 v6, v[2:5] offset:16384

.LBB0_2011:
	v_add_f32_e32 v18, 0, v157
	v_add_f32_e32 v18, v159, v18
	v_add_f32_e32 v18, v155, v18
	v_add_f32_e32 v18, v158, v18
	v_add_f32_e32 v18, v153, v18
	v_add_f32_e32 v18, v156, v18
	v_add_f32_e32 v18, v152, v18
	v_add_f32_e32 v18, v154, v18
	v_add_f32_e32 v18, v147, v18
	v_add_f32_e32 v18, v150, v18
	v_add_f32_e32 v18, v145, v18
	v_add_f32_e32 v18, v148, v18
	v_exp_f32_e32 v17, v128
	v_add_f32_e32 v18, v144, v18
	v_exp_f32_e32 v26, v129
	v_add_f32_e32 v18, v151, v18
	v_exp_f32_e32 v2, v2
	v_add_f32_e32 v18, v146, v18
	v_exp_f32_e32 v3, v3
	v_add_f32_e32 v18, v149, v18
	v_exp_f32_e32 v4, v4
	v_add_f32_e32 v18, v17, v18
	v_exp_f32_e32 v5, v5
	v_add_f32_e32 v18, v26, v18
	v_exp_f32_e32 v6, v6
	v_add_f32_e32 v18, v2, v18
	v_exp_f32_e32 v7, v7
	v_add_f32_e32 v18, v3, v18
	v_exp_f32_e32 v8, v8
	v_add_f32_e32 v18, v4, v18
	v_exp_f32_e32 v9, v9
	v_add_f32_e32 v18, v5, v18
	v_exp_f32_e32 v10, v10
	v_add_f32_e32 v18, v6, v18
	v_exp_f32_e32 v11, v11
	v_add_f32_e32 v18, v7, v18
	v_exp_f32_e32 v12, v12
	v_add_f32_e32 v18, v8, v18
	v_exp_f32_e32 v13, v13
	v_add_f32_e32 v18, v9, v18
	v_exp_f32_e32 v14, v14
	v_add_f32_e32 v18, v10, v18
	v_exp_f32_e32 v15, v15
	v_add_f32_e32 v18, v11, v18
	v_add_f32_e32 v18, v12, v18
	v_add_f32_e32 v18, v13, v18
	v_add_f32_e32 v18, v14, v18
	v_add_f32_e32 v238, v15, v18
	v_mov_b32_e32 v239, v238
	v_cvt_pk_bf16_f32 v18, v157, v159
	v_cvt_pk_bf16_f32 v19, v155, v158
	v_cvt_pk_bf16_f32 v20, v153, v156
	v_cvt_pk_bf16_f32 v21, v152, v154
	v_cvt_pk_bf16_f32 v22, v147, v150
	v_cvt_pk_bf16_f32 v23, v145, v148
	v_cvt_pk_bf16_f32 v24, v144, v151
	v_cvt_pk_bf16_f32 v25, v146, v149
	v_cvt_pk_bf16_f32 v26, v17, v26
	v_cvt_pk_bf16_f32 v27, v2, v3
	v_cvt_pk_bf16_f32 v28, v4, v5
	v_cvt_pk_bf16_f32 v29, v6, v7
	v_cvt_pk_bf16_f32 v128, v8, v9
	v_cvt_pk_bf16_f32 v129, v10, v11
	v_cvt_pk_bf16_f32 v130, v12, v13
	v_cvt_pk_bf16_f32 v131, v14, v15
	v_permlane32_swap_b32_e32 v238, v239
	v_permlane32_swap_b32_e32 v18, v20
	v_permlane32_swap_b32_e32 v19, v21
	v_permlane32_swap_b32_e32 v22, v24
	v_permlane32_swap_b32_e32 v23, v25
	v_permlane32_swap_b32_e32 v26, v28
	v_permlane32_swap_b32_e32 v27, v29
	v_permlane32_swap_b32_e32 v128, v130
	v_permlane32_swap_b32_e32 v129, v131
	s_sub_i32 s34, s21, 63
	s_lshl_b64 s[10:11], s[34:35], 8
	v_mov_b32_e32 v2, v193
	s_add_u32 s40, s6, s10
	s_addc_u32 s22, s7, s11
	s_and_b32 s41, s22, 0xffff
	v_lshlrev_b32_e32 v2, 4, v2
	v_add_u32_e32 v3, 0x2000, v2
	buffer_load_dwordx4 v[184:187], v2, s[40:43], 0 offen sc1
	buffer_load_dwordx4 v[6:9], v3, s[40:43], 0 offen sc1
	s_add_u32 s40, s8, s10
	s_addc_u32 s10, s9, s11
	s_and_b32 s41, s10, 0xffff
	buffer_load_dwordx4 v[10:13], v2, s[40:43], 0 offen sc1
	buffer_load_dwordx4 v[2:5], v3, s[40:43], 0 offen sc1
	s_add_i32 s10, s21, 0xffffff41
	s_cmp_le_i32 s10, s13
	s_cselect_b64 s[10:11], -1, 0
	s_add_i32 s22, s21, 0xffffff80
	s_cmp_gt_i32 s22, s15
	s_cselect_b64 s[22:23], -1, 0
	s_and_b64 s[10:11], s[10:11], s[22:23]
	s_andn2_b64 vcc, exec, s[10:11]
	s_cbranch_vccnz .LBB0_2013
	ds_read_b64_tr_b16 v[132:133], v222 offset:0
	ds_read_b64_tr_b16 v[134:135], v222 offset:0x800
	ds_read_b64_tr_b16 v[136:137], v222 offset:0x1000
	ds_read_b64_tr_b16 v[138:139], v222 offset:0x1800
	ds_read_b64_tr_b16 v[140:141], v222 offset:0x2000
	ds_read_b64_tr_b16 v[142:143], v222 offset:0x2800
	ds_read_b64_tr_b16 v[144:145], v222 offset:0x3000
	ds_read_b64_tr_b16 v[146:147], v222 offset:0x3800
	s_waitcnt lgkmcnt(0)
	v_mfma_f32_32x32x16_bf16 v[80:95], v[18:21], v[132:135], v[80:95]
	ds_read_b64_tr_b16 v[132:133], v222 offset:0x200
	ds_read_b64_tr_b16 v[134:135], v222 offset:0xa00
	v_mfma_f32_32x32x16_bf16 v[80:95], v[22:25], v[136:139], v[80:95]
	ds_read_b64_tr_b16 v[136:137], v222 offset:0x1200
	ds_read_b64_tr_b16 v[138:139], v222 offset:0x1a00
	v_mfma_f32_32x32x16_bf16 v[80:95], v[26:29], v[140:143], v[80:95]
	ds_read_b64_tr_b16 v[140:141], v222 offset:0x2200
	ds_read_b64_tr_b16 v[142:143], v222 offset:0x2a00
	v_mfma_f32_32x32x16_bf16 v[80:95], v[128:131], v[144:147], v[80:95]
	ds_read_b64_tr_b16 v[144:145], v222 offset:0x3200
	ds_read_b64_tr_b16 v[146:147], v222 offset:0x3a00
	s_waitcnt lgkmcnt(0)
	v_mfma_f32_32x32x16_bf16 v[64:79], v[18:21], v[132:135], v[64:79]
	ds_read_b64_tr_b16 v[132:133], v222 offset:0x400
	ds_read_b64_tr_b16 v[134:135], v222 offset:0xc00
	v_mfma_f32_32x32x16_bf16 v[64:79], v[22:25], v[136:139], v[64:79]
	ds_read_b64_tr_b16 v[136:137], v222 offset:0x1400
	ds_read_b64_tr_b16 v[138:139], v222 offset:0x1c00
	v_mfma_f32_32x32x16_bf16 v[64:79], v[26:29], v[140:143], v[64:79]
	ds_read_b64_tr_b16 v[140:141], v222 offset:0x2400
	ds_read_b64_tr_b16 v[142:143], v222 offset:0x2c00
	v_mfma_f32_32x32x16_bf16 v[64:79], v[128:131], v[144:147], v[64:79]
	ds_read_b64_tr_b16 v[144:145], v222 offset:0x3400
	ds_read_b64_tr_b16 v[146:147], v222 offset:0x3c00
	s_waitcnt lgkmcnt(0)
	v_mfma_f32_32x32x16_bf16 v[48:63], v[18:21], v[132:135], v[48:63]
	ds_read_b64_tr_b16 v[132:133], v222 offset:0x600
	ds_read_b64_tr_b16 v[134:135], v222 offset:0xe00
	v_mfma_f32_32x32x16_bf16 v[48:63], v[22:25], v[136:139], v[48:63]
	ds_read_b64_tr_b16 v[136:137], v222 offset:0x1600
	ds_read_b64_tr_b16 v[138:139], v222 offset:0x1e00
	v_mfma_f32_32x32x16_bf16 v[48:63], v[26:29], v[140:143], v[48:63]
	ds_read_b64_tr_b16 v[140:141], v222 offset:0x2600
	ds_read_b64_tr_b16 v[142:143], v222 offset:0x2e00
	v_mfma_f32_32x32x16_bf16 v[48:63], v[128:131], v[144:147], v[48:63]
	ds_read_b64_tr_b16 v[144:145], v222 offset:0x3600
	ds_read_b64_tr_b16 v[146:147], v222 offset:0x3e00
	s_waitcnt lgkmcnt(0)
	v_mfma_f32_32x32x16_bf16 v[32:47], v[18:21], v[132:135], v[32:47]
	v_mfma_f32_32x32x16_bf16 v[32:47], v[22:25], v[136:139], v[32:47]
	v_mfma_f32_32x32x16_bf16 v[32:47], v[26:29], v[140:143], v[32:47]
	v_mfma_f32_32x32x16_bf16 v[32:47], v[128:131], v[144:147], v[32:47]

.LBB0_2023:
	v_sub_f32_e32 v17, v97, v14
	v_exp_f32_e32 v97, v17
	v_sub_f32_e32 v20, v99, v14
	v_sub_f32_e32 v15, v112, v14
	v_exp_f32_e32 v99, v20
	v_sub_f32_e32 v23, v101, v14
	v_exp_f32_e32 v112, v15
	v_add_f32_e32 v15, 0, v96
	v_exp_f32_e32 v101, v23
	v_add_f32_e32 v15, v97, v15
	v_sub_f32_e32 v26, v103, v14
	v_add_f32_e32 v15, v98, v15
	v_exp_f32_e32 v103, v26
	v_add_f32_e32 v15, v99, v15
	v_sub_f32_e32 v29, v105, v14
	v_add_f32_e32 v15, v100, v15
	v_exp_f32_e32 v105, v29
	v_add_f32_e32 v15, v101, v15
	v_sub_f32_e32 v107, v107, v14
	v_add_f32_e32 v15, v102, v15
	v_exp_f32_e32 v107, v107
	v_add_f32_e32 v15, v103, v15
	v_sub_f32_e32 v109, v109, v14
	v_add_f32_e32 v15, v104, v15
	v_exp_f32_e32 v109, v109
	v_add_f32_e32 v15, v105, v15
	v_sub_f32_e32 v111, v111, v14
	v_add_f32_e32 v15, v106, v15
	v_exp_f32_e32 v111, v111
	v_add_f32_e32 v15, v107, v15
	v_sub_f32_e32 v18, v113, v14
	v_add_f32_e32 v15, v108, v15
	v_sub_f32_e32 v19, v114, v14
	v_exp_f32_e32 v113, v18
	v_add_f32_e32 v15, v109, v15
	v_sub_f32_e32 v21, v115, v14
	v_exp_f32_e32 v114, v19
	v_add_f32_e32 v15, v110, v15
	v_sub_f32_e32 v22, v116, v14
	v_exp_f32_e32 v115, v21
	v_add_f32_e32 v15, v111, v15
	v_sub_f32_e32 v24, v117, v14
	v_exp_f32_e32 v116, v22
	v_add_f32_e32 v15, v112, v15
	v_sub_f32_e32 v25, v118, v14
	v_exp_f32_e32 v117, v24
	v_add_f32_e32 v15, v113, v15
	v_sub_f32_e32 v27, v119, v14
	v_exp_f32_e32 v118, v25
	v_add_f32_e32 v15, v114, v15
	v_sub_f32_e32 v28, v120, v14
	v_exp_f32_e32 v119, v27
	v_add_f32_e32 v15, v115, v15
	v_sub_f32_e32 v30, v121, v14
	v_exp_f32_e32 v120, v28
	v_add_f32_e32 v15, v116, v15
	v_sub_f32_e32 v31, v122, v14
	v_exp_f32_e32 v121, v30
	v_add_f32_e32 v15, v117, v15
	v_sub_f32_e32 v123, v123, v14
	v_exp_f32_e32 v122, v31
	v_add_f32_e32 v15, v118, v15
	v_sub_f32_e32 v124, v124, v14
	v_exp_f32_e32 v123, v123
	v_add_f32_e32 v15, v119, v15
	v_sub_f32_e32 v125, v125, v14
	v_exp_f32_e32 v124, v124
	v_add_f32_e32 v15, v120, v15
	v_sub_f32_e32 v126, v126, v14
	v_exp_f32_e32 v125, v125
	v_add_f32_e32 v15, v121, v15
	v_sub_f32_e32 v127, v127, v14
	v_exp_f32_e32 v126, v126
	v_add_f32_e32 v15, v122, v15
	v_exp_f32_e32 v127, v127
	v_add_f32_e32 v15, v123, v15
	v_add_f32_e32 v15, v124, v15
	v_add_f32_e32 v15, v125, v15
	v_add_f32_e32 v15, v126, v15
	v_add_f32_e32 v17, v127, v15
	v_mov_b32_e32 v30, v17
	v_cvt_pk_bf16_f32 v18, v96, v97
	v_cvt_pk_bf16_f32 v19, v98, v99
	v_cvt_pk_bf16_f32 v20, v100, v101
	v_cvt_pk_bf16_f32 v21, v102, v103
	v_cvt_pk_bf16_f32 v22, v104, v105
	v_cvt_pk_bf16_f32 v23, v106, v107
	v_cvt_pk_bf16_f32 v24, v108, v109
	v_cvt_pk_bf16_f32 v25, v110, v111
	v_cvt_pk_bf16_f32 v26, v112, v113
	v_cvt_pk_bf16_f32 v27, v114, v115
	v_cvt_pk_bf16_f32 v28, v116, v117
	v_cvt_pk_bf16_f32 v29, v118, v119
	v_cvt_pk_bf16_f32 v188, v120, v121
	v_cvt_pk_bf16_f32 v189, v122, v123
	v_cvt_pk_bf16_f32 v190, v124, v125
	v_cvt_pk_bf16_f32 v191, v126, v127
	v_permlane32_swap_b32_e32 v17, v30
	v_permlane32_swap_b32_e32 v18, v20
	v_permlane32_swap_b32_e32 v19, v21
	v_permlane32_swap_b32_e32 v22, v24
	v_permlane32_swap_b32_e32 v23, v25
	v_permlane32_swap_b32_e32 v26, v28
	v_permlane32_swap_b32_e32 v27, v29
	v_permlane32_swap_b32_e32 v188, v190
	v_permlane32_swap_b32_e32 v189, v191
	s_add_i32 s22, s20, 1
	s_cmp_le_u32 s22, s18
	s_cselect_b64 s[10:11], -1, 0
	s_cmp_gt_u32 s22, s18
	s_cbranch_scc1 .LBB0_2026
	s_add_i32 s22, s21, 1
	s_mov_b32 s23, s35
	s_lshl_b64 s[22:23], s[22:23], 8
	v_mov_b32_e32 v2, v193
	s_add_u32 s40, s6, s22
	s_addc_u32 s24, s7, s23
	s_and_b32 s41, s24, 0xffff
	v_lshlrev_b32_e32 v2, 4, v2
	v_add_u32_e32 v3, 0x2000, v2
	buffer_load_dwordx4 v[184:187], v2, s[40:43], 0 offen sc1
	buffer_load_dwordx4 v[6:9], v3, s[40:43], 0 offen sc1
	s_add_u32 s40, s8, s22
	s_addc_u32 s22, s9, s23
	s_and_b32 s41, s22, 0xffff
	buffer_load_dwordx4 v[10:13], v2, s[40:43], 0 offen sc1
	buffer_load_dwordx4 v[2:5], v3, s[40:43], 0 offen sc1
	s_and_b64 vcc, exec, s[2:3]
	s_cbranch_vccz .LBB0_2027

.LBB0_2027:
	ds_read_b64_tr_b16 v[200:201], v222 offset:0x4000
	ds_read_b64_tr_b16 v[202:203], v222 offset:0x4800
	ds_read_b64_tr_b16 v[230:231], v222 offset:0x5000
	ds_read_b64_tr_b16 v[232:233], v222 offset:0x5800
	ds_read_b64_tr_b16 v[242:243], v222 offset:0x6000
	ds_read_b64_tr_b16 v[244:245], v222 offset:0x6800
	ds_read_b64_tr_b16 v[246:247], v222 offset:0x7000
	ds_read_b64_tr_b16 v[248:249], v222 offset:0x7800
	s_waitcnt lgkmcnt(0)
	v_mfma_f32_32x32x16_bf16 v[80:95], v[18:21], v[200:203], v[80:95]
	ds_read_b64_tr_b16 v[200:201], v222 offset:0x4200
	ds_read_b64_tr_b16 v[202:203], v222 offset:0x4a00
	v_mfma_f32_32x32x16_bf16 v[80:95], v[22:25], v[230:233], v[80:95]
	ds_read_b64_tr_b16 v[230:231], v222 offset:0x5200
	ds_read_b64_tr_b16 v[232:233], v222 offset:0x5a00
	v_mfma_f32_32x32x16_bf16 v[80:95], v[26:29], v[242:245], v[80:95]
	ds_read_b64_tr_b16 v[242:243], v222 offset:0x6200
	ds_read_b64_tr_b16 v[244:245], v222 offset:0x6a00
	v_mfma_f32_32x32x16_bf16 v[80:95], v[188:191], v[246:249], v[80:95]
	ds_read_b64_tr_b16 v[246:247], v222 offset:0x7200
	ds_read_b64_tr_b16 v[248:249], v222 offset:0x7a00
	s_waitcnt lgkmcnt(0)
	v_mfma_f32_32x32x16_bf16 v[64:79], v[18:21], v[200:203], v[64:79]
	ds_read_b64_tr_b16 v[200:201], v222 offset:0x4400
	ds_read_b64_tr_b16 v[202:203], v222 offset:0x4c00
	v_mfma_f32_32x32x16_bf16 v[64:79], v[22:25], v[230:233], v[64:79]
	ds_read_b64_tr_b16 v[230:231], v222 offset:0x5400
	ds_read_b64_tr_b16 v[232:233], v222 offset:0x5c00
	v_mfma_f32_32x32x16_bf16 v[64:79], v[26:29], v[242:245], v[64:79]
	ds_read_b64_tr_b16 v[242:243], v222 offset:0x6400
	ds_read_b64_tr_b16 v[244:245], v222 offset:0x6c00
	v_mfma_f32_32x32x16_bf16 v[64:79], v[188:191], v[246:249], v[64:79]
	ds_read_b64_tr_b16 v[246:247], v222 offset:0x7400
	ds_read_b64_tr_b16 v[248:249], v222 offset:0x7c00
	s_waitcnt lgkmcnt(0)
	v_mfma_f32_32x32x16_bf16 v[48:63], v[18:21], v[200:203], v[48:63]
	ds_read_b64_tr_b16 v[200:201], v222 offset:0x4600
	ds_read_b64_tr_b16 v[202:203], v222 offset:0x4e00
	v_mfma_f32_32x32x16_bf16 v[48:63], v[22:25], v[230:233], v[48:63]
	ds_read_b64_tr_b16 v[230:231], v222 offset:0x5600
	ds_read_b64_tr_b16 v[232:233], v222 offset:0x5e00
	v_mfma_f32_32x32x16_bf16 v[48:63], v[26:29], v[242:245], v[48:63]
	ds_read_b64_tr_b16 v[242:243], v222 offset:0x6600
	ds_read_b64_tr_b16 v[244:245], v222 offset:0x6e00
	v_mfma_f32_32x32x16_bf16 v[48:63], v[188:191], v[246:249], v[48:63]
	ds_read_b64_tr_b16 v[246:247], v222 offset:0x7600
	ds_read_b64_tr_b16 v[248:249], v222 offset:0x7e00
	s_waitcnt lgkmcnt(0)
	v_mfma_f32_32x32x16_bf16 v[32:47], v[18:21], v[200:203], v[32:47]
	v_mfma_f32_32x32x16_bf16 v[32:47], v[22:25], v[230:233], v[32:47]
	v_mfma_f32_32x32x16_bf16 v[32:47], v[26:29], v[242:245], v[32:47]
	v_mfma_f32_32x32x16_bf16 v[32:47], v[188:191], v[246:249], v[32:47]
	v_mov_b32_e32 v246, 0x600
	s_and_b64 vcc, exec, s[4:5]
	s_cbranch_vccnz .LBB0_2030

.LBB0_2030:
	v_max_f32_e32 v15, v145, v145
	v_max_f32_e32 v18, v144, v144
	v_max_f32_e32 v15, v18, v15
	v_max3_f32 v15, v15, v146, v147
	v_max3_f32 v15, v15, v148, v149
	v_max3_f32 v15, v15, v150, v151
	v_max3_f32 v15, v15, v152, v153
	v_max3_f32 v15, v15, v154, v155
	v_max3_f32 v15, v15, v156, v157
	v_max3_f32 v15, v15, v158, v159
	v_max3_f32 v15, v15, v128, v129
	v_max3_f32 v15, v15, v130, v131
	v_max3_f32 v15, v15, v132, v133
	v_max3_f32 v15, v15, v134, v135
	v_max3_f32 v15, v15, v136, v137
	v_max3_f32 v15, v15, v138, v139
	v_max3_f32 v15, v15, v140, v141
	v_max3_f32 v15, v15, v142, v143
	v_mov_b32_e32 v18, v15
	s_nop 1
	v_permlane32_swap_b32_e32 v15, v18
	v_max_f32_e32 v18, v18, v18
	v_max_f32_e32 v15, v15, v15
	v_max_f32_e32 v15, v15, v18
	v_sub_f32_e32 v18, v15, v14
	v_cmp_ge_f32_e32 vcc, s83, v18
	s_cmp_eq_u64 vcc, exec
	s_cselect_b64 s[2:3], -1, 0
	s_andn2_b64 vcc, exec, s[10:11]
	s_barrier
	s_cbranch_vccnz .LBB0_2032
	v_mov_b32_e32 v18, v193
	s_waitcnt vmcnt(0)
	v_ashrrev_i32_e32 v19, 31, v18
	v_lshrrev_b32_e32 v19, 28, v19
	v_add_u32_e32 v19, v18, v19
	v_lshlrev_b32_e32 v20, 4, v19
	v_and_b32_e32 v20, 0xffffff00, v20
	v_lshlrev_b32_e32 v21, 4, v18
	v_sub_u32_e32 v22, v21, v20
	v_bitop3_b32 v19, v22, v19, s73 bitop3:0x78
	v_add3_u32 v19, 0, v20, v19
	s_waitcnt vmcnt(3)
	ds_write_b128 v19, v[184:187] offset:49152
	v_add_u32_e32 v19, 0x200, v18
	v_ashrrev_i32_e32 v20, 31, v19
	v_lshrrev_b32_e32 v20, 28, v20
	v_add_u32_e32 v20, v19, v20
	v_lshlrev_b32_e32 v22, 4, v20
	v_and_b32_e32 v22, 0xffffff00, v22
	v_lshlrev_b32_e32 v19, 4, v19
	v_sub_u32_e32 v19, v19, v22
	v_bitop3_b32 v19, v19, v20, s73 bitop3:0x78
	v_add3_u32 v19, 0, v22, v19
	s_waitcnt vmcnt(2)
	ds_write_b128 v19, v[6:9] offset:49152
	v_ashrrev_i32_e32 v6, 4, v18
	v_and_b32_e32 v7, 0xfffff0, v6
	v_lshlrev_b32_e32 v8, 1, v6
	v_and_or_b32 v7, v8, 8, v7
	v_lshrrev_b32_e32 v8, 1, v6
	v_lshrrev_b32_e32 v7, 1, v7
	v_bfe_u32 v9, v18, 2, 2
	v_and_b32_e32 v18, 3, v6
	v_or_b32_e32 v7, v7, v9
	v_and_or_b32 v8, v8, 4, v18
	v_lshlrev_b32_e32 v7, 9, v7
	v_and_b32_e32 v18, 48, v21
	v_lshl_add_u32 v8, v8, 6, 0
	v_add3_u32 v7, v8, v7, v18
	v_add_u32_e32 v6, 32, v6
	s_waitcnt vmcnt(1)
	ds_write_b128 v7, v[10:13] offset:16384
	v_and_b32_e32 v7, 0xfffff0, v6
	v_lshlrev_b32_e32 v6, 1, v6
	v_and_or_b32 v6, v6, 8, v7
	v_lshrrev_b32_e32 v6, 1, v6
	v_or_b32_e32 v6, v6, v9
	v_lshlrev_b32_e32 v6, 9, v6
	v_add3_u32 v6, v8, v6, v18
	s_waitcnt vmcnt(0)
	ds_write_b128 v6, v[2:5] offset:16384

.LBB0_2191:
	v_mov_b32_e32 v114, v14
	s_add_i32 s24, 0, 0x12000
	v_mul_lo_u32 v115, v114, s84
	v_lshlrev_b32_e32 v114, 3, v114
	v_add_u32_e32 v115, s24, v115
	v_and_b32_e32 v114, 0x70, v114
	v_xad_u32 v242, v114, v208, v115
	v_xad_u32 v241, v114, v229, v115
	v_xad_u32 v240, v114, v234, v115
	v_xad_u32 v239, v114, v235, v115
	ds_read_b128 v[114:117], v242 offset:0
	ds_read_b128 v[130:133], v242 offset:0x3000
	ds_read_b128 v[194:197], v241 offset:0
	v_exp_f32_e32 v98, v98
	ds_read_b128 v[186:189], v241 offset:0x3000
	s_waitcnt lgkmcnt(3)
	v_add_f32_e32 v134, 0, v82
	v_mfma_f32_32x32x16_bf16 v[114:129], v[114:117], v[178:181], 0
	ds_read_b128 v[182:185], v240 offset:0
	v_add_f32_e32 v190, 0, v98
	s_waitcnt lgkmcnt(3)
	s_sub_i32 s25, s23, 63
	v_exp_f32_e32 v99, v99
	v_add_f32_e32 v202, v134, v83
	v_mfma_f32_32x32x16_bf16 v[130:145], v[130:133], v[178:181], 0
	s_mul_hi_u32 s3, s25, 0x900
	v_add_f32_e32 v243, v190, v99
	ds_read_b128 v[190:193], v240 offset:0x3000
	s_mul_i32 s2, s25, 0x900
	v_lshl_add_u64 v[220:221], v[204:205], 0, s[2:3]
	v_exp_f32_e32 v100, v100
	s_mov_b32 m0, s13
	v_lshl_add_u64 v[200:201], v[220:221], 0, v[0:1]
	global_load_lds_dwordx4 v[200:201], off
	s_waitcnt lgkmcnt(3)
	v_add_f32_e32 v244, v202, v84
	v_mfma_f32_32x32x16_bf16 v[114:129], v[194:197], v[174:177], v[114:129]
	v_add_f32_e32 v200, v243, v100
	ds_read_b128 v[194:197], v239 offset:0
	v_lshl_add_u64 v[222:223], v[220:221], 0, v[210:211]
	s_waitcnt lgkmcnt(3)
	s_mov_b32 m0, s14
	v_exp_f32_e32 v101, v101
	v_mfma_f32_32x32x16_bf16 v[130:145], v[186:189], v[174:177], v[130:145]
	v_add_f32_e32 v201, v244, v85
	ds_read_b128 v[186:189], v239 offset:0x3000
	v_add_f32_e32 v200, v200, v101
	s_waitcnt lgkmcnt(3)
	v_lshl_add_u64 v[224:225], v[220:221], 0, v[212:213]
	v_exp_f32_e32 v102, v102
	v_mfma_f32_32x32x16_bf16 v[114:129], v[182:185], v[170:173], v[114:129]
	v_add_f32_e32 v201, v201, v86
	ds_read_b128 v[182:185], v242 offset:0x80
	v_add_f32_e32 v200, v200, v102
	s_waitcnt lgkmcnt(3)
	s_mul_hi_u32 s3, s25, 0x600
	v_exp_f32_e32 v103, v103
	v_mfma_f32_32x32x16_bf16 v[130:145], v[190:193], v[170:173], v[130:145]
	v_add_f32_e32 v201, v201, v87
	ds_read_b128 v[190:193], v242 offset:0x3080
	v_add_f32_e32 v200, v200, v103
	global_load_lds_dwordx4 v[222:223], off
	v_exp_f32_e32 v104, v104
	s_waitcnt lgkmcnt(3)
	v_add_f32_e32 v201, v201, v88
	v_mfma_f32_32x32x16_bf16 v[114:129], v[194:197], v[166:169], v[114:129]
	v_add_f32_e32 v200, v200, v104
	ds_read_b128 v[194:197], v241 offset:0x80
	s_mov_b32 m0, s15
	s_waitcnt lgkmcnt(3)
	s_mul_i32 s2, s25, 0x600
	v_exp_f32_e32 v105, v105
	v_mfma_f32_32x32x16_bf16 v[130:145], v[186:189], v[166:169], v[130:145]
	v_add_f32_e32 v201, v201, v89
	ds_read_b128 v[186:189], v241 offset:0x3080
	v_add_f32_e32 v200, v200, v105
	s_waitcnt lgkmcnt(3)
	v_lshl_add_u64 v[218:219], v[206:207], 0, s[2:3]
	v_exp_f32_e32 v106, v106
	v_mfma_f32_32x32x16_bf16 v[114:129], v[182:185], v[162:165], v[114:129]
	v_add_f32_e32 v201, v201, v90
	ds_read_b128 v[182:185], v240 offset:0x80
	v_add_f32_e32 v200, v200, v106
	s_waitcnt lgkmcnt(3)
	s_lshl_b32 s2, s26, 14
	v_exp_f32_e32 v107, v107
	v_mfma_f32_32x32x16_bf16 v[130:145], v[190:193], v[162:165], v[130:145]
	v_add_f32_e32 v201, v201, v91
	ds_read_b128 v[190:193], v240 offset:0x3080
	v_add_f32_e32 v200, v200, v107
	s_waitcnt lgkmcnt(3)
	s_add_i32 s3, s2, 0xffffc000
	v_exp_f32_e32 v108, v108
	v_mfma_f32_32x32x16_bf16 v[114:129], v[194:197], v[158:161], v[114:129]
	v_add_f32_e32 v222, v201, v92
	s_cmp_lg_u32 s26, 0
	v_add_f32_e32 v194, v200, v108
	ds_read_b128 v[200:203], v239 offset:0x80
	s_cselect_b32 s3, s3, 0x8000
	global_load_lds_dwordx4 v[224:225], off
	v_exp_f32_e32 v109, v109
	s_waitcnt lgkmcnt(3)
	v_add_f32_e32 v195, v222, v93
	v_mfma_f32_32x32x16_bf16 v[130:145], v[186:189], v[158:161], v[130:145]
	v_add_f32_e32 v186, v194, v109
	ds_read_b128 v[230:233], v239 offset:0x3080
	s_add_i32 s3, s12, s3
	s_waitcnt lgkmcnt(3)
	v_lshl_add_u64 v[220:221], v[218:219], 0, v[214:215]
	v_exp_f32_e32 v110, v110
	v_mfma_f32_32x32x16_bf16 v[114:129], v[182:185], v[154:157], v[114:129]
	v_add_f32_e32 v187, v195, v94
	ds_read_b128 v[182:185], v242 offset:0x100
	v_add_f32_e32 v186, v186, v110
	s_waitcnt lgkmcnt(3)
	s_mov_b32 m0, s3
	v_exp_f32_e32 v111, v111
	v_mfma_f32_32x32x16_bf16 v[130:145], v[190:193], v[154:157], v[130:145]
	v_add_f32_e32 v187, v187, v95
	ds_read_b128 v[194:197], v242 offset:0x3100
	v_add_f32_e32 v186, v186, v111
	s_waitcnt lgkmcnt(3)
	v_lshl_add_u64 v[224:225], v[218:219], 0, v[216:217]
	v_exp_f32_e32 v112, v112
	v_mfma_f32_32x32x16_bf16 v[114:129], v[200:203], v[150:153], v[114:129]
	v_add_f32_e32 v190, v187, v96
	s_sub_i32 s27, s23, 64
	v_add_f32_e32 v191, v186, v112
	ds_read_b128 v[186:189], v241 offset:0x100
	s_waitcnt lgkmcnt(3)
	v_exp_f32_e32 v113, v113
	v_mfma_f32_32x32x16_bf16 v[130:145], v[230:233], v[150:153], v[130:145]
	v_add_f32_e32 v222, v190, v97
	v_add_f32_e32 v223, v191, v113
	ds_read_b128 v[190:193], v241 offset:0x3100
	global_load_lds_dwordx4 v[220:221], off
	s_waitcnt lgkmcnt(3)
	s_add_i32 m0, s3, 0x2000
	v_mfma_f32_32x32x16_bf16 v[114:129], v[182:185], v[146:149], v[114:129]
	ds_read_b128 v[200:203], v240 offset:0x100
	v_cvt_pk_bf16_f32 v182, v82, v83
	v_cvt_pk_bf16_f32 v184, v86, v87
	s_add_i32 s3, s23, 0xffffff81
	v_permlane32_swap_b32_e32 v182, v184
	s_waitcnt lgkmcnt(3)
	s_cmp_le_i32 s27, s9
	v_mfma_f32_32x32x16_bf16 v[130:145], v[194:197], v[146:149], v[130:145]
	ds_read_b128 v[194:197], v240 offset:0x3100
	v_cvt_pk_bf16_f32 v183, v84, v85
	v_cvt_pk_bf16_f32 v185, v88, v89
	s_cselect_b64 s[28:29], -1, 0
	v_permlane32_swap_b32_e32 v183, v185
	s_waitcnt lgkmcnt(3)
	s_cmp_gt_i32 s3, s11
	v_mfma_f32_32x32x16_bf16 v[114:129], v[186:189], v[10:13], v[114:129]
	ds_read_b128 v[230:233], v239 offset:0x100
	v_cvt_pk_bf16_f32 v186, v90, v91
	v_cvt_pk_bf16_f32 v188, v94, v95
	s_cselect_b64 s[30:31], -1, 0
	v_permlane32_swap_b32_e32 v186, v188
	s_waitcnt lgkmcnt(3)
	s_and_b64 s[28:29], s[28:29], s[30:31]
	v_mfma_f32_32x32x16_bf16 v[130:145], v[190:193], v[10:13], v[130:145]
	ds_read_b128 v[218:221], v239 offset:0x3100
	v_cvt_pk_bf16_f32 v187, v92, v93
	v_cvt_pk_bf16_f32 v189, v96, v97
	s_and_b64 vcc, exec, s[28:29]
	v_permlane32_swap_b32_e32 v187, v189
	s_waitcnt lgkmcnt(3)
	v_cvt_pk_bf16_f32 v190, v98, v99
	v_cvt_pk_bf16_f32 v192, v102, v103
	v_mfma_f32_32x32x16_bf16 v[114:129], v[200:203], v[6:9], v[114:129]
	v_permlane32_swap_b32_e32 v190, v192
	global_load_lds_dwordx4 v[224:225], off
	s_waitcnt lgkmcnt(2)
	v_cvt_pk_bf16_f32 v191, v100, v101
	v_cvt_pk_bf16_f32 v193, v104, v105
	s_nop 0
	v_mfma_f32_32x32x16_bf16 v[130:145], v[194:197], v[6:9], v[130:145]
	v_permlane32_swap_b32_e32 v191, v193
	s_waitcnt lgkmcnt(1)
	v_cvt_pk_bf16_f32 v194, v106, v107
	v_cvt_pk_bf16_f32 v196, v110, v111
	v_mfma_f32_32x32x16_bf16 v[114:129], v[230:233], v[2:5], v[114:129]
	v_permlane32_swap_b32_e32 v194, v196
	s_waitcnt lgkmcnt(0)
	v_cvt_pk_bf16_f32 v195, v108, v109
	v_cvt_pk_bf16_f32 v197, v112, v113
	v_mfma_f32_32x32x16_bf16 v[130:145], v[218:221], v[2:5], v[130:145]
	v_permlane32_swap_b32_e32 v195, v197
	v_add_f32_e32 v222, v222, v223
	v_mov_b32_e32 v223, v222
	s_nop 1
	v_permlane32_swap_b32_e32 v222, v223
	s_cbranch_vccnz .LBB0_2193
	v_add_u32_e32 v82, 0x7b, v237
	v_cmp_gt_u32_e32 vcc, 2.0, v82
	v_add_u32_e32 v82, 0x5b, v237
	s_nop 0
	v_cndmask_b32_e32 v114, v16, v114, vcc
	v_cmp_gt_u32_e32 vcc, 2.0, v82
	v_add_u32_e32 v82, 0x7a, v237
	s_nop 0
	v_cndmask_b32_e32 v130, v16, v130, vcc
	v_cmp_gt_u32_e32 vcc, 2.0, v82
	v_add_u32_e32 v82, 0x5a, v237
	s_nop 0
	v_cndmask_b32_e32 v115, v16, v115, vcc
	v_cmp_gt_u32_e32 vcc, 2.0, v82
	v_add_u32_e32 v82, 0x79, v237
	s_nop 0
	v_cndmask_b32_e32 v131, v16, v131, vcc
	v_cmp_gt_u32_e32 vcc, 2.0, v82
	v_add_u32_e32 v82, 0x59, v237
	s_nop 0
	v_cndmask_b32_e32 v116, v16, v116, vcc
	v_cmp_gt_u32_e32 vcc, 2.0, v82
	v_add_u32_e32 v82, 0x78, v237
	s_nop 0
	v_cndmask_b32_e32 v132, v16, v132, vcc
	v_cmp_gt_u32_e32 vcc, 2.0, v82
	v_add_u32_e32 v82, 0x58, v237
	s_nop 0
	v_cndmask_b32_e32 v117, v16, v117, vcc
	v_cmp_gt_u32_e32 vcc, 2.0, v82
	v_add_u32_e32 v82, 0x73, v237
	s_nop 0
	v_cndmask_b32_e32 v133, v16, v133, vcc
	v_cmp_gt_u32_e32 vcc, 2.0, v82
	v_add_u32_e32 v82, 0x53, v237
	s_nop 0
	v_cndmask_b32_e32 v118, v16, v118, vcc
	v_cmp_gt_u32_e32 vcc, 2.0, v82
	v_add_u32_e32 v82, 0x72, v237
	s_nop 0
	v_cndmask_b32_e32 v134, v16, v134, vcc
	v_cmp_gt_u32_e32 vcc, 2.0, v82
	v_add_u32_e32 v82, 0x52, v237
	s_nop 0
	v_cndmask_b32_e32 v119, v16, v119, vcc
	v_cmp_gt_u32_e32 vcc, 2.0, v82
	v_add_u32_e32 v82, 0x71, v237
	s_nop 0
	v_cndmask_b32_e32 v135, v16, v135, vcc
	v_cmp_gt_u32_e32 vcc, 2.0, v82
	v_add_u32_e32 v82, 0x51, v237
	s_nop 0
	v_cndmask_b32_e32 v120, v16, v120, vcc
	v_cmp_gt_u32_e32 vcc, 2.0, v82
	v_add_u32_e32 v82, 0x70, v237
	s_nop 0
	v_cndmask_b32_e32 v136, v16, v136, vcc
	v_cmp_gt_u32_e32 vcc, 2.0, v82
	v_add_u32_e32 v82, 0x50, v237
	s_nop 0
	v_cndmask_b32_e32 v121, v16, v121, vcc
	v_cmp_gt_u32_e32 vcc, 2.0, v82
	v_add_u32_e32 v82, 0x6b, v237
	s_nop 0
	v_cndmask_b32_e32 v137, v16, v137, vcc
	v_cmp_gt_u32_e32 vcc, 2.0, v82
	v_add_u32_e32 v82, 0x4b, v237
	s_nop 0
	v_cndmask_b32_e32 v122, v16, v122, vcc
	v_cmp_gt_u32_e32 vcc, 2.0, v82
	v_add_u32_e32 v82, 0x6a, v237
	s_nop 0
	v_cndmask_b32_e32 v138, v16, v138, vcc
	v_cmp_gt_u32_e32 vcc, 2.0, v82
	v_add_u32_e32 v82, 0x4a, v237
	s_nop 0
	v_cndmask_b32_e32 v123, v16, v123, vcc
	v_cmp_gt_u32_e32 vcc, 2.0, v82
	v_add_u32_e32 v82, 0x69, v237
	s_nop 0
	v_cndmask_b32_e32 v139, v16, v139, vcc
	v_cmp_gt_u32_e32 vcc, 2.0, v82
	v_add_u32_e32 v82, 0x49, v237
	s_nop 0
	v_cndmask_b32_e32 v124, v16, v124, vcc
	v_cmp_gt_u32_e32 vcc, 2.0, v82
	v_add_u32_e32 v82, 0x68, v237
	s_nop 0
	v_cndmask_b32_e32 v140, v16, v140, vcc
	v_cmp_gt_u32_e32 vcc, 2.0, v82
	v_add_u32_e32 v82, 0x48, v237
	s_nop 0
	v_cndmask_b32_e32 v125, v16, v125, vcc
	v_cmp_gt_u32_e32 vcc, 2.0, v82
	v_add_u32_e32 v82, 0x63, v237
	s_nop 0
	v_cndmask_b32_e32 v141, v16, v141, vcc
	v_cmp_gt_u32_e32 vcc, 2.0, v82
	v_add_u32_e32 v82, 0x43, v237
	s_nop 0
	v_cndmask_b32_e32 v126, v16, v126, vcc
	v_cmp_gt_u32_e32 vcc, 2.0, v82
	v_add_u32_e32 v82, 0x62, v237
	s_nop 0
	v_cndmask_b32_e32 v142, v16, v142, vcc
	v_cmp_gt_u32_e32 vcc, 2.0, v82
	v_add_u32_e32 v82, 0x42, v237
	s_nop 0
	v_cndmask_b32_e32 v127, v16, v127, vcc
	v_cmp_gt_u32_e32 vcc, 2.0, v82
	v_add_u32_e32 v82, 0x61, v237
	s_nop 0
	v_cndmask_b32_e32 v143, v16, v143, vcc
	v_cmp_gt_u32_e32 vcc, 2.0, v82
	v_add_u32_e32 v82, 0x41, v237
	s_nop 0
	v_cndmask_b32_e32 v128, v16, v128, vcc
	v_cmp_gt_u32_e32 vcc, 2.0, v82
	v_add_u32_e32 v82, 0x60, v237
	s_nop 0
	v_cndmask_b32_e32 v144, v16, v144, vcc
	v_cmp_gt_u32_e32 vcc, 2.0, v82
	v_add_u32_e32 v82, 64, v237
	s_nop 0
	v_cndmask_b32_e32 v129, v16, v129, vcc
	v_cmp_gt_u32_e32 vcc, 2.0, v82
	s_nop 1
	v_cndmask_b32_e32 v145, v16, v145, vcc
.LBB0_2193:
	v_add_u32_e32 v102, s2, v209
	ds_read_b64_tr_b16 v[82:83], v102 offset:0
	ds_read_b64_tr_b16 v[84:85], v102 offset:0x800
	ds_read_b64_tr_b16 v[86:87], v102 offset:0x1000
	ds_read_b64_tr_b16 v[88:89], v102 offset:0x1800
	ds_read_b64_tr_b16 v[90:91], v102 offset:0x2000
	ds_read_b64_tr_b16 v[92:93], v102 offset:0x2800
	ds_read_b64_tr_b16 v[94:95], v102 offset:0x3000
	v_max3_f32 v98, v114, s72, v115
	ds_read_b64_tr_b16 v[96:97], v102 offset:0x3800
	v_max3_f32 v98, v98, v116, v117
	s_waitcnt lgkmcnt(6)
	v_max3_f32 v98, v98, v118, v119
	v_mfma_f32_32x32x16_bf16 v[50:65], v[182:185], v[82:85], v[50:65]
	v_max3_f32 v98, v98, v120, v121
	ds_read_b64_tr_b16 v[82:83], v102 offset:0x200
	ds_read_b64_tr_b16 v[84:85], v102 offset:0xa00
	v_max_f32_e32 v99, v238, v238
	s_waitcnt lgkmcnt(6)
	v_max3_f32 v98, v98, v122, v123
	v_max3_f32 v98, v98, v124, v125
	v_max3_f32 v98, v98, v126, v127
	v_mfma_f32_32x32x16_bf16 v[50:65], v[186:189], v[86:89], v[50:65]
	v_max3_f32 v98, v98, v128, v129
	ds_read_b64_tr_b16 v[86:87], v102 offset:0x1200
	ds_read_b64_tr_b16 v[88:89], v102 offset:0x1a00
	s_waitcnt lgkmcnt(6)
	v_max3_f32 v98, v98, v130, v131
	v_max3_f32 v98, v98, v132, v133
	v_max3_f32 v98, v98, v134, v135
	v_mfma_f32_32x32x16_bf16 v[50:65], v[190:193], v[90:93], v[50:65]
	v_max3_f32 v98, v98, v136, v137
	ds_read_b64_tr_b16 v[90:91], v102 offset:0x2200
	ds_read_b64_tr_b16 v[92:93], v102 offset:0x2a00
	s_waitcnt lgkmcnt(6)
	v_max3_f32 v98, v98, v138, v139
	v_max3_f32 v98, v98, v140, v141
	v_max3_f32 v98, v98, v142, v143
	v_mfma_f32_32x32x16_bf16 v[50:65], v[194:197], v[94:97], v[50:65]
	v_max3_f32 v98, v98, v144, v145
	ds_read_b64_tr_b16 v[94:95], v102 offset:0x3200
	ds_read_b64_tr_b16 v[96:97], v102 offset:0x3a00
	s_waitcnt lgkmcnt(6)
	v_mov_b32_e32 v100, v98
	s_nop 1
	v_permlane32_swap_b32_e32 v98, v100
	v_max_f32_e32 v100, v100, v100
	v_max_f32_e32 v98, v98, v98
	v_mfma_f32_32x32x16_bf16 v[66:81], v[182:185], v[82:85], v[66:81]
	v_max_f32_e32 v83, v98, v100
	v_sub_f32_e32 v82, v83, v238
	v_cmp_ge_f32_e32 vcc, s83, v82
	s_cmp_eq_u64 vcc, exec
	v_max_f32_e32 v84, v99, v83
	s_cselect_b64 vcc, -1, 0
	v_cndmask_b32_e32 v225, v84, v238, vcc
	v_sub_f32_e32 v84, v238, v225
	v_mov_b32_e32 v82, v225
	v_exp_f32_e32 v224, v84
	ds_read_b64_tr_b16 v[98:99], v102 offset:0x400
	ds_read_b64_tr_b16 v[100:101], v102 offset:0xc00
	s_waitcnt lgkmcnt(6)
	v_cmp_gt_f32_e32 vcc, 1.0, v224
	v_sub_f32_e32 v84, v114, v82
	v_mfma_f32_32x32x16_bf16 v[66:81], v[186:189], v[86:89], v[66:81]
	v_sub_f32_e32 v130, v130, v82
	v_exp_f32_e32 v114, v84
	ds_read_b64_tr_b16 v[84:85], v102 offset:0x1400
	ds_read_b64_tr_b16 v[86:87], v102 offset:0x1c00
	s_waitcnt lgkmcnt(6)
	v_sub_f32_e32 v88, v115, v82
	v_mfma_f32_32x32x16_bf16 v[66:81], v[190:193], v[90:93], v[66:81]
	v_sub_f32_e32 v131, v131, v82
	v_exp_f32_e32 v115, v88
	ds_read_b64_tr_b16 v[88:89], v102 offset:0x2400
	ds_read_b64_tr_b16 v[90:91], v102 offset:0x2c00
	s_waitcnt lgkmcnt(6)
	v_sub_f32_e32 v92, v116, v82
	v_sub_f32_e32 v93, v117, v82
	v_mfma_f32_32x32x16_bf16 v[66:81], v[194:197], v[94:97], v[66:81]
	v_add_f32_e64 v132, v132, -v82
	v_add_f32_e64 v133, v133, -v82
	v_exp_f32_e32 v116, v92
	v_exp_f32_e32 v117, v93
	ds_read_b64_tr_b16 v[92:93], v102 offset:0x3400
	ds_read_b64_tr_b16 v[94:95], v102 offset:0x3c00
	s_waitcnt lgkmcnt(6)
	v_sub_f32_e32 v96, v118, v82
	v_mfma_f32_32x32x16_bf16 v[34:49], v[182:185], v[98:101], v[34:49]
	v_sub_f32_e32 v134, v134, v82
	v_exp_f32_e32 v118, v96
	ds_read_b64_tr_b16 v[96:97], v102 offset:0x600
	ds_read_b64_tr_b16 v[98:99], v102 offset:0xe00
	s_waitcnt lgkmcnt(6)
	v_mov_b32_e32 v100, v135
	v_mov_b32_e32 v101, v136
	v_sub_f32_e32 v103, v119, v82
	v_sub_f32_e32 v104, v120, v82
	v_pk_add_f32 v[100:101], v[100:101], v[82:83] op_sel_hi:[1,0] neg_lo:[0,1] neg_hi:[0,1]
	v_mfma_f32_32x32x16_bf16 v[34:49], v[186:189], v[84:87], v[34:49]
	v_exp_f32_e32 v119, v103
	v_exp_f32_e32 v120, v104
	v_mov_b32_e32 v135, v100
	v_mov_b32_e32 v136, v101
	ds_read_b64_tr_b16 v[84:85], v102 offset:0x1600
	ds_read_b64_tr_b16 v[86:87], v102 offset:0x1e00
	s_waitcnt lgkmcnt(6)
	v_sub_f32_e32 v100, v121, v82
	v_mfma_f32_32x32x16_bf16 v[34:49], v[190:193], v[88:91], v[34:49]
	v_sub_f32_e32 v137, v137, v82
	v_exp_f32_e32 v121, v100
	ds_read_b64_tr_b16 v[88:89], v102 offset:0x2600
	ds_read_b64_tr_b16 v[90:91], v102 offset:0x2e00
	s_waitcnt lgkmcnt(6)
	v_sub_f32_e32 v100, v122, v82
	v_sub_f32_e32 v101, v123, v82
	v_mfma_f32_32x32x16_bf16 v[34:49], v[194:197], v[92:95], v[34:49]
	v_add_f32_e64 v138, v138, -v82
	v_add_f32_e64 v139, v139, -v82
	v_exp_f32_e32 v122, v100
	v_exp_f32_e32 v123, v101
	ds_read_b64_tr_b16 v[92:93], v102 offset:0x3600
	ds_read_b64_tr_b16 v[94:95], v102 offset:0x3e00
	s_waitcnt lgkmcnt(6)
	v_sub_f32_e32 v100, v124, v82
	v_sub_f32_e32 v140, v140, v82
	v_exp_f32_e32 v124, v100
	v_mfma_f32_32x32x16_bf16 v[18:33], v[182:185], v[96:99], v[18:33]
	s_waitcnt lgkmcnt(4)
	v_mov_b32_e32 v96, v141
	v_mov_b32_e32 v97, v142
	v_sub_f32_e32 v98, v125, v82
	v_sub_f32_e32 v99, v126, v82
	v_pk_add_f32 v[96:97], v[96:97], v[82:83] op_sel_hi:[1,0] neg_lo:[0,1] neg_hi:[0,1]
	v_exp_f32_e32 v125, v98
	v_exp_f32_e32 v126, v99
	v_mfma_f32_32x32x16_bf16 v[18:33], v[186:189], v[84:87], v[18:33]
	v_mov_b32_e32 v141, v96
	v_mov_b32_e32 v142, v97
	s_waitcnt lgkmcnt(2)
	v_sub_f32_e32 v84, v127, v82
	v_exp_f32_e32 v127, v84
	v_mfma_f32_32x32x16_bf16 v[18:33], v[190:193], v[88:91], v[18:33]
	v_sub_f32_e32 v143, v143, v82
	s_waitcnt lgkmcnt(0)
	v_sub_f32_e32 v84, v128, v82
	v_sub_f32_e32 v85, v129, v82
	v_exp_f32_e32 v128, v84
	v_exp_f32_e32 v129, v85
	v_mfma_f32_32x32x16_bf16 v[18:33], v[194:197], v[92:95], v[18:33]
	v_add_f32_e64 v144, v144, -v82
	v_add_f32_e64 v145, v145, -v82
	s_cbranch_vccz .LBB0_2197
	s_and_saveexec_b64 s[2:3], s[0:1]
	ds_write_b32 v228, v224 offset:128
	s_or_b64 exec, exec, s[2:3]
	s_waitcnt lgkmcnt(0)
	ds_read_b128 v[82:85], v227 offset:224
	ds_read_b128 v[86:89], v227 offset:192
	ds_read_b128 v[90:93], v227 offset:160
	ds_read_b128 v[94:97], v227 offset:128
	s_waitcnt lgkmcnt(0)
	v_pk_mul_f32 v[64:65], v[64:65], v[84:85]
	v_pk_mul_f32 v[60:61], v[60:61], v[88:89]
	v_pk_mul_f32 v[56:57], v[56:57], v[92:93]
	v_pk_mul_f32 v[52:53], v[52:53], v[96:97]
	v_pk_mul_f32 v[62:63], v[62:63], v[82:83]
	v_pk_mul_f32 v[58:59], v[58:59], v[86:87]
	v_pk_mul_f32 v[54:55], v[54:55], v[90:91]
	v_pk_mul_f32 v[50:51], v[50:51], v[94:95]
	v_pk_mul_f32 v[80:81], v[80:81], v[84:85]
	v_pk_mul_f32 v[76:77], v[76:77], v[88:89]
	v_pk_mul_f32 v[72:73], v[72:73], v[92:93]
	v_pk_mul_f32 v[68:69], v[68:69], v[96:97]
	v_pk_mul_f32 v[78:79], v[78:79], v[82:83]
	v_pk_mul_f32 v[74:75], v[74:75], v[86:87]
	v_pk_mul_f32 v[70:71], v[70:71], v[90:91]
	v_pk_mul_f32 v[66:67], v[66:67], v[94:95]
	v_pk_mul_f32 v[48:49], v[48:49], v[84:85]
	v_pk_mul_f32 v[44:45], v[44:45], v[88:89]
	v_pk_mul_f32 v[40:41], v[40:41], v[92:93]
	v_pk_mul_f32 v[36:37], v[36:37], v[96:97]
	v_pk_mul_f32 v[46:47], v[46:47], v[82:83]
	v_pk_mul_f32 v[42:43], v[42:43], v[86:87]
	v_pk_mul_f32 v[38:39], v[38:39], v[90:91]
	v_pk_mul_f32 v[34:35], v[34:35], v[94:95]
	v_pk_mul_f32 v[32:33], v[32:33], v[84:85]
	v_pk_mul_f32 v[28:29], v[28:29], v[88:89]
	v_pk_mul_f32 v[24:25], v[24:25], v[92:93]
	v_pk_mul_f32 v[20:21], v[20:21], v[96:97]
	v_pk_mul_f32 v[30:31], v[30:31], v[82:83]
	v_pk_mul_f32 v[26:27], v[26:27], v[86:87]
	v_pk_mul_f32 v[22:23], v[22:23], v[90:91]
	v_pk_mul_f32 v[18:19], v[18:19], v[94:95]
.LBB0_2197:
	v_mov_b32_e32 v82, v14
	s_waitcnt vmcnt(0)
	s_waitcnt vmcnt(0) lgkmcnt(0)
	s_barrier
	v_exp_f32_e32 v130, v130
	v_mul_lo_u32 v83, v82, s84
	v_lshlrev_b32_e32 v82, 3, v82
	v_add_u32_e32 v83, s19, v83
	v_and_b32_e32 v82, 0x70, v82
	v_xad_u32 v241, v82, v208, v83
	v_xad_u32 v240, v82, v229, v83
	v_xad_u32 v239, v82, v234, v83
	v_xad_u32 v238, v82, v235, v83
	ds_read_b128 v[82:85], v241 offset:0
	ds_read_b128 v[98:101], v241 offset:0x3000
	ds_read_b128 v[200:203], v240 offset:0
	ds_read_b128 v[190:193], v240 offset:0x3000
	v_add_f32_e32 v196, 0, v114
	s_waitcnt lgkmcnt(3)
	v_add_f32_e32 v197, 0, v130
	v_mfma_f32_32x32x16_bf16 v[82:97], v[82:85], v[178:181], 0
	ds_read_b128 v[182:185], v239 offset:0
	s_add_i32 s2, s26, 1
	s_cmp_lg_u32 s26, 2
	v_exp_f32_e32 v131, v131
	s_waitcnt lgkmcnt(3)
	s_cselect_b32 s26, s2, 0
	s_add_i32 s2, s20, 1
	v_mfma_f32_32x32x16_bf16 v[98:113], v[98:101], v[178:181], 0
	s_min_i32 s2, s2, s22
	ds_read_b128 v[186:189], v239 offset:0x3000
	v_add_f32_e32 v220, v196, v115
	v_add_f32_e32 v221, v197, v131
	s_lshl_b32 s27, s2, 6
	v_mad_u64_u32 v[194:195], s[2:3], s27, v252, v[204:205]
	v_exp_f32_e32 v132, v132
	s_mov_b32 m0, s16
	v_lshl_add_u64 v[196:197], v[194:195], 0, v[0:1]
	global_load_lds_dwordx4 v[196:197], off
	s_waitcnt lgkmcnt(3)
	v_add_f32_e32 v243, v220, v116
	v_mfma_f32_32x32x16_bf16 v[82:97], v[200:203], v[174:177], v[82:97]
	v_add_f32_e32 v242, v221, v132
	ds_read_b128 v[200:203], v238 offset:0
	v_lshl_add_u64 v[196:197], v[194:195], 0, v[210:211]
	s_waitcnt lgkmcnt(3)
	s_mov_b32 m0, s17
	v_exp_f32_e32 v133, v133
	v_mfma_f32_32x32x16_bf16 v[98:113], v[190:193], v[174:177], v[98:113]
	v_add_f32_e32 v230, v243, v117
	ds_read_b128 v[190:193], v238 offset:0x3000
	v_add_f32_e32 v231, v242, v133
	s_waitcnt lgkmcnt(3)
	v_lshl_add_u64 v[194:195], v[194:195], 0, v[212:213]
	v_exp_f32_e32 v134, v134
	v_mfma_f32_32x32x16_bf16 v[82:97], v[182:185], v[170:173], v[82:97]
	v_add_f32_e32 v230, v230, v118
	ds_read_b128 v[182:185], v241 offset:0x80
	v_add_f32_e32 v231, v231, v134
	s_waitcnt lgkmcnt(3)
	v_mad_u64_u32 v[218:219], s[2:3], s27, v246, v[206:207]
	v_exp_f32_e32 v135, v135
	v_mfma_f32_32x32x16_bf16 v[98:113], v[186:189], v[170:173], v[98:113]
	v_add_f32_e32 v230, v230, v119
	ds_read_b128 v[186:189], v241 offset:0x3080
	v_add_f32_e32 v231, v231, v135
	global_load_lds_dwordx4 v[196:197], off
	v_exp_f32_e32 v136, v136
	s_waitcnt lgkmcnt(3)
	v_add_f32_e32 v196, v230, v120
	v_mfma_f32_32x32x16_bf16 v[82:97], v[200:203], v[166:169], v[82:97]
	v_add_f32_e32 v197, v231, v136
	ds_read_b128 v[200:203], v240 offset:0x80
	s_mov_b32 m0, s18
	s_waitcnt lgkmcnt(3)
	s_lshl_b32 s2, s26, 14
	v_exp_f32_e32 v137, v137
	v_mfma_f32_32x32x16_bf16 v[98:113], v[190:193], v[166:169], v[98:113]
	v_add_f32_e32 v196, v196, v121
	ds_read_b128 v[190:193], v240 offset:0x3080
	v_add_f32_e32 v197, v197, v137
	s_waitcnt lgkmcnt(3)
	s_add_i32 s3, s2, 0xffffc000
	v_exp_f32_e32 v138, v138
	v_mfma_f32_32x32x16_bf16 v[82:97], v[182:185], v[162:165], v[82:97]
	v_add_f32_e32 v196, v196, v122
	ds_read_b128 v[182:185], v239 offset:0x80
	v_add_f32_e32 v197, v197, v138
	s_waitcnt lgkmcnt(3)
	s_cmp_lg_u32 s26, 0
	v_exp_f32_e32 v139, v139
	v_mfma_f32_32x32x16_bf16 v[98:113], v[186:189], v[162:165], v[98:113]
	v_add_f32_e32 v196, v196, v123
	ds_read_b128 v[186:189], v239 offset:0x3080
	v_add_f32_e32 v197, v197, v139
	s_waitcnt lgkmcnt(3)
	s_cselect_b32 s3, s3, 0x8000
	v_exp_f32_e32 v140, v140
	v_mfma_f32_32x32x16_bf16 v[82:97], v[200:203], v[158:161], v[82:97]
	v_add_f32_e32 v196, v196, v124
	ds_read_b128 v[200:203], v238 offset:0x80
	v_add_f32_e32 v197, v197, v140
	global_load_lds_dwordx4 v[194:195], off
	v_exp_f32_e32 v141, v141
	s_waitcnt lgkmcnt(3)
	v_add_f32_e32 v194, v196, v125
	v_mfma_f32_32x32x16_bf16 v[98:113], v[190:193], v[158:161], v[98:113]
	v_add_f32_e32 v195, v197, v141
	ds_read_b128 v[190:193], v238 offset:0x3080
	s_add_i32 s3, s12, s3
	s_waitcnt lgkmcnt(3)
	v_lshl_add_u64 v[220:221], v[218:219], 0, v[214:215]
	v_exp_f32_e32 v142, v142
	v_mfma_f32_32x32x16_bf16 v[82:97], v[182:185], v[154:157], v[82:97]
	v_add_f32_e32 v194, v194, v126
	ds_read_b128 v[182:185], v241 offset:0x100
	v_add_f32_e32 v195, v195, v142
	s_waitcnt lgkmcnt(3)
	s_mov_b32 m0, s3
	v_exp_f32_e32 v143, v143
	v_mfma_f32_32x32x16_bf16 v[98:113], v[186:189], v[154:157], v[98:113]
	v_add_f32_e32 v230, v194, v127
	v_lshl_add_u64 v[244:245], v[218:219], 0, v[216:217]
	v_add_f32_e32 v186, v195, v143
	ds_read_b128 v[194:197], v241 offset:0x3100
	s_waitcnt lgkmcnt(3)
	v_exp_f32_e32 v144, v144
	v_mfma_f32_32x32x16_bf16 v[82:97], v[200:203], v[150:153], v[82:97]
	v_add_f32_e32 v230, v230, v128
	v_add_f32_e32 v200, v186, v144
	ds_read_b128 v[186:189], v240 offset:0x100
	s_waitcnt lgkmcnt(3)
	v_exp_f32_e32 v145, v145
	v_mfma_f32_32x32x16_bf16 v[98:113], v[190:193], v[150:153], v[98:113]
	v_add_f32_e32 v241, v230, v129
	ds_read_b128 v[190:193], v240 offset:0x3100
	v_add_f32_e32 v242, v200, v145
	global_load_lds_dwordx4 v[220:221], off
	s_waitcnt lgkmcnt(3)
	s_add_i32 m0, s3, 0x2000
	v_mfma_f32_32x32x16_bf16 v[82:97], v[182:185], v[146:149], v[82:97]
	ds_read_b128 v[200:203], v239 offset:0x100
	v_cvt_pk_bf16_f32 v182, v114, v115
	v_cvt_pk_bf16_f32 v184, v118, v119
	s_cmp_le_i32 s23, s9
	v_permlane32_swap_b32_e32 v182, v184
	s_waitcnt lgkmcnt(3)
	s_cselect_b64 s[28:29], -1, 0
	v_mfma_f32_32x32x16_bf16 v[98:113], v[194:197], v[146:149], v[98:113]
	ds_read_b128 v[194:197], v239 offset:0x3100
	v_cvt_pk_bf16_f32 v183, v116, v117
	v_cvt_pk_bf16_f32 v185, v120, v121
	s_cmp_gt_i32 s25, s11
	v_permlane32_swap_b32_e32 v183, v185
	s_waitcnt lgkmcnt(3)
	s_cselect_b64 s[30:31], -1, 0
	v_mfma_f32_32x32x16_bf16 v[82:97], v[186:189], v[10:13], v[82:97]
	ds_read_b128 v[230:233], v238 offset:0x100
	v_cvt_pk_bf16_f32 v186, v122, v123
	v_cvt_pk_bf16_f32 v188, v126, v127
	s_and_b64 s[28:29], s[28:29], s[30:31]
	v_permlane32_swap_b32_e32 v186, v188
	s_waitcnt lgkmcnt(3)
	s_and_b64 vcc, exec, s[28:29]
	v_mfma_f32_32x32x16_bf16 v[98:113], v[190:193], v[10:13], v[98:113]
	ds_read_b128 v[218:221], v238 offset:0x3100
	v_cvt_pk_bf16_f32 v187, v124, v125
	v_cvt_pk_bf16_f32 v189, v128, v129
	s_nop 0
	v_permlane32_swap_b32_e32 v187, v189
	s_waitcnt lgkmcnt(3)
	v_cvt_pk_bf16_f32 v190, v130, v131
	v_cvt_pk_bf16_f32 v192, v134, v135
	v_mfma_f32_32x32x16_bf16 v[82:97], v[200:203], v[6:9], v[82:97]
	v_permlane32_swap_b32_e32 v190, v192
	global_load_lds_dwordx4 v[244:245], off
	s_waitcnt lgkmcnt(2)
	v_cvt_pk_bf16_f32 v191, v132, v133
	v_cvt_pk_bf16_f32 v193, v136, v137
	s_nop 0
	v_mfma_f32_32x32x16_bf16 v[98:113], v[194:197], v[6:9], v[98:113]
	v_permlane32_swap_b32_e32 v191, v193
	s_waitcnt lgkmcnt(1)
	v_cvt_pk_bf16_f32 v194, v138, v139
	v_cvt_pk_bf16_f32 v196, v142, v143
	v_mfma_f32_32x32x16_bf16 v[82:97], v[230:233], v[2:5], v[82:97]
	v_permlane32_swap_b32_e32 v194, v196
	s_waitcnt lgkmcnt(0)
	v_cvt_pk_bf16_f32 v195, v140, v141
	v_cvt_pk_bf16_f32 v197, v144, v145
	v_mfma_f32_32x32x16_bf16 v[98:113], v[218:221], v[2:5], v[98:113]
	v_permlane32_swap_b32_e32 v195, v197
	v_add_f32_e32 v115, v241, v242
	v_mov_b32_e32 v116, v115
	s_nop 1
	v_permlane32_swap_b32_e32 v115, v116
	s_cbranch_vccnz .LBB0_2199
	v_add_u32_e32 v114, 59, v237
	v_cmp_gt_u32_e32 vcc, 2.0, v114
	v_add_u32_e32 v114, 27, v237
	s_nop 0
	v_cndmask_b32_e32 v82, v16, v82, vcc
	v_cmp_gt_u32_e32 vcc, 2.0, v114
	v_add_u32_e32 v114, 58, v237
	s_nop 0
	v_cndmask_b32_e32 v98, v16, v98, vcc
	v_cmp_gt_u32_e32 vcc, 2.0, v114
	v_add_u32_e32 v114, 26, v237
	s_nop 0
	v_cndmask_b32_e32 v83, v16, v83, vcc
	v_cmp_gt_u32_e32 vcc, 2.0, v114
	v_add_u32_e32 v114, 57, v237
	s_nop 0
	v_cndmask_b32_e32 v99, v16, v99, vcc
	v_cmp_gt_u32_e32 vcc, 2.0, v114
	v_add_u32_e32 v114, 25, v237
	s_nop 0
	v_cndmask_b32_e32 v84, v16, v84, vcc
	v_cmp_gt_u32_e32 vcc, 2.0, v114
	v_add_u32_e32 v114, 56, v237
	s_nop 0
	v_cndmask_b32_e32 v100, v16, v100, vcc
	v_cmp_gt_u32_e32 vcc, 2.0, v114
	v_add_u32_e32 v114, 24, v237
	s_nop 0
	v_cndmask_b32_e32 v85, v16, v85, vcc
	v_cmp_gt_u32_e32 vcc, 2.0, v114
	v_add_u32_e32 v114, 51, v237
	s_nop 0
	v_cndmask_b32_e32 v101, v16, v101, vcc
	v_cmp_gt_u32_e32 vcc, 2.0, v114
	v_add_u32_e32 v114, 19, v237
	s_nop 0
	v_cndmask_b32_e32 v86, v16, v86, vcc
	v_cmp_gt_u32_e32 vcc, 2.0, v114
	v_add_u32_e32 v114, 50, v237
	s_nop 0
	v_cndmask_b32_e32 v102, v16, v102, vcc
	v_cmp_gt_u32_e32 vcc, 2.0, v114
	v_add_u32_e32 v114, 18, v237
	s_nop 0
	v_cndmask_b32_e32 v87, v16, v87, vcc
	v_cmp_gt_u32_e32 vcc, 2.0, v114
	v_add_u32_e32 v114, 49, v237
	s_nop 0
	v_cndmask_b32_e32 v103, v16, v103, vcc
	v_cmp_gt_u32_e32 vcc, 2.0, v114
	v_add_u32_e32 v114, 17, v237
	s_nop 0
	v_cndmask_b32_e32 v88, v16, v88, vcc
	v_cmp_gt_u32_e32 vcc, 2.0, v114
	v_add_u32_e32 v114, 48, v237
	s_nop 0
	v_cndmask_b32_e32 v104, v16, v104, vcc
	v_cmp_gt_u32_e32 vcc, 2.0, v114
	v_add_u32_e32 v114, 16, v237
	s_nop 0
	v_cndmask_b32_e32 v89, v16, v89, vcc
	v_cmp_gt_u32_e32 vcc, 2.0, v114
	v_add_u32_e32 v114, 43, v237
	s_nop 0
	v_cndmask_b32_e32 v105, v16, v105, vcc
	v_cmp_gt_u32_e32 vcc, 2.0, v114
	v_add_u32_e32 v114, 11, v237
	s_nop 0
	v_cndmask_b32_e32 v90, v16, v90, vcc
	v_cmp_gt_u32_e32 vcc, 2.0, v114
	v_add_u32_e32 v114, 42, v237
	s_nop 0
	v_cndmask_b32_e32 v106, v16, v106, vcc
	v_cmp_gt_u32_e32 vcc, 2.0, v114
	v_add_u32_e32 v114, 10, v237
	s_nop 0
	v_cndmask_b32_e32 v91, v16, v91, vcc
	v_cmp_gt_u32_e32 vcc, 2.0, v114
	v_add_u32_e32 v114, 41, v237
	s_nop 0
	v_cndmask_b32_e32 v107, v16, v107, vcc
	v_cmp_gt_u32_e32 vcc, 2.0, v114
	v_add_u32_e32 v114, 9, v237
	s_nop 0
	v_cndmask_b32_e32 v92, v16, v92, vcc
	v_cmp_gt_u32_e32 vcc, 2.0, v114
	v_add_u32_e32 v114, 40, v237
	s_nop 0
	v_cndmask_b32_e32 v108, v16, v108, vcc
	v_cmp_gt_u32_e32 vcc, 2.0, v114
	v_add_u32_e32 v114, 8, v237
	s_nop 0
	v_cndmask_b32_e32 v93, v16, v93, vcc
	v_cmp_gt_u32_e32 vcc, 2.0, v114
	v_add_u32_e32 v114, 35, v237
	s_nop 0
	v_cndmask_b32_e32 v109, v16, v109, vcc
	v_cmp_gt_u32_e32 vcc, 2.0, v114
	v_add_u32_e32 v114, 3, v237
	s_nop 0
	v_cndmask_b32_e32 v94, v16, v94, vcc
	v_cmp_gt_u32_e32 vcc, 2.0, v114
	v_add_u32_e32 v114, 34, v237
	s_nop 0
	v_cndmask_b32_e32 v110, v16, v110, vcc
	v_cmp_gt_u32_e32 vcc, 2.0, v114
	v_add_u32_e32 v114, 2, v237
	s_nop 0
	v_cndmask_b32_e32 v95, v16, v95, vcc
	v_cmp_gt_u32_e32 vcc, 2.0, v114
	v_add_u32_e32 v114, 33, v237
	s_nop 0
	v_cndmask_b32_e32 v111, v16, v111, vcc
	v_cmp_gt_u32_e32 vcc, 2.0, v114
	v_add_u32_e32 v114, 1, v237
	s_nop 0
	v_cndmask_b32_e32 v96, v16, v96, vcc
	v_cmp_gt_u32_e32 vcc, 2.0, v114
	v_add_u32_e32 v114, 32, v237
	s_nop 0
	v_cndmask_b32_e32 v112, v16, v112, vcc
	v_cmp_gt_u32_e32 vcc, 2.0, v114
	s_nop 1
	v_cndmask_b32_e32 v97, v16, v97, vcc
	v_cmp_gt_u32_e32 vcc, 2.0, v237
	s_nop 1
	v_cndmask_b32_e32 v113, v16, v113, vcc
.LBB0_2199:
	v_add_u32_e32 v117, s2, v209
	ds_read_b64_tr_b16 v[118:119], v117 offset:0
	ds_read_b64_tr_b16 v[120:121], v117 offset:0x800
	ds_read_b64_tr_b16 v[122:123], v117 offset:0x1000
	ds_read_b64_tr_b16 v[124:125], v117 offset:0x1800
	ds_read_b64_tr_b16 v[126:127], v117 offset:0x2000
	ds_read_b64_tr_b16 v[128:129], v117 offset:0x2800
	ds_read_b64_tr_b16 v[130:131], v117 offset:0x3000
	v_max3_f32 v114, v82, s72, v83
	ds_read_b64_tr_b16 v[132:133], v117 offset:0x3800
	v_max3_f32 v114, v114, v84, v85
	s_waitcnt lgkmcnt(6)
	v_max3_f32 v114, v114, v86, v87
	v_mfma_f32_32x32x16_bf16 v[50:65], v[182:185], v[118:121], v[50:65]
	v_max3_f32 v114, v114, v88, v89
	ds_read_b64_tr_b16 v[118:119], v117 offset:0x200
	ds_read_b64_tr_b16 v[120:121], v117 offset:0xa00
	v_max_f32_e32 v134, v225, v225
	s_waitcnt lgkmcnt(6)
	v_max3_f32 v114, v114, v90, v91
	v_max3_f32 v114, v114, v92, v93
	v_max3_f32 v114, v114, v94, v95
	v_mfma_f32_32x32x16_bf16 v[50:65], v[186:189], v[122:125], v[50:65]
	v_max3_f32 v114, v114, v96, v97
	ds_read_b64_tr_b16 v[122:123], v117 offset:0x1200
	ds_read_b64_tr_b16 v[124:125], v117 offset:0x1a00
	s_waitcnt lgkmcnt(6)
	v_max3_f32 v114, v114, v98, v99
	v_max3_f32 v114, v114, v100, v101
	v_max3_f32 v114, v114, v102, v103
	v_mfma_f32_32x32x16_bf16 v[50:65], v[190:193], v[126:129], v[50:65]
	v_max3_f32 v114, v114, v104, v105
	ds_read_b64_tr_b16 v[126:127], v117 offset:0x2200
	ds_read_b64_tr_b16 v[128:129], v117 offset:0x2a00
	s_waitcnt lgkmcnt(6)
	v_max3_f32 v114, v114, v106, v107
	v_max3_f32 v114, v114, v108, v109
	v_max3_f32 v114, v114, v110, v111
	v_mfma_f32_32x32x16_bf16 v[50:65], v[194:197], v[130:133], v[50:65]
	v_max3_f32 v114, v114, v112, v113
	ds_read_b64_tr_b16 v[130:131], v117 offset:0x3200
	ds_read_b64_tr_b16 v[132:133], v117 offset:0x3a00
	s_waitcnt lgkmcnt(6)
	v_mov_b32_e32 v135, v114
	s_nop 1
	v_permlane32_swap_b32_e32 v114, v135
	v_max_f32_e32 v135, v135, v135
	v_max_f32_e32 v114, v114, v114
	v_max_f32_e32 v136, v114, v135
	v_sub_f32_e32 v114, v136, v225
	v_cmp_ge_f32_e32 vcc, s83, v114
	s_cmp_eq_u64 vcc, exec
	v_mfma_f32_32x32x16_bf16 v[66:81], v[182:185], v[118:121], v[66:81]
	v_max_f32_e32 v118, v134, v136
	s_cselect_b64 vcc, -1, 0
	v_cndmask_b32_e32 v238, v118, v225, vcc
	v_sub_f32_e32 v118, v225, v238
	v_mov_b32_e32 v114, v238
	v_exp_f32_e32 v218, v118
	ds_read_b64_tr_b16 v[118:119], v117 offset:0x400
	ds_read_b64_tr_b16 v[120:121], v117 offset:0xc00
	s_waitcnt lgkmcnt(6)
	v_cmp_gt_f32_e32 vcc, 1.0, v218
	v_sub_f32_e32 v82, v82, v114
	v_mfma_f32_32x32x16_bf16 v[66:81], v[186:189], v[122:125], v[66:81]
	v_sub_f32_e32 v98, v98, v114
	v_exp_f32_e32 v82, v82
	ds_read_b64_tr_b16 v[122:123], v117 offset:0x1400
	ds_read_b64_tr_b16 v[124:125], v117 offset:0x1c00
	s_waitcnt lgkmcnt(6)
	v_sub_f32_e32 v83, v83, v114
	v_mfma_f32_32x32x16_bf16 v[66:81], v[190:193], v[126:129], v[66:81]
	v_sub_f32_e32 v99, v99, v114
	v_exp_f32_e32 v83, v83
	ds_read_b64_tr_b16 v[126:127], v117 offset:0x2400
	ds_read_b64_tr_b16 v[128:129], v117 offset:0x2c00
	s_waitcnt lgkmcnt(6)
	v_sub_f32_e32 v84, v84, v114
	v_sub_f32_e32 v85, v85, v114
	v_mfma_f32_32x32x16_bf16 v[66:81], v[194:197], v[130:133], v[66:81]
	v_add_f32_e64 v100, v100, -v114
	v_add_f32_e64 v101, v101, -v114
	v_exp_f32_e32 v84, v84
	v_exp_f32_e32 v85, v85
	ds_read_b64_tr_b16 v[130:131], v117 offset:0x3400
	ds_read_b64_tr_b16 v[132:133], v117 offset:0x3c00
	s_waitcnt lgkmcnt(6)
	v_sub_f32_e32 v86, v86, v114
	v_mfma_f32_32x32x16_bf16 v[34:49], v[182:185], v[118:121], v[34:49]
	v_sub_f32_e32 v102, v102, v114
	v_exp_f32_e32 v86, v86
	ds_read_b64_tr_b16 v[118:119], v117 offset:0x600
	ds_read_b64_tr_b16 v[120:121], v117 offset:0xe00
	s_waitcnt lgkmcnt(6)
	v_mov_b32_e32 v134, v103
	v_mov_b32_e32 v135, v104
	v_sub_f32_e32 v87, v87, v114
	v_sub_f32_e32 v88, v88, v114
	v_pk_add_f32 v[134:135], v[134:135], v[114:115] op_sel_hi:[1,0] neg_lo:[0,1] neg_hi:[0,1]
	v_mfma_f32_32x32x16_bf16 v[34:49], v[186:189], v[122:125], v[34:49]
	v_exp_f32_e32 v87, v87
	v_exp_f32_e32 v88, v88
	v_mov_b32_e32 v103, v134
	v_mov_b32_e32 v104, v135
	ds_read_b64_tr_b16 v[122:123], v117 offset:0x1600
	ds_read_b64_tr_b16 v[124:125], v117 offset:0x1e00
	s_waitcnt lgkmcnt(6)
	v_sub_f32_e32 v89, v89, v114
	v_mfma_f32_32x32x16_bf16 v[34:49], v[190:193], v[126:129], v[34:49]
	v_sub_f32_e32 v105, v105, v114
	v_exp_f32_e32 v89, v89
	ds_read_b64_tr_b16 v[126:127], v117 offset:0x2600
	ds_read_b64_tr_b16 v[128:129], v117 offset:0x2e00
	s_waitcnt lgkmcnt(6)
	v_sub_f32_e32 v90, v90, v114
	v_sub_f32_e32 v91, v91, v114
	v_mfma_f32_32x32x16_bf16 v[34:49], v[194:197], v[130:133], v[34:49]
	v_add_f32_e64 v106, v106, -v114
	v_add_f32_e64 v107, v107, -v114
	v_exp_f32_e32 v90, v90
	v_exp_f32_e32 v91, v91
	ds_read_b64_tr_b16 v[130:131], v117 offset:0x3600
	ds_read_b64_tr_b16 v[132:133], v117 offset:0x3e00
	s_waitcnt lgkmcnt(6)
	v_sub_f32_e32 v92, v92, v114
	v_sub_f32_e32 v108, v108, v114
	v_exp_f32_e32 v92, v92
	v_mfma_f32_32x32x16_bf16 v[18:33], v[182:185], v[118:121], v[18:33]
	s_waitcnt lgkmcnt(4)
	v_mov_b32_e32 v118, v109
	v_mov_b32_e32 v119, v110
	v_sub_f32_e32 v93, v93, v114
	v_sub_f32_e32 v94, v94, v114
	v_pk_add_f32 v[118:119], v[118:119], v[114:115] op_sel_hi:[1,0] neg_lo:[0,1] neg_hi:[0,1]
	v_exp_f32_e32 v93, v93
	v_exp_f32_e32 v94, v94
	v_mfma_f32_32x32x16_bf16 v[18:33], v[186:189], v[122:125], v[18:33]
	v_mov_b32_e32 v109, v118
	v_mov_b32_e32 v110, v119
	s_waitcnt lgkmcnt(2)
	v_sub_f32_e32 v95, v95, v114
	v_exp_f32_e32 v95, v95
	v_mfma_f32_32x32x16_bf16 v[18:33], v[190:193], v[126:129], v[18:33]
	v_sub_f32_e32 v111, v111, v114
	s_waitcnt lgkmcnt(0)
	v_sub_f32_e32 v96, v96, v114
	v_sub_f32_e32 v97, v97, v114
	v_exp_f32_e32 v96, v96
	v_exp_f32_e32 v97, v97
	v_mfma_f32_32x32x16_bf16 v[18:33], v[194:197], v[130:133], v[18:33]
	v_add_f32_e64 v112, v112, -v114
	v_add_f32_e64 v113, v113, -v114
	s_cbranch_vccz .LBB0_2203
	s_and_saveexec_b64 s[2:3], s[0:1]
	ds_write_b32 v228, v218 offset:128
	s_or_b64 exec, exec, s[2:3]
	s_waitcnt lgkmcnt(0)
	ds_read_b128 v[118:121], v227 offset:224
	ds_read_b128 v[122:125], v227 offset:192
	ds_read_b128 v[126:129], v227 offset:160
	ds_read_b128 v[130:133], v227 offset:128
	s_waitcnt lgkmcnt(0)
	v_pk_mul_f32 v[64:65], v[64:65], v[120:121]
	v_pk_mul_f32 v[60:61], v[60:61], v[124:125]
	v_pk_mul_f32 v[56:57], v[56:57], v[128:129]
	v_pk_mul_f32 v[52:53], v[52:53], v[132:133]
	v_pk_mul_f32 v[62:63], v[62:63], v[118:119]
	v_pk_mul_f32 v[58:59], v[58:59], v[122:123]
	v_pk_mul_f32 v[54:55], v[54:55], v[126:127]
	v_pk_mul_f32 v[50:51], v[50:51], v[130:131]
	v_pk_mul_f32 v[80:81], v[80:81], v[120:121]
	v_pk_mul_f32 v[76:77], v[76:77], v[124:125]
	v_pk_mul_f32 v[72:73], v[72:73], v[128:129]
	v_pk_mul_f32 v[68:69], v[68:69], v[132:133]
	v_pk_mul_f32 v[78:79], v[78:79], v[118:119]
	v_pk_mul_f32 v[74:75], v[74:75], v[122:123]
	v_pk_mul_f32 v[70:71], v[70:71], v[126:127]
	v_pk_mul_f32 v[66:67], v[66:67], v[130:131]
	v_pk_mul_f32 v[48:49], v[48:49], v[120:121]
	v_pk_mul_f32 v[44:45], v[44:45], v[124:125]
	v_pk_mul_f32 v[40:41], v[40:41], v[128:129]
	v_pk_mul_f32 v[36:37], v[36:37], v[132:133]
	v_pk_mul_f32 v[46:47], v[46:47], v[118:119]
	v_pk_mul_f32 v[42:43], v[42:43], v[122:123]
	v_pk_mul_f32 v[38:39], v[38:39], v[126:127]
	v_pk_mul_f32 v[34:35], v[34:35], v[130:131]
	v_pk_mul_f32 v[32:33], v[32:33], v[120:121]
	v_pk_mul_f32 v[28:29], v[28:29], v[124:125]
	v_pk_mul_f32 v[24:25], v[24:25], v[128:129]
	v_pk_mul_f32 v[20:21], v[20:21], v[132:133]
	v_pk_mul_f32 v[30:31], v[30:31], v[118:119]
	v_pk_mul_f32 v[26:27], v[26:27], v[122:123]
	v_pk_mul_f32 v[22:23], v[22:23], v[126:127]
	v_pk_mul_f32 v[18:19], v[18:19], v[130:131]

.LBB0_2475:
	s_mov_b32 s0, 0
	v_readlane_b32 s2, v253, 0
	v_mbcnt_lo_u32_b32 v0, -1, s0
	v_mbcnt_hi_u32_b32 v0, -1, v0
	v_readlane_b32 s0, v253, 43
	s_lshl_b32 s1, s2, 12
	s_and_b32 s8, s1, 0x7000
	v_add_u32_e32 v1, s0, v0
	s_and_b32 s1, s2, -8
	v_readfirstlane_b32 s0, v1
	s_ashr_i32 s0, s0, 6
	s_add_i32 s1, s8, s1
	s_add_i32 s0, s1, s0
	s_addk_i32 s8, 0x1000
	v_readlane_b32 s12, v253, 53
	s_cmp_ge_i32 s0, s8
	v_readlane_b32 s13, v253, 54
	v_readlane_b32 s14, v253, 55
	v_readlane_b32 s15, v253, 56
	s_cbranch_scc1 .LBB0_2478
	v_and_b32_e32 v2, 63, v0
	v_readlane_b32 s16, v253, 33
	v_lshlrev_b32_e32 v12, 4, v2
	v_mov_b32_e32 v13, 0
	v_readlane_b32 s22, v253, 39
	v_readlane_b32 s23, v253, 40
	v_and_b32_e32 v19, 31, v0
	s_mov_b64 s[6:7], 0x1400
	v_lshl_add_u64 v[0:1], s[22:23], 0, v[12:13]
	v_readlane_b32 s1, v254, 3
	v_lshl_add_u64 v[4:5], v[0:1], 0, s[6:7]
	s_mov_b64 s[6:7], 0x1800
	s_and_b32 s2, s1, -8
	v_lshl_add_u64 v[6:7], v[0:1], 0, s[6:7]
	s_mov_b64 s[6:7], 0x1c00
	s_ashr_i32 s1, s0, 31
	v_lshl_add_u64 v[8:9], v[0:1], 0, s[6:7]
	s_lshl_b64 s[6:7], s[0:1], 13
	s_add_u32 s6, s12, s6
	s_addc_u32 s7, s13, s7
	v_lshlrev_b32_e32 v2, 2, v2
	s_mov_b64 s[4:5], 0x1000
	v_lshl_add_u64 v[10:11], s[6:7], 0, v[12:13]
	s_ashr_i32 s3, s2, 31
	v_xor_b32_e32 v14, 4, v2
	v_xor_b32_e32 v15, 8, v2
	v_xor_b32_e32 v16, 16, v2
	v_xor_b32_e32 v17, 32, v2
	v_xor_b32_e32 v18, 64, v2
	v_lshl_add_u64 v[2:3], v[0:1], 0, s[4:5]
	v_lshl_add_u64 v[10:11], v[10:11], 0, s[4:5]
	s_lshl_b64 s[4:5], s[2:3], 13
	s_lshl_b64 s[6:7], s[0:1], 7
	s_add_u32 s6, s14, s6
	v_lshlrev_b32_e32 v12, 2, v19
	s_addc_u32 s7, s15, s7
	v_lshl_add_u64 v[12:13], s[6:7], 0, v[12:13]
	s_mov_b64 s[6:7], 0x30c00000
	v_lshl_add_u64 v[12:13], v[12:13], 0, s[6:7]
	s_lshl_b64 s[6:7], s[2:3], 7
	v_mov_b32_e32 v19, 0x358637bd
	s_mov_b32 s1, 0x800000
	v_readlane_b32 s17, v253, 34
	v_readlane_b32 s18, v253, 35
	v_readlane_b32 s19, v253, 36
	v_readlane_b32 s20, v253, 37
	v_readlane_b32 s21, v253, 38
	global_load_dwordx4 v[40:43], v[0:1], off
	global_load_dwordx4 v[44:47], v[0:1], off offset:1024
	global_load_dwordx4 v[48:51], v[0:1], off offset:2048
	global_load_dwordx4 v[52:55], v[0:1], off offset:3072
	global_load_dwordx4 v[56:59], v[2:3], off
	global_load_dwordx4 v[60:63], v[4:5], off
	global_load_dwordx4 v[64:67], v[6:7], off
	global_load_dwordx4 v[68:71], v[8:9], off
.LBB0_2477:
	flat_load_dword v32, v[12:13]
	global_load_dwordx4 v[72:75], v[10:11], off offset:-4096
	global_load_dwordx4 v[76:79], v[10:11], off offset:-3072
	global_load_dwordx4 v[80:83], v[10:11], off offset:-2048
	global_load_dwordx4 v[84:87], v[10:11], off offset:-1024
	global_load_dwordx4 v[88:91], v[10:11], off
	global_load_dwordx4 v[92:95], v[10:11], off offset:1024
	global_load_dwordx4 v[96:99], v[10:11], off offset:2048
	global_load_dwordx4 v[100:103], v[10:11], off offset:3072
	s_add_i32 s0, s0, s2
	v_lshl_add_u64 v[12:13], v[12:13], 0, s[6:7]
	s_waitcnt vmcnt(8) lgkmcnt(0)
	ds_bpermute_b32 v33, v14, v32
	s_waitcnt lgkmcnt(0)
	v_add_f32_e32 v32, v32, v33
	ds_bpermute_b32 v33, v15, v32
	s_waitcnt lgkmcnt(0)
	v_add_f32_e32 v32, v32, v33
	ds_bpermute_b32 v33, v16, v32
	s_waitcnt lgkmcnt(0)
	v_add_f32_e32 v32, v32, v33
	ds_bpermute_b32 v33, v17, v32
	s_waitcnt lgkmcnt(0)
	v_add_f32_e32 v32, v32, v33
	ds_bpermute_b32 v33, v18, v32
	s_waitcnt lgkmcnt(0)
	v_add_f32_e32 v32, v32, v33
	v_fmamk_f32 v32, v32, 0x3a000000, v19
	v_mul_f32_e32 v33, 0x4b800000, v32
	v_cmp_gt_f32_e32 vcc, s1, v32
	s_nop 1
	v_cndmask_b32_e32 v32, v32, v33, vcc
	v_rsq_f32_e32 v32, v32
	s_nop 0
	v_mul_f32_e32 v33, 0x45800000, v32
	v_cndmask_b32_e32 v32, v32, v33, vcc
	s_waitcnt vmcnt(7)
	v_pk_mul_f32 v[72:73], v[32:33], v[72:73] op_sel_hi:[0,1]
	v_pk_mul_f32 v[74:75], v[32:33], v[74:75] op_sel_hi:[0,1]
	v_pk_mul_f32 v[72:73], v[72:73], v[40:41]
	v_pk_mul_f32 v[74:75], v[74:75], v[42:43]
	s_waitcnt vmcnt(6)
	v_pk_mul_f32 v[76:77], v[32:33], v[76:77] op_sel_hi:[0,1]
	v_pk_mul_f32 v[78:79], v[32:33], v[78:79] op_sel_hi:[0,1]
	v_pk_mul_f32 v[76:77], v[76:77], v[44:45]
	v_pk_mul_f32 v[78:79], v[78:79], v[46:47]
	s_waitcnt vmcnt(5)
	v_pk_mul_f32 v[80:81], v[32:33], v[80:81] op_sel_hi:[0,1]
	v_pk_mul_f32 v[82:83], v[32:33], v[82:83] op_sel_hi:[0,1]
	v_pk_mul_f32 v[80:81], v[80:81], v[48:49]
	v_pk_mul_f32 v[82:83], v[82:83], v[50:51]
	s_waitcnt vmcnt(4)
	v_pk_mul_f32 v[84:85], v[32:33], v[84:85] op_sel_hi:[0,1]
	v_pk_mul_f32 v[86:87], v[32:33], v[86:87] op_sel_hi:[0,1]
	v_pk_mul_f32 v[84:85], v[84:85], v[52:53]
	v_pk_mul_f32 v[86:87], v[86:87], v[54:55]
	s_waitcnt vmcnt(3)
	v_pk_mul_f32 v[88:89], v[32:33], v[88:89] op_sel_hi:[0,1]
	v_pk_mul_f32 v[90:91], v[32:33], v[90:91] op_sel_hi:[0,1]
	v_pk_mul_f32 v[88:89], v[88:89], v[56:57]
	v_pk_mul_f32 v[90:91], v[90:91], v[58:59]
	s_waitcnt vmcnt(2)
	v_pk_mul_f32 v[92:93], v[32:33], v[92:93] op_sel_hi:[0,1]
	v_pk_mul_f32 v[94:95], v[32:33], v[94:95] op_sel_hi:[0,1]
	v_pk_mul_f32 v[92:93], v[92:93], v[60:61]
	v_pk_mul_f32 v[94:95], v[94:95], v[62:63]
	s_waitcnt vmcnt(1)
	v_pk_mul_f32 v[96:97], v[32:33], v[96:97] op_sel_hi:[0,1]
	v_pk_mul_f32 v[98:99], v[32:33], v[98:99] op_sel_hi:[0,1]
	v_pk_mul_f32 v[96:97], v[96:97], v[64:65]
	v_pk_mul_f32 v[98:99], v[98:99], v[66:67]
	s_waitcnt vmcnt(0)
	v_pk_mul_f32 v[100:101], v[32:33], v[100:101] op_sel_hi:[0,1]
	v_pk_mul_f32 v[102:103], v[32:33], v[102:103] op_sel_hi:[0,1]
	v_pk_mul_f32 v[100:101], v[100:101], v[68:69]
	v_pk_mul_f32 v[102:103], v[102:103], v[70:71]
	global_store_dwordx4 v[10:11], v[72:75], off offset:-4096
	global_store_dwordx4 v[10:11], v[76:79], off offset:-3072
	global_store_dwordx4 v[10:11], v[80:83], off offset:-2048
	global_store_dwordx4 v[10:11], v[84:87], off offset:-1024
	global_store_dwordx4 v[10:11], v[88:91], off
	global_store_dwordx4 v[10:11], v[92:95], off offset:1024
	global_store_dwordx4 v[10:11], v[96:99], off offset:2048
	global_store_dwordx4 v[10:11], v[100:103], off offset:3072
	s_cmp_ge_i32 s0, s8
	v_lshl_add_u64 v[10:11], v[10:11], 0, s[4:5]
	s_cbranch_scc0 .LBB0_2477
